# S3 load segment trimmed the same way: 4 scalar ops moved into the preceding MFMA stream, 2 LDS-DMA in sgpr-base form
# baseline (speedup 1.0000x reference)
; #define PG8_STAGE(bufoff, gbase, VO) do { _Pragma("unroll") for (int _i = 0; _i < 2; ++_i) \
;         __builtin_amdgcn_global_load_lds((const unsigned*)((const char*)(gbase) + VO[_i]), (LAS unsigned*)(lds + (bufoff) + ldsw + _i * 8192), 16, 0, 0); } while (0)
; #define PG8_LDA(dst, b, h) do { _Pragma("unroll") for (int m = 0; m < 4; ++m) _Pragma("unroll") for (int k = 0; k < 2; ++k) dst[m][k] = *(const LAS bf16x8*)(lds + PG8_SA(b, h) + aoff + m * 2048 + k * 1024); } while (0)
; #define PG8_LDB(dst, b, h) do { _Pragma("unroll") for (int n = 0; n < 2; ++n) _Pragma("unroll") for (int k = 0; k < 2; ++k) dst[n][k] = *(const LAS bf16x8*)(lds + PG8_SB(b, h) + boff + n * 2048 + k * 1024); } while (0)
; #define PG8_MMA(ai, bj, At, Bt) do { __builtin_amdgcn_s_setprio(1); _Pragma("unroll") for (int m = 0; m < 4; ++m) _Pragma("unroll") for (int n = 0; n < 2; ++n) _Pragma("unroll") for (int k = 0; k < 2; ++k) \
;         acc[ai][bj][m][n] = __builtin_amdgcn_mfma_f32_16x16x32_bf16(Bt[n][k], At[m][k], acc[ai][bj][m][n], 0, 0, 0); __builtin_amdgcn_s_setprio(0); } while (0)
; #define PG8_BAR __builtin_amdgcn_s_barrier()
; template <int NSEG, class Epi, bool ALIGN_EPI = PG8_ALIGN, bool SP2 = PG8_SP2>
; DI void gemm_phase(LAS unsigned char* lds, const Gemm g, const StaticOrder& S, const Epi& E) {
;     ...
;         for (int t = 0; t < nt; t += 2) {
;             const bool last = (t == nt - 2);
;             const char* a1 = cA + (size_t)(t + 1) * kstep;
;             const char* a2 = last ? nA : cA + (size_t)(t + 2) * kstep; const char* b2 = last ? nB : cB + (size_t)(t + 2) * kstep;
;             const char* a3 = a2 + kstep; const char* b3 = b2 + kstep;
;             unsigned v2[2]; v2[0] = (NSEG > 1 && last) ? voffN[0] : voffC[0]; v2[1] = (NSEG > 1 && last) ? voffN[1] : voffC[1];
;             const size_t h2 = (NSEG > 1 && last) ? hstepN : hstepC;
;             if constexpr (SP2) {
;             PG8_LDB(B0, 0, 0); PG8_LDB(B1, 0, 1); PG8_SCHED; PG8_LDA(At, 0, 0); PG8_STAGE(PG8_SA(1, 1), a1 + hstepC, voffC);
;             PG8_WAIT_V(8); PG8_WAIT_L(0); PG8_BAR; PG8_MMA(0, 0, At, B0); PG8_MMA(0, 1, At, B1); PG8_BAR; PG8_SCHED;
;             PG8_LDA(At, 0, 1); PG8_STAGE(PG8_SB(0, 0), b2, v2); PG8_STAGE(PG8_SB(0, 1), b2 + h2, v2); PG8_STAGE(PG8_SA(0, 0), a2, v2);
;             PG8_WAIT_V(8); PG8_WAIT_L(0); PG8_BAR; PG8_MMA(1, 0, At, B0); PG8_MMA(1, 1, At, B1); PG8_BAR; PG8_SCHED;
.LBB0_139:
	v_add_u32_e32 v134, s62, v157
	ds_read_b128 v[144:147], v178
	ds_read_b128 v[148:151], v178 offset:1024
	ds_read_b128 v[152:155], v178 offset:2048
	ds_read_b128 v[182:185], v178 offset:3072
	ds_read_b128 v[186:189], v134
	ds_read_b128 v[190:193], v134 offset:1024
	ds_read_b128 v[194:197], v134 offset:2048
	ds_read_b128 v[198:201], v134 offset:3072
	s_add_i32 m0, s45, 0xc000
	ds_read_b128 v[202:205], v179
	ds_read_b128 v[206:209], v179 offset:1024
	ds_read_b128 v[210:213], v179 offset:2048
	ds_read_b128 v[214:217], v179 offset:3072
	ds_read_b128 v[218:221], v179 offset:4096
	ds_read_b128 v[222:225], v179 offset:5120
	ds_read_b128 v[226:229], v179 offset:6144
	ds_read_b128 v[230:233], v179 offset:7168
	global_load_lds_dwordx4 v136, s[34:35]
	s_add_i32 m0, s45, 0xe000
	s_nop 0
	global_load_lds_dwordx4 v138, s[34:35]
	s_waitcnt vmcnt(8)
	s_waitcnt lgkmcnt(0)
	s_setprio 1
	s_barrier
	v_mfma_f32_16x16x32_bf16 v[126:129], v[144:147], v[202:205], v[126:129]
	v_mfma_f32_16x16x32_bf16 v[122:125], v[152:155], v[202:205], v[122:125]
	s_add_u32 s36, s34, 0xfff80080
	s_addc_u32 s37, s35, -1
	v_mfma_f32_16x16x32_bf16 v[110:113], v[144:147], v[210:213], v[110:113]
	v_mfma_f32_16x16x32_bf16 v[106:109], v[152:155], v[210:213], v[106:109]
	s_cmp_eq_u32 s72, 28
	s_cselect_b32 s41, s3, s37
	v_mfma_f32_16x16x32_bf16 v[94:97], v[144:147], v[218:221], v[94:97]
	v_mfma_f32_16x16x32_bf16 v[90:93], v[152:155], v[218:221], v[90:93]
	s_cselect_b32 s40, s25, s36
	s_cselect_b32 s37, s27, s71
	v_mfma_f32_16x16x32_bf16 v[78:81], v[144:147], v[226:229], v[78:81]
	v_mfma_f32_16x16x32_bf16 v[74:77], v[152:155], v[226:229], v[74:77]
	s_cselect_b32 s36, s69, s70
	v_mfma_f32_16x16x32_bf16 v[126:129], v[148:151], v[206:209], v[126:129]
	v_mfma_f32_16x16x32_bf16 v[122:125], v[182:185], v[206:209], v[122:125]
	v_mfma_f32_16x16x32_bf16 v[110:113], v[148:151], v[214:217], v[110:113]
	v_mfma_f32_16x16x32_bf16 v[106:109], v[182:185], v[214:217], v[106:109]
	v_mfma_f32_16x16x32_bf16 v[94:97], v[148:151], v[222:225], v[94:97]
	v_mfma_f32_16x16x32_bf16 v[90:93], v[182:185], v[222:225], v[90:93]
	v_mfma_f32_16x16x32_bf16 v[78:81], v[148:151], v[230:233], v[78:81]
	v_mfma_f32_16x16x32_bf16 v[74:77], v[182:185], v[230:233], v[74:77]
	s_setprio 0
	s_setprio 1
	v_mfma_f32_16x16x32_bf16 v[118:121], v[186:189], v[202:205], v[118:121]
	v_mfma_f32_16x16x32_bf16 v[114:117], v[194:197], v[202:205], v[114:117]
	v_mfma_f32_16x16x32_bf16 v[102:105], v[186:189], v[210:213], v[102:105]
	v_mfma_f32_16x16x32_bf16 v[98:101], v[194:197], v[210:213], v[98:101]
	v_mfma_f32_16x16x32_bf16 v[86:89], v[186:189], v[218:221], v[86:89]
	v_mfma_f32_16x16x32_bf16 v[82:85], v[194:197], v[218:221], v[82:85]
	v_mfma_f32_16x16x32_bf16 v[70:73], v[186:189], v[226:229], v[70:73]
	v_mfma_f32_16x16x32_bf16 v[66:69], v[194:197], v[226:229], v[66:69]
	v_mfma_f32_16x16x32_bf16 v[118:121], v[190:193], v[206:209], v[118:121]
	v_mfma_f32_16x16x32_bf16 v[114:117], v[198:201], v[206:209], v[114:117]
	v_mfma_f32_16x16x32_bf16 v[102:105], v[190:193], v[214:217], v[102:105]
	v_mfma_f32_16x16x32_bf16 v[98:101], v[198:201], v[214:217], v[98:101]
	v_mfma_f32_16x16x32_bf16 v[86:89], v[190:193], v[222:225], v[86:89]
	v_mfma_f32_16x16x32_bf16 v[82:85], v[198:201], v[222:225], v[82:85]
	v_mfma_f32_16x16x32_bf16 v[70:73], v[190:193], v[230:233], v[70:73]
	v_mfma_f32_16x16x32_bf16 v[66:69], v[198:201], v[230:233], v[66:69]
	s_setprio 0
	s_barrier
	s_add_i32 s73, s61, s51
	v_lshl_add_u64 v[234:235], s[36:37], 0, v[130:131]
	s_mov_b32 m0, s73
	ds_read_b128 v[202:205], v179 offset:16384
	ds_read_b128 v[206:209], v179 offset:17408
	ds_read_b128 v[210:213], v179 offset:18432
	ds_read_b128 v[214:217], v179 offset:19456
	ds_read_b128 v[218:221], v179 offset:20480
	ds_read_b128 v[222:225], v179 offset:21504
	ds_read_b128 v[226:229], v179 offset:22528
	ds_read_b128 v[230:233], v179 offset:23552
	global_load_lds_dwordx4 v[234:235], off
	s_add_i32 m0, s73, 0x2000
	s_add_u32 s74, s36, 0x80000
	v_lshl_add_u64 v[236:237], s[36:37], 0, v[132:133]
	s_addc_u32 s75, s37, 0
	s_add_i32 s73, s62, s51
	global_load_lds_dwordx4 v[236:237], off
	v_lshl_add_u64 v[238:239], s[74:75], 0, v[130:131]
	s_mov_b32 m0, s73
	v_lshl_add_u64 v[240:241], s[40:41], 0, v[132:133]
	global_load_lds_dwordx4 v[238:239], off
	v_lshl_add_u64 v[238:239], s[74:75], 0, v[132:133]
	s_add_i32 m0, s73, 0x2000
	s_nop 0
	global_load_lds_dwordx4 v[238:239], off
	v_lshl_add_u64 v[238:239], s[40:41], 0, v[130:131]
	s_mov_b32 m0, s45
	s_nop 0
	global_load_lds_dwordx4 v[238:239], off
	s_mov_b32 m0, s54
	s_nop 0
	global_load_lds_dwordx4 v[240:241], off
	s_waitcnt vmcnt(8)
	s_waitcnt lgkmcnt(0)
	s_setprio 1
	s_barrier
; #define PG8_STAGE(bufoff, gbase, VO) do { _Pragma("unroll") for (int _i = 0; _i < 2; ++_i) \
;         __builtin_amdgcn_global_load_lds((const unsigned*)((const char*)(gbase) + VO[_i]), (LAS unsigned*)(lds + (bufoff) + ldsw + _i * 8192), 16, 0, 0); } while (0)
; #define PG8_LDA(dst, b, h) do { _Pragma("unroll") for (int m = 0; m < 4; ++m) _Pragma("unroll") for (int k = 0; k < 2; ++k) dst[m][k] = *(const LAS bf16x8*)(lds + PG8_SA(b, h) + aoff + m * 2048 + k * 1024); } while (0)
; #define PG8_LDB(dst, b, h) do { _Pragma("unroll") for (int n = 0; n < 2; ++n) _Pragma("unroll") for (int k = 0; k < 2; ++k) dst[n][k] = *(const LAS bf16x8*)(lds + PG8_SB(b, h) + boff + n * 2048 + k * 1024); } while (0)
; #define PG8_MMA(ai, bj, At, Bt) do { __builtin_amdgcn_s_setprio(1); _Pragma("unroll") for (int m = 0; m < 4; ++m) _Pragma("unroll") for (int n = 0; n < 2; ++n) _Pragma("unroll") for (int k = 0; k < 2; ++k) \
;         acc[ai][bj][m][n] = __builtin_amdgcn_mfma_f32_16x16x32_bf16(Bt[n][k], At[m][k], acc[ai][bj][m][n], 0, 0, 0); __builtin_amdgcn_s_setprio(0); } while (0)
; #define PG8_WAIT_V(n) asm volatile("s_waitcnt vmcnt(" #n ")" ::: "memory")
; #define PG8_WAIT_L(n) asm volatile("s_waitcnt lgkmcnt(" #n ")" ::: "memory")
; #define PG8_BAR __builtin_amdgcn_s_barrier()
; #define PG8_SCHED __builtin_amdgcn_sched_barrier(0)
; template <int NSEG, class Epi, bool ALIGN_EPI = PG8_ALIGN, bool SP2 = PG8_SP2>
; DI void gemm_phase(LAS unsigned char* lds, const Gemm g, const StaticOrder& S, const Epi& E) {
;     ...
;             PG8_WAIT_V(8); PG8_WAIT_L(0); PG8_BAR; PG8_MMA(1, 0, At, B0); PG8_MMA(1, 1, At, B1); PG8_BAR; PG8_SCHED;
;             PG8_LDB(B0, 1, 0); PG8_LDB(B1, 1, 1); PG8_SCHED; PG8_LDA(At, 1, 0); PG8_STAGE(PG8_SA(0, 1), a2 + h2, v2);
;             PG8_WAIT_V(8); PG8_WAIT_L(0); PG8_BAR; PG8_MMA(0, 0, At, B0); PG8_MMA(0, 1, At, B1); PG8_BAR; PG8_SCHED;
	v_mfma_f32_16x16x32_bf16 v[62:65], v[144:147], v[202:205], v[62:65]
	v_mfma_f32_16x16x32_bf16 v[58:61], v[152:155], v[202:205], v[58:61]
	s_add_i32 s73, 0, 0x18000
	s_add_i32 s74, 0, 0x1c000
	v_mfma_f32_16x16x32_bf16 v[46:49], v[144:147], v[210:213], v[46:49]
	v_mfma_f32_16x16x32_bf16 v[42:45], v[152:155], v[210:213], v[42:45]
	s_add_u32 s40, s40, 0x80000
	s_addc_u32 s41, s41, 0
	v_mfma_f32_16x16x32_bf16 v[22:25], v[144:147], v[218:221], v[22:25]
	v_mfma_f32_16x16x32_bf16 v[18:21], v[152:155], v[218:221], v[18:21]
	v_mfma_f32_16x16x32_bf16 v[6:9], v[144:147], v[226:229], v[6:9]
	v_mfma_f32_16x16x32_bf16 v[2:5], v[152:155], v[226:229], v[2:5]
	v_mfma_f32_16x16x32_bf16 v[62:65], v[148:151], v[206:209], v[62:65]
	v_mfma_f32_16x16x32_bf16 v[58:61], v[182:185], v[206:209], v[58:61]
	v_mfma_f32_16x16x32_bf16 v[46:49], v[148:151], v[214:217], v[46:49]
	v_mfma_f32_16x16x32_bf16 v[42:45], v[182:185], v[214:217], v[42:45]
	v_mfma_f32_16x16x32_bf16 v[22:25], v[148:151], v[222:225], v[22:25]
	v_mfma_f32_16x16x32_bf16 v[18:21], v[182:185], v[222:225], v[18:21]
	v_mfma_f32_16x16x32_bf16 v[6:9], v[148:151], v[230:233], v[6:9]
	v_mfma_f32_16x16x32_bf16 v[2:5], v[182:185], v[230:233], v[2:5]
	s_setprio 0
	s_setprio 1
	v_mfma_f32_16x16x32_bf16 v[54:57], v[186:189], v[202:205], v[54:57]
	v_mfma_f32_16x16x32_bf16 v[50:53], v[194:197], v[202:205], v[50:53]
	v_mfma_f32_16x16x32_bf16 v[38:41], v[186:189], v[210:213], v[38:41]
	v_mfma_f32_16x16x32_bf16 v[26:29], v[194:197], v[210:213], v[26:29]
	v_mfma_f32_16x16x32_bf16 v[34:37], v[186:189], v[218:221], v[34:37]
	v_mfma_f32_16x16x32_bf16 v[30:33], v[194:197], v[218:221], v[30:33]
	v_mfma_f32_16x16x32_bf16 v[14:17], v[186:189], v[226:229], v[14:17]
	v_mfma_f32_16x16x32_bf16 v[10:13], v[194:197], v[226:229], v[10:13]
	v_mfma_f32_16x16x32_bf16 v[54:57], v[190:193], v[206:209], v[54:57]
	v_mfma_f32_16x16x32_bf16 v[50:53], v[198:201], v[206:209], v[50:53]
	v_mfma_f32_16x16x32_bf16 v[38:41], v[190:193], v[214:217], v[38:41]
	v_mfma_f32_16x16x32_bf16 v[26:29], v[198:201], v[214:217], v[26:29]
	v_mfma_f32_16x16x32_bf16 v[34:37], v[190:193], v[222:225], v[34:37]
	v_mfma_f32_16x16x32_bf16 v[30:33], v[198:201], v[222:225], v[30:33]
	v_mfma_f32_16x16x32_bf16 v[14:17], v[190:193], v[230:233], v[14:17]
	v_mfma_f32_16x16x32_bf16 v[10:13], v[198:201], v[230:233], v[10:13]
	s_setprio 0
	s_barrier
	v_add_u32_e32 v134, s73, v157
	ds_read_b128 v[144:147], v134
	ds_read_b128 v[148:151], v134 offset:1024
	ds_read_b128 v[152:155], v134 offset:2048
	ds_read_b128 v[182:185], v134 offset:3072
	v_add_u32_e32 v134, s74, v157
	ds_read_b128 v[186:189], v134
	ds_read_b128 v[190:193], v134 offset:1024
	ds_read_b128 v[194:197], v134 offset:2048
	ds_read_b128 v[198:201], v134 offset:3072
	s_mov_b32 m0, s55
	ds_read_b128 v[202:205], v179 offset:32768
	ds_read_b128 v[206:209], v179 offset:33792
	ds_read_b128 v[210:213], v179 offset:34816
	ds_read_b128 v[214:217], v179 offset:35840
	ds_read_b128 v[218:221], v179 offset:36864
	ds_read_b128 v[222:225], v179 offset:37888
	ds_read_b128 v[226:229], v179 offset:38912
	ds_read_b128 v[230:233], v179 offset:39936
	global_load_lds_dwordx4 v130, s[40:41]
	s_mov_b32 m0, s56
	s_nop 0
	global_load_lds_dwordx4 v132, s[40:41]
	s_waitcnt vmcnt(8)
	s_waitcnt lgkmcnt(0)
	s_setprio 1
	s_barrier
	v_mfma_f32_16x16x32_bf16 v[126:129], v[144:147], v[202:205], v[126:129]
	v_mfma_f32_16x16x32_bf16 v[122:125], v[152:155], v[202:205], v[122:125]
	v_mfma_f32_16x16x32_bf16 v[110:113], v[144:147], v[210:213], v[110:113]
	v_mfma_f32_16x16x32_bf16 v[106:109], v[152:155], v[210:213], v[106:109]
	v_mfma_f32_16x16x32_bf16 v[94:97], v[144:147], v[218:221], v[94:97]
	v_mfma_f32_16x16x32_bf16 v[90:93], v[152:155], v[218:221], v[90:93]
	v_mfma_f32_16x16x32_bf16 v[78:81], v[144:147], v[226:229], v[78:81]
	v_mfma_f32_16x16x32_bf16 v[74:77], v[152:155], v[226:229], v[74:77]
	v_mfma_f32_16x16x32_bf16 v[126:129], v[148:151], v[206:209], v[126:129]
	v_mfma_f32_16x16x32_bf16 v[122:125], v[182:185], v[206:209], v[122:125]
	v_mfma_f32_16x16x32_bf16 v[110:113], v[148:151], v[214:217], v[110:113]
	v_mfma_f32_16x16x32_bf16 v[106:109], v[182:185], v[214:217], v[106:109]
	v_mfma_f32_16x16x32_bf16 v[94:97], v[148:151], v[222:225], v[94:97]
	v_mfma_f32_16x16x32_bf16 v[90:93], v[182:185], v[222:225], v[90:93]
	v_mfma_f32_16x16x32_bf16 v[78:81], v[148:151], v[230:233], v[78:81]
	v_mfma_f32_16x16x32_bf16 v[74:77], v[182:185], v[230:233], v[74:77]
	s_setprio 0
	s_setprio 1
	v_mfma_f32_16x16x32_bf16 v[118:121], v[186:189], v[202:205], v[118:121]
	v_mfma_f32_16x16x32_bf16 v[114:117], v[194:197], v[202:205], v[114:117]
	v_mfma_f32_16x16x32_bf16 v[102:105], v[186:189], v[210:213], v[102:105]
	v_mfma_f32_16x16x32_bf16 v[98:101], v[194:197], v[210:213], v[98:101]
	v_mfma_f32_16x16x32_bf16 v[86:89], v[186:189], v[218:221], v[86:89]
	v_mfma_f32_16x16x32_bf16 v[82:85], v[194:197], v[218:221], v[82:85]
	v_mfma_f32_16x16x32_bf16 v[70:73], v[186:189], v[226:229], v[70:73]
	v_mfma_f32_16x16x32_bf16 v[66:69], v[194:197], v[226:229], v[66:69]
	v_mfma_f32_16x16x32_bf16 v[118:121], v[190:193], v[206:209], v[118:121]
	v_mfma_f32_16x16x32_bf16 v[114:117], v[198:201], v[206:209], v[114:117]
	v_mfma_f32_16x16x32_bf16 v[102:105], v[190:193], v[214:217], v[102:105]
	v_mfma_f32_16x16x32_bf16 v[98:101], v[198:201], v[214:217], v[98:101]
	v_mfma_f32_16x16x32_bf16 v[86:89], v[190:193], v[222:225], v[86:89]
	v_mfma_f32_16x16x32_bf16 v[82:85], v[198:201], v[222:225], v[82:85]
	v_mfma_f32_16x16x32_bf16 v[70:73], v[190:193], v[230:233], v[70:73]
	v_mfma_f32_16x16x32_bf16 v[66:69], v[198:201], v[230:233], v[66:69]
	s_setprio 0
	s_barrier
; #define PG8_STAGE(bufoff, gbase, VO) do { _Pragma("unroll") for (int _i = 0; _i < 2; ++_i) \
;         __builtin_amdgcn_global_load_lds((const unsigned*)((const char*)(gbase) + VO[_i]), (LAS unsigned*)(lds + (bufoff) + ldsw + _i * 8192), 16, 0, 0); } while (0)
; #define PG8_LDA(dst, b, h) do { _Pragma("unroll") for (int m = 0; m < 4; ++m) _Pragma("unroll") for (int k = 0; k < 2; ++k) dst[m][k] = *(const LAS bf16x8*)(lds + PG8_SA(b, h) + aoff + m * 2048 + k * 1024); } while (0)
; #define PG8_MMA(ai, bj, At, Bt) do { __builtin_amdgcn_s_setprio(1); _Pragma("unroll") for (int m = 0; m < 4; ++m) _Pragma("unroll") for (int n = 0; n < 2; ++n) _Pragma("unroll") for (int k = 0; k < 2; ++k) \
;         acc[ai][bj][m][n] = __builtin_amdgcn_mfma_f32_16x16x32_bf16(Bt[n][k], At[m][k], acc[ai][bj][m][n], 0, 0, 0); __builtin_amdgcn_s_setprio(0); } while (0)
; #define PG8_WAIT_V(n) asm volatile("s_waitcnt vmcnt(" #n ")" ::: "memory")
; #define PG8_WAIT_L(n) asm volatile("s_waitcnt lgkmcnt(" #n ")" ::: "memory")
; #define PG8_BAR __builtin_amdgcn_s_barrier()
; #define PG8_SCHED __builtin_amdgcn_sched_barrier(0)
; template <int NSEG, class Epi, bool ALIGN_EPI = PG8_ALIGN, bool SP2 = PG8_SP2>
; DI void gemm_phase(LAS unsigned char* lds, const Gemm g, const StaticOrder& S, const Epi& E) {
;     ...
;             PG8_LDA(At, 1, 1); PG8_STAGE(PG8_SB(1, 0), b3, v2); PG8_STAGE(PG8_SB(1, 1), b3 + h2, v2); PG8_STAGE(PG8_SA(1, 0), a3, v2);
;             PG8_WAIT_V(8); PG8_WAIT_L(0); PG8_BAR; PG8_MMA(1, 0, At, B0); PG8_MMA(1, 1, At, B1); PG8_BAR; PG8_SCHED;
;     DI void operator()(const AccT& acc, const Unit& u, int wr, int wc, int fr, int fq) const {
;         const int pn = u.pn, rowbase = u.pm * 256 + wr * 64 + fr;
;         if (pn < 16) {
	s_add_i32 s40, s73, s51
	v_lshl_add_u64 v[234:235], v[234:235], 0, s[12:13]
	s_mov_b32 m0, s40
	ds_read_b128 v[202:205], v179 offset:49152
	ds_read_b128 v[206:209], v179 offset:50176
	ds_read_b128 v[210:213], v179 offset:51200
	ds_read_b128 v[214:217], v179 offset:52224
	ds_read_b128 v[218:221], v179 offset:53248
	ds_read_b128 v[222:225], v179 offset:54272
	ds_read_b128 v[226:229], v179 offset:55296
	ds_read_b128 v[230:233], v179 offset:56320
	global_load_lds_dwordx4 v[234:235], off
	s_add_i32 m0, s40, 0x2000
	s_add_u32 s36, s36, 0x80080
	v_lshl_add_u64 v[234:235], v[236:237], 0, s[12:13]
	s_addc_u32 s37, s37, 0
	s_add_i32 s40, s74, s51
	global_load_lds_dwordx4 v[234:235], off
	v_lshl_add_u64 v[234:235], s[36:37], 0, v[130:131]
	s_mov_b32 m0, s40
	s_nop 0
	global_load_lds_dwordx4 v[234:235], off
	v_lshl_add_u64 v[234:235], s[36:37], 0, v[132:133]
	s_add_i32 m0, s40, 0x2000
	s_nop 0
	global_load_lds_dwordx4 v[234:235], off
	v_lshl_add_u64 v[234:235], v[238:239], 0, s[12:13]
	s_mov_b32 m0, s57
	s_nop 0
	global_load_lds_dwordx4 v[234:235], off
	v_lshl_add_u64 v[234:235], v[240:241], 0, s[12:13]
	s_mov_b32 m0, s58
	s_nop 0
	global_load_lds_dwordx4 v[234:235], off
	s_waitcnt vmcnt(8)
	s_waitcnt lgkmcnt(0)
	s_setprio 1
	s_barrier
	v_mfma_f32_16x16x32_bf16 v[62:65], v[144:147], v[202:205], v[62:65]
	v_mfma_f32_16x16x32_bf16 v[58:61], v[152:155], v[202:205], v[58:61]
	v_mfma_f32_16x16x32_bf16 v[46:49], v[144:147], v[210:213], v[46:49]
	v_mfma_f32_16x16x32_bf16 v[42:45], v[152:155], v[210:213], v[42:45]
	v_mfma_f32_16x16x32_bf16 v[22:25], v[144:147], v[218:221], v[22:25]
	v_mfma_f32_16x16x32_bf16 v[18:21], v[152:155], v[218:221], v[18:21]
	v_mfma_f32_16x16x32_bf16 v[6:9], v[144:147], v[226:229], v[6:9]
	v_mfma_f32_16x16x32_bf16 v[2:5], v[152:155], v[226:229], v[2:5]
	v_mfma_f32_16x16x32_bf16 v[62:65], v[148:151], v[206:209], v[62:65]
	v_mfma_f32_16x16x32_bf16 v[58:61], v[182:185], v[206:209], v[58:61]
	v_mfma_f32_16x16x32_bf16 v[46:49], v[148:151], v[214:217], v[46:49]
	v_mfma_f32_16x16x32_bf16 v[42:45], v[182:185], v[214:217], v[42:45]
	v_mfma_f32_16x16x32_bf16 v[22:25], v[148:151], v[222:225], v[22:25]
	v_mfma_f32_16x16x32_bf16 v[18:21], v[182:185], v[222:225], v[18:21]
	v_mfma_f32_16x16x32_bf16 v[6:9], v[148:151], v[230:233], v[6:9]
	v_mfma_f32_16x16x32_bf16 v[2:5], v[182:185], v[230:233], v[2:5]
	s_setprio 0
	s_setprio 1
	v_mfma_f32_16x16x32_bf16 v[54:57], v[186:189], v[202:205], v[54:57]
	v_mfma_f32_16x16x32_bf16 v[50:53], v[194:197], v[202:205], v[50:53]
	v_mfma_f32_16x16x32_bf16 v[38:41], v[186:189], v[210:213], v[38:41]
	v_mfma_f32_16x16x32_bf16 v[26:29], v[194:197], v[210:213], v[26:29]
	v_mfma_f32_16x16x32_bf16 v[34:37], v[186:189], v[218:221], v[34:37]
	v_mfma_f32_16x16x32_bf16 v[30:33], v[194:197], v[218:221], v[30:33]
	v_mfma_f32_16x16x32_bf16 v[14:17], v[186:189], v[226:229], v[14:17]
	v_mfma_f32_16x16x32_bf16 v[10:13], v[194:197], v[226:229], v[10:13]
	v_mfma_f32_16x16x32_bf16 v[54:57], v[190:193], v[206:209], v[54:57]
	v_mfma_f32_16x16x32_bf16 v[50:53], v[198:201], v[206:209], v[50:53]
	v_mfma_f32_16x16x32_bf16 v[38:41], v[190:193], v[214:217], v[38:41]
	v_mfma_f32_16x16x32_bf16 v[26:29], v[198:201], v[214:217], v[26:29]
	v_mfma_f32_16x16x32_bf16 v[34:37], v[190:193], v[222:225], v[34:37]
	v_mfma_f32_16x16x32_bf16 v[30:33], v[198:201], v[222:225], v[30:33]
	v_mfma_f32_16x16x32_bf16 v[14:17], v[190:193], v[230:233], v[14:17]
	v_mfma_f32_16x16x32_bf16 v[10:13], v[198:201], v[230:233], v[10:13]
	s_setprio 0
	s_barrier
	s_add_i32 s72, s72, 2
	s_add_u32 s34, s34, 0x100
	s_addc_u32 s35, s35, 0
	s_add_u32 s70, s70, 0x100
	s_addc_u32 s71, s71, 0
	s_cmp_gt_u32 s72, 29
	s_cbranch_scc0 .LBB0_139
	s_and_b64 vcc, exec, s[14:15]
	s_cbranch_vccnz .LBB0_144
	v_lshl_add_u32 v144, s2, 8, v1
	s_cmp_gt_i32 s44, 15
	s_mov_b64 s[2:3], -1
	s_cbranch_scc1 .LBB0_145

; #define PG8_STAGE(bufoff, gbase, VO) do { _Pragma("unroll") for (int _i = 0; _i < 2; ++_i) \
;         __builtin_amdgcn_global_load_lds((const unsigned*)((const char*)(gbase) + VO[_i]), (LAS unsigned*)(lds + (bufoff) + ldsw + _i * 8192), 16, 0, 0); } while (0)
; #define PG8_LDA(dst, b, h) do { _Pragma("unroll") for (int m = 0; m < 4; ++m) _Pragma("unroll") for (int k = 0; k < 2; ++k) dst[m][k] = *(const LAS bf16x8*)(lds + PG8_SA(b, h) + aoff + m * 2048 + k * 1024); } while (0)
; #define PG8_LDB(dst, b, h) do { _Pragma("unroll") for (int n = 0; n < 2; ++n) _Pragma("unroll") for (int k = 0; k < 2; ++k) dst[n][k] = *(const LAS bf16x8*)(lds + PG8_SB(b, h) + boff + n * 2048 + k * 1024); } while (0)
; #define PG8_MMA(ai, bj, At, Bt) do { __builtin_amdgcn_s_setprio(1); _Pragma("unroll") for (int m = 0; m < 4; ++m) _Pragma("unroll") for (int n = 0; n < 2; ++n) _Pragma("unroll") for (int k = 0; k < 2; ++k) \
;         acc[ai][bj][m][n] = __builtin_amdgcn_mfma_f32_16x16x32_bf16(Bt[n][k], At[m][k], acc[ai][bj][m][n], 0, 0, 0); __builtin_amdgcn_s_setprio(0); } while (0)
; #define PG8_BAR __builtin_amdgcn_s_barrier()
; template <int NSEG, class Epi, bool ALIGN_EPI = PG8_ALIGN, bool SP2 = PG8_SP2>
; DI void gemm_phase(LAS unsigned char* lds, const Gemm g, const StaticOrder& S, const Epi& E) {
;     ...
;         for (int t = 0; t < nt; t += 2) {
;             const bool last = (t == nt - 2);
;             const char* a1 = cA + (size_t)(t + 1) * kstep;
;             const char* a2 = last ? nA : cA + (size_t)(t + 2) * kstep; const char* b2 = last ? nB : cB + (size_t)(t + 2) * kstep;
;             const char* a3 = a2 + kstep; const char* b3 = b2 + kstep;
;             unsigned v2[2]; v2[0] = (NSEG > 1 && last) ? voffN[0] : voffC[0]; v2[1] = (NSEG > 1 && last) ? voffN[1] : voffC[1];
;             const size_t h2 = (NSEG > 1 && last) ? hstepN : hstepC;
;             if constexpr (SP2) {
;             PG8_LDB(B0, 0, 0); PG8_LDB(B1, 0, 1); PG8_SCHED; PG8_LDA(At, 0, 0); PG8_STAGE(PG8_SA(1, 1), a1 + hstepC, voffC);
;             PG8_WAIT_V(8); PG8_WAIT_L(0); PG8_BAR; PG8_MMA(0, 0, At, B0); PG8_MMA(0, 1, At, B1); PG8_BAR; PG8_SCHED;
;             PG8_LDA(At, 0, 1); PG8_STAGE(PG8_SB(0, 0), b2, v2); PG8_STAGE(PG8_SB(0, 1), b2 + h2, v2); PG8_STAGE(PG8_SA(0, 0), a2, v2);
;             PG8_WAIT_V(8); PG8_WAIT_L(0); PG8_BAR; PG8_MMA(1, 0, At, B0); PG8_MMA(1, 1, At, B1); PG8_BAR; PG8_SCHED;
.LBB0_281:
	ds_read_b128 v[42:45], v250
	ds_read_b128 v[46:49], v250 offset:1024
	ds_read_b128 v[58:61], v250 offset:2048
	ds_read_b128 v[62:65], v250 offset:3072
	ds_read_b128 v[122:125], v251
	ds_read_b128 v[134:137], v251 offset:1024
	ds_read_b128 v[146:149], v251 offset:2048
	ds_read_b128 v[150:153], v251 offset:3072
	s_add_i32 m0, s37, 0xc000
	ds_read_b128 v[154:157], v252
	ds_read_b128 v[166:169], v252 offset:1024
	ds_read_b128 v[170:173], v252 offset:2048
	ds_read_b128 v[174:177], v252 offset:3072
	ds_read_b128 v[178:181], v252 offset:4096
	ds_read_b128 v[182:185], v252 offset:5120
	ds_read_b128 v[186:189], v252 offset:6144
	ds_read_b128 v[190:193], v252 offset:7168
	global_load_lds_dwordx4 v206, s[22:23]
	s_add_i32 m0, s37, 0xe000
	s_nop 0
	global_load_lds_dwordx4 v208, s[22:23]
	s_waitcnt vmcnt(8)
	s_waitcnt lgkmcnt(0)
	s_setprio 1
	s_barrier
	v_mfma_f32_16x16x32_bf16 v[162:165], v[42:45], v[154:157], v[162:165]
	v_mfma_f32_16x16x32_bf16 v[158:161], v[58:61], v[154:157], v[158:161]
	s_add_u32 s24, s22, 0xfff80080
	s_addc_u32 s25, s23, -1
	v_mfma_f32_16x16x32_bf16 v[130:133], v[42:45], v[170:173], v[130:133]
	v_mfma_f32_16x16x32_bf16 v[126:129], v[58:61], v[170:173], v[126:129]
	s_cmp_eq_u32 s56, 28
	s_cselect_b32 s27, s15, s25
	v_mfma_f32_16x16x32_bf16 v[110:113], v[42:45], v[178:181], v[110:113]
	v_mfma_f32_16x16x32_bf16 v[106:109], v[58:61], v[178:181], v[106:109]
	s_cselect_b32 s26, s17, s24
	s_cselect_b32 s25, s52, s55
	v_mfma_f32_16x16x32_bf16 v[94:97], v[42:45], v[186:189], v[94:97]
	v_mfma_f32_16x16x32_bf16 v[90:93], v[58:61], v[186:189], v[90:93]
	s_cselect_b32 s24, s53, s54
	v_mfma_f32_16x16x32_bf16 v[162:165], v[46:49], v[166:169], v[162:165]
	v_mfma_f32_16x16x32_bf16 v[158:161], v[62:65], v[166:169], v[158:161]
	v_mfma_f32_16x16x32_bf16 v[130:133], v[46:49], v[174:177], v[130:133]
	v_mfma_f32_16x16x32_bf16 v[126:129], v[62:65], v[174:177], v[126:129]
	v_mfma_f32_16x16x32_bf16 v[110:113], v[46:49], v[182:185], v[110:113]
	v_mfma_f32_16x16x32_bf16 v[106:109], v[62:65], v[182:185], v[106:109]
	v_mfma_f32_16x16x32_bf16 v[94:97], v[46:49], v[190:193], v[94:97]
	v_mfma_f32_16x16x32_bf16 v[90:93], v[62:65], v[190:193], v[90:93]
	s_setprio 0
	s_setprio 1
	v_mfma_f32_16x16x32_bf16 v[142:145], v[122:125], v[154:157], v[142:145]
	v_mfma_f32_16x16x32_bf16 v[138:141], v[146:149], v[154:157], v[138:141]
	v_mfma_f32_16x16x32_bf16 v[118:121], v[122:125], v[170:173], v[118:121]
	v_mfma_f32_16x16x32_bf16 v[114:117], v[146:149], v[170:173], v[114:117]
	v_mfma_f32_16x16x32_bf16 v[102:105], v[122:125], v[178:181], v[102:105]
	v_mfma_f32_16x16x32_bf16 v[98:101], v[146:149], v[178:181], v[98:101]
	v_mfma_f32_16x16x32_bf16 v[86:89], v[122:125], v[186:189], v[86:89]
	v_mfma_f32_16x16x32_bf16 v[82:85], v[146:149], v[186:189], v[82:85]
	v_mfma_f32_16x16x32_bf16 v[142:145], v[134:137], v[166:169], v[142:145]
	v_mfma_f32_16x16x32_bf16 v[138:141], v[150:153], v[166:169], v[138:141]
	v_mfma_f32_16x16x32_bf16 v[118:121], v[134:137], v[174:177], v[118:121]
	v_mfma_f32_16x16x32_bf16 v[114:117], v[150:153], v[174:177], v[114:117]
	v_mfma_f32_16x16x32_bf16 v[102:105], v[134:137], v[182:185], v[102:105]
	v_mfma_f32_16x16x32_bf16 v[98:101], v[150:153], v[182:185], v[98:101]
	v_mfma_f32_16x16x32_bf16 v[86:89], v[134:137], v[190:193], v[86:89]
	v_mfma_f32_16x16x32_bf16 v[82:85], v[150:153], v[190:193], v[82:85]
	s_setprio 0
	s_barrier
	s_add_i32 s57, s50, s36
	v_lshl_add_u64 v[194:195], s[24:25], 0, v[202:203]
	s_mov_b32 m0, s57
	ds_read_b128 v[154:157], v252 offset:16384
	ds_read_b128 v[166:169], v252 offset:17408
	ds_read_b128 v[170:173], v252 offset:18432
	ds_read_b128 v[174:177], v252 offset:19456
	ds_read_b128 v[178:181], v252 offset:20480
	ds_read_b128 v[182:185], v252 offset:21504
	ds_read_b128 v[186:189], v252 offset:22528
	ds_read_b128 v[190:193], v252 offset:23552
	global_load_lds_dwordx4 v[194:195], off
	s_add_i32 m0, s57, 0x2000
	s_add_u32 s58, s24, 0x80000
	v_lshl_add_u64 v[196:197], s[24:25], 0, v[204:205]
	s_addc_u32 s59, s25, 0
	s_add_i32 s57, s51, s36
	global_load_lds_dwordx4 v[196:197], off
	v_lshl_add_u64 v[198:199], s[58:59], 0, v[202:203]
	s_mov_b32 m0, s57
	v_lshl_add_u64 v[200:201], s[26:27], 0, v[204:205]
	global_load_lds_dwordx4 v[198:199], off
	v_lshl_add_u64 v[198:199], s[58:59], 0, v[204:205]
	s_add_i32 m0, s57, 0x2000
	s_nop 0
	global_load_lds_dwordx4 v[198:199], off
	v_lshl_add_u64 v[198:199], s[26:27], 0, v[202:203]
	s_mov_b32 m0, s37
	s_nop 0
	global_load_lds_dwordx4 v[198:199], off
	s_mov_b32 m0, s38
	s_nop 0
	global_load_lds_dwordx4 v[200:201], off
	s_waitcnt vmcnt(8)
	s_waitcnt lgkmcnt(0)
	s_setprio 1
	s_barrier
; #define PG8_STAGE(bufoff, gbase, VO) do { _Pragma("unroll") for (int _i = 0; _i < 2; ++_i) \
;         __builtin_amdgcn_global_load_lds((const unsigned*)((const char*)(gbase) + VO[_i]), (LAS unsigned*)(lds + (bufoff) + ldsw + _i * 8192), 16, 0, 0); } while (0)
; #define PG8_LDA(dst, b, h) do { _Pragma("unroll") for (int m = 0; m < 4; ++m) _Pragma("unroll") for (int k = 0; k < 2; ++k) dst[m][k] = *(const LAS bf16x8*)(lds + PG8_SA(b, h) + aoff + m * 2048 + k * 1024); } while (0)
; #define PG8_LDB(dst, b, h) do { _Pragma("unroll") for (int n = 0; n < 2; ++n) _Pragma("unroll") for (int k = 0; k < 2; ++k) dst[n][k] = *(const LAS bf16x8*)(lds + PG8_SB(b, h) + boff + n * 2048 + k * 1024); } while (0)
; #define PG8_MMA(ai, bj, At, Bt) do { __builtin_amdgcn_s_setprio(1); _Pragma("unroll") for (int m = 0; m < 4; ++m) _Pragma("unroll") for (int n = 0; n < 2; ++n) _Pragma("unroll") for (int k = 0; k < 2; ++k) \
;         acc[ai][bj][m][n] = __builtin_amdgcn_mfma_f32_16x16x32_bf16(Bt[n][k], At[m][k], acc[ai][bj][m][n], 0, 0, 0); __builtin_amdgcn_s_setprio(0); } while (0)
; #define PG8_WAIT_V(n) asm volatile("s_waitcnt vmcnt(" #n ")" ::: "memory")
; #define PG8_WAIT_L(n) asm volatile("s_waitcnt lgkmcnt(" #n ")" ::: "memory")
; #define PG8_BAR __builtin_amdgcn_s_barrier()
; #define PG8_SCHED __builtin_amdgcn_sched_barrier(0)
; template <int NSEG, class Epi, bool ALIGN_EPI = PG8_ALIGN, bool SP2 = PG8_SP2>
; DI void gemm_phase(LAS unsigned char* lds, const Gemm g, const StaticOrder& S, const Epi& E) {
;     ...
;             PG8_WAIT_V(8); PG8_WAIT_L(0); PG8_BAR; PG8_MMA(1, 0, At, B0); PG8_MMA(1, 1, At, B1); PG8_BAR; PG8_SCHED;
;             PG8_LDB(B0, 1, 0); PG8_LDB(B1, 1, 1); PG8_SCHED; PG8_LDA(At, 1, 0); PG8_STAGE(PG8_SA(0, 1), a2 + h2, v2);
;             PG8_WAIT_V(8); PG8_WAIT_L(0); PG8_BAR; PG8_MMA(0, 0, At, B0); PG8_MMA(0, 1, At, B1); PG8_BAR; PG8_SCHED;
	v_mfma_f32_16x16x32_bf16 v[78:81], v[42:45], v[154:157], v[78:81]
	v_mfma_f32_16x16x32_bf16 v[74:77], v[58:61], v[154:157], v[74:77]
	s_add_i32 s57, 0, 0x18000
	s_add_i32 s58, 0, 0x1c000
	v_mfma_f32_16x16x32_bf16 v[54:57], v[42:45], v[170:173], v[54:57]
	v_mfma_f32_16x16x32_bf16 v[50:53], v[58:61], v[170:173], v[50:53]
	s_add_u32 s26, s26, 0x80000
	s_addc_u32 s27, s27, 0
	v_mfma_f32_16x16x32_bf16 v[30:33], v[42:45], v[178:181], v[30:33]
	v_mfma_f32_16x16x32_bf16 v[26:29], v[58:61], v[178:181], v[26:29]
	v_mfma_f32_16x16x32_bf16 v[14:17], v[42:45], v[186:189], v[14:17]
	v_mfma_f32_16x16x32_bf16 v[10:13], v[58:61], v[186:189], v[10:13]
	v_mfma_f32_16x16x32_bf16 v[78:81], v[46:49], v[166:169], v[78:81]
	v_mfma_f32_16x16x32_bf16 v[74:77], v[62:65], v[166:169], v[74:77]
	v_mfma_f32_16x16x32_bf16 v[54:57], v[46:49], v[174:177], v[54:57]
	v_mfma_f32_16x16x32_bf16 v[50:53], v[62:65], v[174:177], v[50:53]
	v_mfma_f32_16x16x32_bf16 v[30:33], v[46:49], v[182:185], v[30:33]
	v_mfma_f32_16x16x32_bf16 v[26:29], v[62:65], v[182:185], v[26:29]
	v_mfma_f32_16x16x32_bf16 v[14:17], v[46:49], v[190:193], v[14:17]
	v_mfma_f32_16x16x32_bf16 v[10:13], v[62:65], v[190:193], v[10:13]
	s_setprio 0
	s_setprio 1
	v_mfma_f32_16x16x32_bf16 v[38:41], v[122:125], v[170:173], v[38:41]
	v_mfma_f32_16x16x32_bf16 v[34:37], v[146:149], v[170:173], v[34:37]
	v_mfma_f32_16x16x32_bf16 v[22:25], v[122:125], v[178:181], v[22:25]
	v_mfma_f32_16x16x32_bf16 v[18:21], v[146:149], v[178:181], v[18:21]
	v_mfma_f32_16x16x32_bf16 v[6:9], v[122:125], v[186:189], v[6:9]
	v_mfma_f32_16x16x32_bf16 v[2:5], v[146:149], v[186:189], v[2:5]
	v_mfma_f32_16x16x32_bf16 v[42:45], v[122:125], v[154:157], v[70:73]
	v_mfma_f32_16x16x32_bf16 v[46:49], v[146:149], v[154:157], v[66:69]
	v_mfma_f32_16x16x32_bf16 v[38:41], v[134:137], v[174:177], v[38:41]
	v_mfma_f32_16x16x32_bf16 v[34:37], v[150:153], v[174:177], v[34:37]
	v_mfma_f32_16x16x32_bf16 v[22:25], v[134:137], v[182:185], v[22:25]
	v_mfma_f32_16x16x32_bf16 v[18:21], v[150:153], v[182:185], v[18:21]
	v_mfma_f32_16x16x32_bf16 v[6:9], v[134:137], v[190:193], v[6:9]
	v_mfma_f32_16x16x32_bf16 v[2:5], v[150:153], v[190:193], v[2:5]
	v_mfma_f32_16x16x32_bf16 v[42:45], v[134:137], v[166:169], v[42:45]
	v_mfma_f32_16x16x32_bf16 v[46:49], v[150:153], v[166:169], v[46:49]
	s_setprio 0
	s_barrier
	v_add_u32_e32 v70, s57, v248
	v_add_u32_e32 v150, s58, v248
	ds_read_b128 v[58:61], v70
	ds_read_b128 v[62:65], v70 offset:1024
	ds_read_b128 v[66:69], v70 offset:2048
	ds_read_b128 v[70:73], v70 offset:3072
	ds_read_b128 v[122:125], v150
	ds_read_b128 v[134:137], v150 offset:1024
	ds_read_b128 v[146:149], v150 offset:2048
	ds_read_b128 v[150:153], v150 offset:3072
	s_mov_b32 m0, s39
	ds_read_b128 v[154:157], v252 offset:32768
	ds_read_b128 v[166:169], v252 offset:33792
	ds_read_b128 v[170:173], v252 offset:34816
	ds_read_b128 v[174:177], v252 offset:35840
	ds_read_b128 v[178:181], v252 offset:36864
	ds_read_b128 v[182:185], v252 offset:37888
	ds_read_b128 v[186:189], v252 offset:38912
	ds_read_b128 v[190:193], v252 offset:39936
	global_load_lds_dwordx4 v202, s[26:27]
	s_mov_b32 m0, s40
	s_nop 0
	global_load_lds_dwordx4 v204, s[26:27]
	s_waitcnt vmcnt(8)
	s_waitcnt lgkmcnt(0)
	s_setprio 1
	s_barrier
	v_mfma_f32_16x16x32_bf16 v[162:165], v[58:61], v[154:157], v[162:165]
	v_mfma_f32_16x16x32_bf16 v[158:161], v[66:69], v[154:157], v[158:161]
	v_mfma_f32_16x16x32_bf16 v[130:133], v[58:61], v[170:173], v[130:133]
	v_mfma_f32_16x16x32_bf16 v[126:129], v[66:69], v[170:173], v[126:129]
	v_mfma_f32_16x16x32_bf16 v[110:113], v[58:61], v[178:181], v[110:113]
	v_mfma_f32_16x16x32_bf16 v[106:109], v[66:69], v[178:181], v[106:109]
	v_mfma_f32_16x16x32_bf16 v[94:97], v[58:61], v[186:189], v[94:97]
	v_mfma_f32_16x16x32_bf16 v[90:93], v[66:69], v[186:189], v[90:93]
	v_mfma_f32_16x16x32_bf16 v[162:165], v[62:65], v[166:169], v[162:165]
	v_mfma_f32_16x16x32_bf16 v[158:161], v[70:73], v[166:169], v[158:161]
	v_mfma_f32_16x16x32_bf16 v[130:133], v[62:65], v[174:177], v[130:133]
	v_mfma_f32_16x16x32_bf16 v[126:129], v[70:73], v[174:177], v[126:129]
	v_mfma_f32_16x16x32_bf16 v[110:113], v[62:65], v[182:185], v[110:113]
	v_mfma_f32_16x16x32_bf16 v[106:109], v[70:73], v[182:185], v[106:109]
	v_mfma_f32_16x16x32_bf16 v[94:97], v[62:65], v[190:193], v[94:97]
	v_mfma_f32_16x16x32_bf16 v[90:93], v[70:73], v[190:193], v[90:93]
	s_setprio 0
	s_setprio 1
	v_mfma_f32_16x16x32_bf16 v[142:145], v[122:125], v[154:157], v[142:145]
	v_mfma_f32_16x16x32_bf16 v[138:141], v[146:149], v[154:157], v[138:141]
	v_mfma_f32_16x16x32_bf16 v[118:121], v[122:125], v[170:173], v[118:121]
	v_mfma_f32_16x16x32_bf16 v[114:117], v[146:149], v[170:173], v[114:117]
	v_mfma_f32_16x16x32_bf16 v[102:105], v[122:125], v[178:181], v[102:105]
	v_mfma_f32_16x16x32_bf16 v[98:101], v[146:149], v[178:181], v[98:101]
	v_mfma_f32_16x16x32_bf16 v[86:89], v[122:125], v[186:189], v[86:89]
	v_mfma_f32_16x16x32_bf16 v[82:85], v[146:149], v[186:189], v[82:85]
	v_mfma_f32_16x16x32_bf16 v[142:145], v[134:137], v[166:169], v[142:145]
	v_mfma_f32_16x16x32_bf16 v[138:141], v[150:153], v[166:169], v[138:141]
	v_mfma_f32_16x16x32_bf16 v[118:121], v[134:137], v[174:177], v[118:121]
	v_mfma_f32_16x16x32_bf16 v[114:117], v[150:153], v[174:177], v[114:117]
	v_mfma_f32_16x16x32_bf16 v[102:105], v[134:137], v[182:185], v[102:105]
	v_mfma_f32_16x16x32_bf16 v[98:101], v[150:153], v[182:185], v[98:101]
	v_mfma_f32_16x16x32_bf16 v[86:89], v[134:137], v[190:193], v[86:89]
	v_mfma_f32_16x16x32_bf16 v[82:85], v[150:153], v[190:193], v[82:85]
	s_setprio 0
	s_barrier
; #define PG8_STAGE(bufoff, gbase, VO) do { _Pragma("unroll") for (int _i = 0; _i < 2; ++_i) \
;         __builtin_amdgcn_global_load_lds((const unsigned*)((const char*)(gbase) + VO[_i]), (LAS unsigned*)(lds + (bufoff) + ldsw + _i * 8192), 16, 0, 0); } while (0)
; #define PG8_LDA(dst, b, h) do { _Pragma("unroll") for (int m = 0; m < 4; ++m) _Pragma("unroll") for (int k = 0; k < 2; ++k) dst[m][k] = *(const LAS bf16x8*)(lds + PG8_SA(b, h) + aoff + m * 2048 + k * 1024); } while (0)
; #define PG8_MMA(ai, bj, At, Bt) do { __builtin_amdgcn_s_setprio(1); _Pragma("unroll") for (int m = 0; m < 4; ++m) _Pragma("unroll") for (int n = 0; n < 2; ++n) _Pragma("unroll") for (int k = 0; k < 2; ++k) \
;         acc[ai][bj][m][n] = __builtin_amdgcn_mfma_f32_16x16x32_bf16(Bt[n][k], At[m][k], acc[ai][bj][m][n], 0, 0, 0); __builtin_amdgcn_s_setprio(0); } while (0)
; #define PG8_WAIT_V(n) asm volatile("s_waitcnt vmcnt(" #n ")" ::: "memory")
; #define PG8_WAIT_L(n) asm volatile("s_waitcnt lgkmcnt(" #n ")" ::: "memory")
; #define PG8_BAR __builtin_amdgcn_s_barrier()
; #define PG8_SCHED __builtin_amdgcn_sched_barrier(0)
; template <int NSEG, class Epi, bool ALIGN_EPI = PG8_ALIGN, bool SP2 = PG8_SP2>
; DI void gemm_phase(LAS unsigned char* lds, const Gemm g, const StaticOrder& S, const Epi& E) {
;     ...
;             PG8_LDA(At, 1, 1); PG8_STAGE(PG8_SB(1, 0), b3, v2); PG8_STAGE(PG8_SB(1, 1), b3 + h2, v2); PG8_STAGE(PG8_SA(1, 0), a3, v2);
;             PG8_WAIT_V(8); PG8_WAIT_L(0); PG8_BAR; PG8_MMA(1, 0, At, B0); PG8_MMA(1, 1, At, B1); PG8_BAR; PG8_SCHED;
;     ...
;         if constexpr (ALIGN_EPI) { if (wr == 0) PG8_BAR; }
	s_add_i32 s26, s57, s36
	v_lshl_add_u64 v[194:195], v[194:195], 0, s[10:11]
	s_mov_b32 m0, s26
	ds_read_b128 v[154:157], v252 offset:49152
	ds_read_b128 v[166:169], v252 offset:50176
	ds_read_b128 v[170:173], v252 offset:51200
	ds_read_b128 v[174:177], v252 offset:52224
	ds_read_b128 v[178:181], v252 offset:53248
	ds_read_b128 v[182:185], v252 offset:54272
	ds_read_b128 v[186:189], v252 offset:55296
	ds_read_b128 v[190:193], v252 offset:56320
	global_load_lds_dwordx4 v[194:195], off
	s_add_i32 m0, s26, 0x2000
	s_add_u32 s24, s24, 0x80080
	v_lshl_add_u64 v[194:195], v[196:197], 0, s[10:11]
	s_addc_u32 s25, s25, 0
	s_add_i32 s26, s58, s36
	global_load_lds_dwordx4 v[194:195], off
	v_lshl_add_u64 v[194:195], s[24:25], 0, v[202:203]
	s_mov_b32 m0, s26
	s_nop 0
	global_load_lds_dwordx4 v[194:195], off
	v_lshl_add_u64 v[194:195], s[24:25], 0, v[204:205]
	s_add_i32 m0, s26, 0x2000
	s_nop 0
	global_load_lds_dwordx4 v[194:195], off
	v_lshl_add_u64 v[194:195], v[198:199], 0, s[10:11]
	s_mov_b32 m0, s48
	s_nop 0
	global_load_lds_dwordx4 v[194:195], off
	v_lshl_add_u64 v[194:195], v[200:201], 0, s[10:11]
	s_mov_b32 m0, s49
	s_nop 0
	global_load_lds_dwordx4 v[194:195], off
	s_waitcnt vmcnt(8)
	s_waitcnt lgkmcnt(0)
	s_setprio 1
	s_barrier
	v_mfma_f32_16x16x32_bf16 v[78:81], v[58:61], v[154:157], v[78:81]
	v_mfma_f32_16x16x32_bf16 v[74:77], v[66:69], v[154:157], v[74:77]
	v_mfma_f32_16x16x32_bf16 v[54:57], v[58:61], v[170:173], v[54:57]
	v_mfma_f32_16x16x32_bf16 v[50:53], v[66:69], v[170:173], v[50:53]
	v_mfma_f32_16x16x32_bf16 v[30:33], v[58:61], v[178:181], v[30:33]
	v_mfma_f32_16x16x32_bf16 v[26:29], v[66:69], v[178:181], v[26:29]
	v_mfma_f32_16x16x32_bf16 v[14:17], v[58:61], v[186:189], v[14:17]
	v_mfma_f32_16x16x32_bf16 v[10:13], v[66:69], v[186:189], v[10:13]
	v_mfma_f32_16x16x32_bf16 v[78:81], v[62:65], v[166:169], v[78:81]
	v_mfma_f32_16x16x32_bf16 v[74:77], v[70:73], v[166:169], v[74:77]
	v_mfma_f32_16x16x32_bf16 v[54:57], v[62:65], v[174:177], v[54:57]
	v_mfma_f32_16x16x32_bf16 v[50:53], v[70:73], v[174:177], v[50:53]
	v_mfma_f32_16x16x32_bf16 v[30:33], v[62:65], v[182:185], v[30:33]
	v_mfma_f32_16x16x32_bf16 v[26:29], v[70:73], v[182:185], v[26:29]
	v_mfma_f32_16x16x32_bf16 v[14:17], v[62:65], v[190:193], v[14:17]
	v_mfma_f32_16x16x32_bf16 v[10:13], v[70:73], v[190:193], v[10:13]
	s_setprio 0
	s_setprio 1
	v_mfma_f32_16x16x32_bf16 v[42:45], v[122:125], v[154:157], v[42:45]
	v_mfma_f32_16x16x32_bf16 v[70:73], v[134:137], v[166:169], v[42:45]
	v_mfma_f32_16x16x32_bf16 v[42:45], v[146:149], v[154:157], v[46:49]
	v_mfma_f32_16x16x32_bf16 v[38:41], v[122:125], v[170:173], v[38:41]
	v_mfma_f32_16x16x32_bf16 v[34:37], v[146:149], v[170:173], v[34:37]
	v_mfma_f32_16x16x32_bf16 v[22:25], v[122:125], v[178:181], v[22:25]
	v_mfma_f32_16x16x32_bf16 v[18:21], v[146:149], v[178:181], v[18:21]
	v_mfma_f32_16x16x32_bf16 v[6:9], v[122:125], v[186:189], v[6:9]
	v_mfma_f32_16x16x32_bf16 v[2:5], v[146:149], v[186:189], v[2:5]
	v_mfma_f32_16x16x32_bf16 v[66:69], v[150:153], v[166:169], v[42:45]
	v_mfma_f32_16x16x32_bf16 v[38:41], v[134:137], v[174:177], v[38:41]
	v_mfma_f32_16x16x32_bf16 v[34:37], v[150:153], v[174:177], v[34:37]
	v_mfma_f32_16x16x32_bf16 v[22:25], v[134:137], v[182:185], v[22:25]
	v_mfma_f32_16x16x32_bf16 v[18:21], v[150:153], v[182:185], v[18:21]
	v_mfma_f32_16x16x32_bf16 v[6:9], v[134:137], v[190:193], v[6:9]
	v_mfma_f32_16x16x32_bf16 v[2:5], v[150:153], v[190:193], v[2:5]
	s_setprio 0
	s_barrier
	s_add_i32 s56, s56, 2
	s_add_u32 s22, s22, 0x100
	s_addc_u32 s23, s23, 0
	s_add_u32 s54, s54, 0x100
	s_addc_u32 s55, s55, 0
	s_cmp_gt_u32 s56, 29
	s_cbranch_scc0 .LBB0_281
	s_and_b64 vcc, exec, s[12:13]
	s_cbranch_vccz .LBB0_284
	s_barrier

; #define PG8_STAGE(bufoff, gbase, VO) do { _Pragma("unroll") for (int _i = 0; _i < 2; ++_i) \
;         __builtin_amdgcn_global_load_lds((const unsigned*)((const char*)(gbase) + VO[_i]), (LAS unsigned*)(lds + (bufoff) + ldsw + _i * 8192), 16, 0, 0); } while (0)
; #define PG8_LDA(dst, b, h) do { _Pragma("unroll") for (int m = 0; m < 4; ++m) _Pragma("unroll") for (int k = 0; k < 2; ++k) dst[m][k] = *(const LAS bf16x8*)(lds + PG8_SA(b, h) + aoff + m * 2048 + k * 1024); } while (0)
; #define PG8_LDB(dst, b, h) do { _Pragma("unroll") for (int n = 0; n < 2; ++n) _Pragma("unroll") for (int k = 0; k < 2; ++k) dst[n][k] = *(const LAS bf16x8*)(lds + PG8_SB(b, h) + boff + n * 2048 + k * 1024); } while (0)
; #define PG8_MMA(ai, bj, At, Bt) do { __builtin_amdgcn_s_setprio(1); _Pragma("unroll") for (int m = 0; m < 4; ++m) _Pragma("unroll") for (int n = 0; n < 2; ++n) _Pragma("unroll") for (int k = 0; k < 2; ++k) \
;         acc[ai][bj][m][n] = __builtin_amdgcn_mfma_f32_16x16x32_bf16(Bt[n][k], At[m][k], acc[ai][bj][m][n], 0, 0, 0); __builtin_amdgcn_s_setprio(0); } while (0)
; #define PG8_BAR __builtin_amdgcn_s_barrier()
; template <int NSEG, class Epi, bool ALIGN_EPI = PG8_ALIGN, bool SP2 = PG8_SP2>
; DI void gemm_phase(LAS unsigned char* lds, const Gemm g, const StaticOrder& S, const Epi& E) {
;     ...
;         for (int t = 0; t < nt; t += 2) {
;             const bool last = (t == nt - 2);
;             const char* a1 = cA + (size_t)(t + 1) * kstep;
;             const char* a2 = last ? nA : cA + (size_t)(t + 2) * kstep; const char* b2 = last ? nB : cB + (size_t)(t + 2) * kstep;
;             const char* a3 = a2 + kstep; const char* b3 = b2 + kstep;
;             unsigned v2[2]; v2[0] = (NSEG > 1 && last) ? voffN[0] : voffC[0]; v2[1] = (NSEG > 1 && last) ? voffN[1] : voffC[1];
;             const size_t h2 = (NSEG > 1 && last) ? hstepN : hstepC;
;             if constexpr (SP2) {
;             PG8_LDB(B0, 0, 0); PG8_LDB(B1, 0, 1); PG8_SCHED; PG8_LDA(At, 0, 0); PG8_STAGE(PG8_SA(1, 1), a1 + hstepC, voffC);
;             PG8_WAIT_V(8); PG8_WAIT_L(0); PG8_BAR; PG8_MMA(0, 0, At, B0); PG8_MMA(0, 1, At, B1); PG8_BAR; PG8_SCHED;
;             PG8_LDA(At, 0, 1); PG8_STAGE(PG8_SB(0, 0), b2, v2); PG8_STAGE(PG8_SB(0, 1), b2 + h2, v2); PG8_STAGE(PG8_SA(0, 0), a2, v2);
;             PG8_WAIT_V(8); PG8_WAIT_L(0); PG8_BAR; PG8_MMA(1, 0, At, B0); PG8_MMA(1, 1, At, B1); PG8_BAR; PG8_SCHED;
.LBB0_305:
	ds_read_b128 v[130:133], v161
	ds_read_b128 v[134:137], v161 offset:1024
	ds_read_b128 v[150:153], v161 offset:2048
	ds_read_b128 v[154:157], v161 offset:3072
	ds_read_b128 v[164:167], v162
	ds_read_b128 v[168:171], v162 offset:1024
	ds_read_b128 v[172:175], v162 offset:2048
	ds_read_b128 v[176:179], v162 offset:3072
	s_add_i32 m0, s35, 0xc000
	ds_read_b128 v[180:183], v163
	ds_read_b128 v[184:187], v163 offset:1024
	ds_read_b128 v[188:191], v163 offset:2048
	ds_read_b128 v[192:195], v163 offset:3072
	ds_read_b128 v[196:199], v163 offset:4096
	ds_read_b128 v[200:203], v163 offset:5120
	ds_read_b128 v[204:207], v163 offset:6144
	ds_read_b128 v[208:211], v163 offset:7168
	global_load_lds_dwordx4 v142, s[36:37]
	s_add_i32 m0, s35, 0xe000
	s_nop 0
	global_load_lds_dwordx4 v144, s[36:37]
	s_waitcnt vmcnt(8)
	s_waitcnt lgkmcnt(0)
	s_setprio 1
	s_barrier
	v_mfma_f32_16x16x32_bf16 v[126:129], v[130:133], v[180:183], v[126:129]
	v_mfma_f32_16x16x32_bf16 v[122:125], v[150:153], v[180:183], v[122:125]
	s_add_u32 s38, s36, 0xfff80080
	s_addc_u32 s39, s37, -1
	v_mfma_f32_16x16x32_bf16 v[118:121], v[130:133], v[188:191], v[118:121]
	v_mfma_f32_16x16x32_bf16 v[114:117], v[150:153], v[188:191], v[114:117]
	s_cmp_eq_u32 s66, 28
	s_cselect_b32 s41, s21, s39
	v_mfma_f32_16x16x32_bf16 v[110:113], v[130:133], v[196:199], v[110:113]
	v_mfma_f32_16x16x32_bf16 v[106:109], v[150:153], v[196:199], v[106:109]
	s_cselect_b32 s40, s23, s38
	s_cselect_b32 s39, s62, s65
	v_mfma_f32_16x16x32_bf16 v[102:105], v[130:133], v[204:207], v[102:105]
	v_mfma_f32_16x16x32_bf16 v[98:101], v[150:153], v[204:207], v[98:101]
	s_cselect_b32 s38, s63, s64
	v_mfma_f32_16x16x32_bf16 v[126:129], v[134:137], v[184:187], v[126:129]
	v_mfma_f32_16x16x32_bf16 v[122:125], v[154:157], v[184:187], v[122:125]
	v_mfma_f32_16x16x32_bf16 v[118:121], v[134:137], v[192:195], v[118:121]
	v_mfma_f32_16x16x32_bf16 v[114:117], v[154:157], v[192:195], v[114:117]
	v_mfma_f32_16x16x32_bf16 v[110:113], v[134:137], v[200:203], v[110:113]
	v_mfma_f32_16x16x32_bf16 v[106:109], v[154:157], v[200:203], v[106:109]
	v_mfma_f32_16x16x32_bf16 v[102:105], v[134:137], v[208:211], v[102:105]
	v_mfma_f32_16x16x32_bf16 v[98:101], v[154:157], v[208:211], v[98:101]
	s_setprio 0
	s_setprio 1
	v_mfma_f32_16x16x32_bf16 v[62:65], v[164:167], v[180:183], v[62:65]
	v_mfma_f32_16x16x32_bf16 v[58:61], v[172:175], v[180:183], v[58:61]
	v_mfma_f32_16x16x32_bf16 v[54:57], v[164:167], v[188:191], v[54:57]
	v_mfma_f32_16x16x32_bf16 v[50:53], v[172:175], v[188:191], v[50:53]
	v_mfma_f32_16x16x32_bf16 v[46:49], v[164:167], v[196:199], v[46:49]
	v_mfma_f32_16x16x32_bf16 v[42:45], v[172:175], v[196:199], v[42:45]
	v_mfma_f32_16x16x32_bf16 v[38:41], v[164:167], v[204:207], v[38:41]
	v_mfma_f32_16x16x32_bf16 v[34:37], v[172:175], v[204:207], v[34:37]
	v_mfma_f32_16x16x32_bf16 v[62:65], v[168:171], v[184:187], v[62:65]
	v_mfma_f32_16x16x32_bf16 v[58:61], v[176:179], v[184:187], v[58:61]
	v_mfma_f32_16x16x32_bf16 v[54:57], v[168:171], v[192:195], v[54:57]
	v_mfma_f32_16x16x32_bf16 v[50:53], v[176:179], v[192:195], v[50:53]
	v_mfma_f32_16x16x32_bf16 v[46:49], v[168:171], v[200:203], v[46:49]
	v_mfma_f32_16x16x32_bf16 v[42:45], v[176:179], v[200:203], v[42:45]
	v_mfma_f32_16x16x32_bf16 v[38:41], v[168:171], v[208:211], v[38:41]
	v_mfma_f32_16x16x32_bf16 v[34:37], v[176:179], v[208:211], v[34:37]
	s_setprio 0
	s_barrier
	s_add_i32 s67, s55, s48
	v_lshl_add_u64 v[212:213], s[38:39], 0, v[138:139]
	s_mov_b32 m0, s67
	ds_read_b128 v[180:183], v163 offset:16384
	ds_read_b128 v[184:187], v163 offset:17408
	ds_read_b128 v[188:191], v163 offset:18432
	ds_read_b128 v[192:195], v163 offset:19456
	ds_read_b128 v[196:199], v163 offset:20480
	ds_read_b128 v[200:203], v163 offset:21504
	ds_read_b128 v[204:207], v163 offset:22528
	ds_read_b128 v[208:211], v163 offset:23552
	global_load_lds_dwordx4 v[212:213], off
	s_add_i32 m0, s67, 0x2000
	s_add_u32 s68, s38, 0x80000
	v_lshl_add_u64 v[214:215], s[38:39], 0, v[140:141]
	s_addc_u32 s69, s39, 0
	s_add_i32 s67, s56, s48
	global_load_lds_dwordx4 v[214:215], off
	v_lshl_add_u64 v[216:217], s[68:69], 0, v[138:139]
	s_mov_b32 m0, s67
	v_lshl_add_u64 v[218:219], s[40:41], 0, v[140:141]
	global_load_lds_dwordx4 v[216:217], off
	v_lshl_add_u64 v[216:217], s[68:69], 0, v[140:141]
	s_add_i32 m0, s67, 0x2000
	s_nop 0
	global_load_lds_dwordx4 v[216:217], off
	v_lshl_add_u64 v[216:217], s[40:41], 0, v[138:139]
	s_mov_b32 m0, s35
	s_nop 0
	global_load_lds_dwordx4 v[216:217], off
	s_mov_b32 m0, s49
	s_nop 0
	global_load_lds_dwordx4 v[218:219], off
	s_waitcnt vmcnt(8)
	s_waitcnt lgkmcnt(0)
	s_setprio 1
	s_barrier
; #define PG8_STAGE(bufoff, gbase, VO) do { _Pragma("unroll") for (int _i = 0; _i < 2; ++_i) \
;         __builtin_amdgcn_global_load_lds((const unsigned*)((const char*)(gbase) + VO[_i]), (LAS unsigned*)(lds + (bufoff) + ldsw + _i * 8192), 16, 0, 0); } while (0)
; #define PG8_LDA(dst, b, h) do { _Pragma("unroll") for (int m = 0; m < 4; ++m) _Pragma("unroll") for (int k = 0; k < 2; ++k) dst[m][k] = *(const LAS bf16x8*)(lds + PG8_SA(b, h) + aoff + m * 2048 + k * 1024); } while (0)
; #define PG8_LDB(dst, b, h) do { _Pragma("unroll") for (int n = 0; n < 2; ++n) _Pragma("unroll") for (int k = 0; k < 2; ++k) dst[n][k] = *(const LAS bf16x8*)(lds + PG8_SB(b, h) + boff + n * 2048 + k * 1024); } while (0)
; #define PG8_MMA(ai, bj, At, Bt) do { __builtin_amdgcn_s_setprio(1); _Pragma("unroll") for (int m = 0; m < 4; ++m) _Pragma("unroll") for (int n = 0; n < 2; ++n) _Pragma("unroll") for (int k = 0; k < 2; ++k) \
;         acc[ai][bj][m][n] = __builtin_amdgcn_mfma_f32_16x16x32_bf16(Bt[n][k], At[m][k], acc[ai][bj][m][n], 0, 0, 0); __builtin_amdgcn_s_setprio(0); } while (0)
; #define PG8_WAIT_V(n) asm volatile("s_waitcnt vmcnt(" #n ")" ::: "memory")
; #define PG8_WAIT_L(n) asm volatile("s_waitcnt lgkmcnt(" #n ")" ::: "memory")
; #define PG8_BAR __builtin_amdgcn_s_barrier()
; #define PG8_SCHED __builtin_amdgcn_sched_barrier(0)
; template <int NSEG, class Epi, bool ALIGN_EPI = PG8_ALIGN, bool SP2 = PG8_SP2>
; DI void gemm_phase(LAS unsigned char* lds, const Gemm g, const StaticOrder& S, const Epi& E) {
;     ...
;             PG8_WAIT_V(8); PG8_WAIT_L(0); PG8_BAR; PG8_MMA(1, 0, At, B0); PG8_MMA(1, 1, At, B1); PG8_BAR; PG8_SCHED;
;             PG8_LDB(B0, 1, 0); PG8_LDB(B1, 1, 1); PG8_SCHED; PG8_LDA(At, 1, 0); PG8_STAGE(PG8_SA(0, 1), a2 + h2, v2);
;             PG8_WAIT_V(8); PG8_WAIT_L(0); PG8_BAR; PG8_MMA(0, 0, At, B0); PG8_MMA(0, 1, At, B1); PG8_BAR; PG8_SCHED;
	v_mfma_f32_16x16x32_bf16 v[94:97], v[130:133], v[180:183], v[94:97]
	v_mfma_f32_16x16x32_bf16 v[90:93], v[150:153], v[180:183], v[90:93]
	s_add_i32 s67, 0, 0x18000
	s_add_i32 s68, 0, 0x1c000
	v_mfma_f32_16x16x32_bf16 v[86:89], v[130:133], v[188:191], v[86:89]
	v_mfma_f32_16x16x32_bf16 v[82:85], v[150:153], v[188:191], v[82:85]
	s_add_u32 s40, s40, 0x80000
	s_addc_u32 s41, s41, 0
	v_mfma_f32_16x16x32_bf16 v[78:81], v[130:133], v[196:199], v[78:81]
	v_mfma_f32_16x16x32_bf16 v[74:77], v[150:153], v[196:199], v[74:77]
	v_mfma_f32_16x16x32_bf16 v[70:73], v[130:133], v[204:207], v[70:73]
	v_mfma_f32_16x16x32_bf16 v[66:69], v[150:153], v[204:207], v[66:69]
	v_mfma_f32_16x16x32_bf16 v[94:97], v[134:137], v[184:187], v[94:97]
	v_mfma_f32_16x16x32_bf16 v[90:93], v[154:157], v[184:187], v[90:93]
	v_mfma_f32_16x16x32_bf16 v[86:89], v[134:137], v[192:195], v[86:89]
	v_mfma_f32_16x16x32_bf16 v[82:85], v[154:157], v[192:195], v[82:85]
	v_mfma_f32_16x16x32_bf16 v[78:81], v[134:137], v[200:203], v[78:81]
	v_mfma_f32_16x16x32_bf16 v[74:77], v[154:157], v[200:203], v[74:77]
	v_mfma_f32_16x16x32_bf16 v[70:73], v[134:137], v[208:211], v[70:73]
	v_mfma_f32_16x16x32_bf16 v[66:69], v[154:157], v[208:211], v[66:69]
	s_setprio 0
	s_setprio 1
	v_mfma_f32_16x16x32_bf16 v[30:33], v[164:167], v[180:183], v[30:33]
	v_mfma_f32_16x16x32_bf16 v[26:29], v[172:175], v[180:183], v[26:29]
	v_mfma_f32_16x16x32_bf16 v[14:17], v[164:167], v[188:191], v[14:17]
	v_mfma_f32_16x16x32_bf16 v[2:5], v[172:175], v[188:191], v[2:5]
	v_mfma_f32_16x16x32_bf16 v[22:25], v[164:167], v[196:199], v[22:25]
	v_mfma_f32_16x16x32_bf16 v[18:21], v[172:175], v[196:199], v[18:21]
	v_mfma_f32_16x16x32_bf16 v[10:13], v[164:167], v[204:207], v[10:13]
	v_mfma_f32_16x16x32_bf16 v[6:9], v[172:175], v[204:207], v[6:9]
	v_mfma_f32_16x16x32_bf16 v[30:33], v[168:171], v[184:187], v[30:33]
	v_mfma_f32_16x16x32_bf16 v[26:29], v[176:179], v[184:187], v[26:29]
	v_mfma_f32_16x16x32_bf16 v[14:17], v[168:171], v[192:195], v[14:17]
	v_mfma_f32_16x16x32_bf16 v[2:5], v[176:179], v[192:195], v[2:5]
	v_mfma_f32_16x16x32_bf16 v[22:25], v[168:171], v[200:203], v[22:25]
	v_mfma_f32_16x16x32_bf16 v[18:21], v[176:179], v[200:203], v[18:21]
	v_mfma_f32_16x16x32_bf16 v[10:13], v[168:171], v[208:211], v[10:13]
	v_mfma_f32_16x16x32_bf16 v[6:9], v[176:179], v[208:211], v[6:9]
	s_setprio 0
	s_barrier
	v_add_u32_e32 v154, s67, v159
	v_add_u32_e32 v176, s68, v159
	ds_read_b128 v[130:133], v154
	ds_read_b128 v[134:137], v154 offset:1024
	ds_read_b128 v[150:153], v154 offset:2048
	ds_read_b128 v[154:157], v154 offset:3072
	ds_read_b128 v[164:167], v176
	ds_read_b128 v[168:171], v176 offset:1024
	ds_read_b128 v[172:175], v176 offset:2048
	ds_read_b128 v[176:179], v176 offset:3072
	s_mov_b32 m0, s50
	ds_read_b128 v[180:183], v163 offset:32768
	ds_read_b128 v[184:187], v163 offset:33792
	ds_read_b128 v[188:191], v163 offset:34816
	ds_read_b128 v[192:195], v163 offset:35840
	ds_read_b128 v[196:199], v163 offset:36864
	ds_read_b128 v[200:203], v163 offset:37888
	ds_read_b128 v[204:207], v163 offset:38912
	ds_read_b128 v[208:211], v163 offset:39936
	global_load_lds_dwordx4 v138, s[40:41]
	s_mov_b32 m0, s51
	s_nop 0
	global_load_lds_dwordx4 v140, s[40:41]
	s_waitcnt vmcnt(8)
	s_waitcnt lgkmcnt(0)
	s_setprio 1
	s_barrier
	v_mfma_f32_16x16x32_bf16 v[126:129], v[130:133], v[180:183], v[126:129]
	v_mfma_f32_16x16x32_bf16 v[122:125], v[150:153], v[180:183], v[122:125]
	v_mfma_f32_16x16x32_bf16 v[118:121], v[130:133], v[188:191], v[118:121]
	v_mfma_f32_16x16x32_bf16 v[114:117], v[150:153], v[188:191], v[114:117]
	v_mfma_f32_16x16x32_bf16 v[110:113], v[130:133], v[196:199], v[110:113]
	v_mfma_f32_16x16x32_bf16 v[106:109], v[150:153], v[196:199], v[106:109]
	v_mfma_f32_16x16x32_bf16 v[102:105], v[130:133], v[204:207], v[102:105]
	v_mfma_f32_16x16x32_bf16 v[98:101], v[150:153], v[204:207], v[98:101]
	v_mfma_f32_16x16x32_bf16 v[126:129], v[134:137], v[184:187], v[126:129]
	v_mfma_f32_16x16x32_bf16 v[122:125], v[154:157], v[184:187], v[122:125]
	v_mfma_f32_16x16x32_bf16 v[118:121], v[134:137], v[192:195], v[118:121]
	v_mfma_f32_16x16x32_bf16 v[114:117], v[154:157], v[192:195], v[114:117]
	v_mfma_f32_16x16x32_bf16 v[110:113], v[134:137], v[200:203], v[110:113]
	v_mfma_f32_16x16x32_bf16 v[106:109], v[154:157], v[200:203], v[106:109]
	v_mfma_f32_16x16x32_bf16 v[102:105], v[134:137], v[208:211], v[102:105]
	v_mfma_f32_16x16x32_bf16 v[98:101], v[154:157], v[208:211], v[98:101]
	s_setprio 0
	s_setprio 1
	v_mfma_f32_16x16x32_bf16 v[62:65], v[164:167], v[180:183], v[62:65]
	v_mfma_f32_16x16x32_bf16 v[58:61], v[172:175], v[180:183], v[58:61]
	v_mfma_f32_16x16x32_bf16 v[54:57], v[164:167], v[188:191], v[54:57]
	v_mfma_f32_16x16x32_bf16 v[50:53], v[172:175], v[188:191], v[50:53]
	v_mfma_f32_16x16x32_bf16 v[46:49], v[164:167], v[196:199], v[46:49]
	v_mfma_f32_16x16x32_bf16 v[42:45], v[172:175], v[196:199], v[42:45]
	v_mfma_f32_16x16x32_bf16 v[38:41], v[164:167], v[204:207], v[38:41]
	v_mfma_f32_16x16x32_bf16 v[34:37], v[172:175], v[204:207], v[34:37]
	v_mfma_f32_16x16x32_bf16 v[62:65], v[168:171], v[184:187], v[62:65]
	v_mfma_f32_16x16x32_bf16 v[58:61], v[176:179], v[184:187], v[58:61]
	v_mfma_f32_16x16x32_bf16 v[54:57], v[168:171], v[192:195], v[54:57]
	v_mfma_f32_16x16x32_bf16 v[50:53], v[176:179], v[192:195], v[50:53]
	v_mfma_f32_16x16x32_bf16 v[46:49], v[168:171], v[200:203], v[46:49]
	v_mfma_f32_16x16x32_bf16 v[42:45], v[176:179], v[200:203], v[42:45]
	v_mfma_f32_16x16x32_bf16 v[38:41], v[168:171], v[208:211], v[38:41]
	v_mfma_f32_16x16x32_bf16 v[34:37], v[176:179], v[208:211], v[34:37]
	s_setprio 0
	s_barrier
; #define PG8_STAGE(bufoff, gbase, VO) do { _Pragma("unroll") for (int _i = 0; _i < 2; ++_i) \
;         __builtin_amdgcn_global_load_lds((const unsigned*)((const char*)(gbase) + VO[_i]), (LAS unsigned*)(lds + (bufoff) + ldsw + _i * 8192), 16, 0, 0); } while (0)
; #define PG8_LDA(dst, b, h) do { _Pragma("unroll") for (int m = 0; m < 4; ++m) _Pragma("unroll") for (int k = 0; k < 2; ++k) dst[m][k] = *(const LAS bf16x8*)(lds + PG8_SA(b, h) + aoff + m * 2048 + k * 1024); } while (0)
; #define PG8_MMA(ai, bj, At, Bt) do { __builtin_amdgcn_s_setprio(1); _Pragma("unroll") for (int m = 0; m < 4; ++m) _Pragma("unroll") for (int n = 0; n < 2; ++n) _Pragma("unroll") for (int k = 0; k < 2; ++k) \
;         acc[ai][bj][m][n] = __builtin_amdgcn_mfma_f32_16x16x32_bf16(Bt[n][k], At[m][k], acc[ai][bj][m][n], 0, 0, 0); __builtin_amdgcn_s_setprio(0); } while (0)
; #define PG8_WAIT_V(n) asm volatile("s_waitcnt vmcnt(" #n ")" ::: "memory")
; #define PG8_WAIT_L(n) asm volatile("s_waitcnt lgkmcnt(" #n ")" ::: "memory")
; #define PG8_BAR __builtin_amdgcn_s_barrier()
; #define PG8_SCHED __builtin_amdgcn_sched_barrier(0)
; template <int NSEG, class Epi, bool ALIGN_EPI = PG8_ALIGN, bool SP2 = PG8_SP2>
; DI void gemm_phase(LAS unsigned char* lds, const Gemm g, const StaticOrder& S, const Epi& E) {
;     ...
;             PG8_LDA(At, 1, 1); PG8_STAGE(PG8_SB(1, 0), b3, v2); PG8_STAGE(PG8_SB(1, 1), b3 + h2, v2); PG8_STAGE(PG8_SA(1, 0), a3, v2);
;             PG8_WAIT_V(8); PG8_WAIT_L(0); PG8_BAR; PG8_MMA(1, 0, At, B0); PG8_MMA(1, 1, At, B1); PG8_BAR; PG8_SCHED;
;     ...
;         if constexpr (ALIGN_EPI) { if (wr == 0) PG8_BAR; }
	s_add_i32 s40, s67, s48
	v_lshl_add_u64 v[212:213], v[212:213], 0, s[8:9]
	s_mov_b32 m0, s40
	ds_read_b128 v[180:183], v163 offset:49152
	ds_read_b128 v[184:187], v163 offset:50176
	ds_read_b128 v[188:191], v163 offset:51200
	ds_read_b128 v[192:195], v163 offset:52224
	ds_read_b128 v[196:199], v163 offset:53248
	ds_read_b128 v[200:203], v163 offset:54272
	ds_read_b128 v[204:207], v163 offset:55296
	ds_read_b128 v[208:211], v163 offset:56320
	global_load_lds_dwordx4 v[212:213], off
	s_add_i32 m0, s40, 0x2000
	s_add_u32 s38, s38, 0x80080
	v_lshl_add_u64 v[212:213], v[214:215], 0, s[8:9]
	s_addc_u32 s39, s39, 0
	s_add_i32 s40, s68, s48
	global_load_lds_dwordx4 v[212:213], off
	v_lshl_add_u64 v[212:213], s[38:39], 0, v[138:139]
	s_mov_b32 m0, s40
	s_nop 0
	global_load_lds_dwordx4 v[212:213], off
	v_lshl_add_u64 v[212:213], s[38:39], 0, v[140:141]
	s_add_i32 m0, s40, 0x2000
	s_nop 0
	global_load_lds_dwordx4 v[212:213], off
	v_lshl_add_u64 v[212:213], v[216:217], 0, s[8:9]
	s_mov_b32 m0, s53
	s_nop 0
	global_load_lds_dwordx4 v[212:213], off
	v_lshl_add_u64 v[212:213], v[218:219], 0, s[8:9]
	s_mov_b32 m0, s54
	s_nop 0
	global_load_lds_dwordx4 v[212:213], off
	s_waitcnt vmcnt(8)
	s_waitcnt lgkmcnt(0)
	s_setprio 1
	s_barrier
	v_mfma_f32_16x16x32_bf16 v[94:97], v[130:133], v[180:183], v[94:97]
	v_mfma_f32_16x16x32_bf16 v[90:93], v[150:153], v[180:183], v[90:93]
	v_mfma_f32_16x16x32_bf16 v[86:89], v[130:133], v[188:191], v[86:89]
	v_mfma_f32_16x16x32_bf16 v[82:85], v[150:153], v[188:191], v[82:85]
	v_mfma_f32_16x16x32_bf16 v[78:81], v[130:133], v[196:199], v[78:81]
	v_mfma_f32_16x16x32_bf16 v[74:77], v[150:153], v[196:199], v[74:77]
	v_mfma_f32_16x16x32_bf16 v[70:73], v[130:133], v[204:207], v[70:73]
	v_mfma_f32_16x16x32_bf16 v[66:69], v[150:153], v[204:207], v[66:69]
	v_mfma_f32_16x16x32_bf16 v[94:97], v[134:137], v[184:187], v[94:97]
	v_mfma_f32_16x16x32_bf16 v[90:93], v[154:157], v[184:187], v[90:93]
	v_mfma_f32_16x16x32_bf16 v[86:89], v[134:137], v[192:195], v[86:89]
	v_mfma_f32_16x16x32_bf16 v[82:85], v[154:157], v[192:195], v[82:85]
	v_mfma_f32_16x16x32_bf16 v[78:81], v[134:137], v[200:203], v[78:81]
	v_mfma_f32_16x16x32_bf16 v[74:77], v[154:157], v[200:203], v[74:77]
	v_mfma_f32_16x16x32_bf16 v[70:73], v[134:137], v[208:211], v[70:73]
	v_mfma_f32_16x16x32_bf16 v[66:69], v[154:157], v[208:211], v[66:69]
	s_setprio 0
	s_setprio 1
	v_mfma_f32_16x16x32_bf16 v[30:33], v[164:167], v[180:183], v[30:33]
	v_mfma_f32_16x16x32_bf16 v[26:29], v[172:175], v[180:183], v[26:29]
	v_mfma_f32_16x16x32_bf16 v[14:17], v[164:167], v[188:191], v[14:17]
	v_mfma_f32_16x16x32_bf16 v[2:5], v[172:175], v[188:191], v[2:5]
	v_mfma_f32_16x16x32_bf16 v[22:25], v[164:167], v[196:199], v[22:25]
	v_mfma_f32_16x16x32_bf16 v[18:21], v[172:175], v[196:199], v[18:21]
	v_mfma_f32_16x16x32_bf16 v[10:13], v[164:167], v[204:207], v[10:13]
	v_mfma_f32_16x16x32_bf16 v[6:9], v[172:175], v[204:207], v[6:9]
	v_mfma_f32_16x16x32_bf16 v[30:33], v[168:171], v[184:187], v[30:33]
	v_mfma_f32_16x16x32_bf16 v[26:29], v[176:179], v[184:187], v[26:29]
	v_mfma_f32_16x16x32_bf16 v[14:17], v[168:171], v[192:195], v[14:17]
	v_mfma_f32_16x16x32_bf16 v[2:5], v[176:179], v[192:195], v[2:5]
	v_mfma_f32_16x16x32_bf16 v[22:25], v[168:171], v[200:203], v[22:25]
	v_mfma_f32_16x16x32_bf16 v[18:21], v[176:179], v[200:203], v[18:21]
	v_mfma_f32_16x16x32_bf16 v[10:13], v[168:171], v[208:211], v[10:13]
	v_mfma_f32_16x16x32_bf16 v[6:9], v[176:179], v[208:211], v[6:9]
	s_setprio 0
	s_barrier
	s_add_i32 s66, s66, 2
	s_add_u32 s36, s36, 0x100
	s_addc_u32 s37, s37, 0
	s_add_u32 s64, s64, 0x100
	s_addc_u32 s65, s65, 0
	s_cmp_gt_u32 s66, 29
	s_cbranch_scc0 .LBB0_305
	s_and_b64 vcc, exec, s[10:11]
	s_cbranch_vccz .LBB0_308
	s_barrier

; #define PG8_STAGE(bufoff, gbase, VO) do { _Pragma("unroll") for (int _i = 0; _i < 2; ++_i) \
;         __builtin_amdgcn_global_load_lds((const unsigned*)((const char*)(gbase) + VO[_i]), (LAS unsigned*)(lds + (bufoff) + ldsw + _i * 8192), 16, 0, 0); } while (0)
; #define PG8_LDA(dst, b, h) do { _Pragma("unroll") for (int m = 0; m < 4; ++m) _Pragma("unroll") for (int k = 0; k < 2; ++k) dst[m][k] = *(const LAS bf16x8*)(lds + PG8_SA(b, h) + aoff + m * 2048 + k * 1024); } while (0)
; #define PG8_LDB(dst, b, h) do { _Pragma("unroll") for (int n = 0; n < 2; ++n) _Pragma("unroll") for (int k = 0; k < 2; ++k) dst[n][k] = *(const LAS bf16x8*)(lds + PG8_SB(b, h) + boff + n * 2048 + k * 1024); } while (0)
; #define PG8_MMA(ai, bj, At, Bt) do { __builtin_amdgcn_s_setprio(1); _Pragma("unroll") for (int m = 0; m < 4; ++m) _Pragma("unroll") for (int n = 0; n < 2; ++n) _Pragma("unroll") for (int k = 0; k < 2; ++k) \
;         acc[ai][bj][m][n] = __builtin_amdgcn_mfma_f32_16x16x32_bf16(Bt[n][k], At[m][k], acc[ai][bj][m][n], 0, 0, 0); __builtin_amdgcn_s_setprio(0); } while (0)
; #define PG8_WAIT_V(n) asm volatile("s_waitcnt vmcnt(" #n ")" ::: "memory")
; #define PG8_BAR __builtin_amdgcn_s_barrier()
; template <int NSEG, class Epi, bool ALIGN_EPI = PG8_ALIGN, bool SP2 = PG8_SP2>
; DI void gemm_phase(LAS unsigned char* lds, const Gemm g, const StaticOrder& S, const Epi& E) {
;     ...
;             const char* a1 = cA + (size_t)(t + 1) * kstep;
;             const char* a2 = last ? nA : cA + (size_t)(t + 2) * kstep; const char* b2 = last ? nB : cB + (size_t)(t + 2) * kstep;
;             const char* a3 = a2 + kstep; const char* b3 = b2 + kstep;
;             unsigned v2[2]; v2[0] = (NSEG > 1 && last) ? voffN[0] : voffC[0]; v2[1] = (NSEG > 1 && last) ? voffN[1] : voffC[1];
;             const size_t h2 = (NSEG > 1 && last) ? hstepN : hstepC;
;             if constexpr (SP2) {
;             PG8_LDB(B0, 0, 0); PG8_LDB(B1, 0, 1); PG8_SCHED; PG8_LDA(At, 0, 0); PG8_STAGE(PG8_SA(1, 1), a1 + hstepC, voffC);
;             PG8_WAIT_V(8); PG8_WAIT_L(0); PG8_BAR; PG8_MMA(0, 0, At, B0); PG8_MMA(0, 1, At, B1); PG8_BAR; PG8_SCHED;
;             PG8_LDA(At, 0, 1); PG8_STAGE(PG8_SB(0, 0), b2, v2); PG8_STAGE(PG8_SB(0, 1), b2 + h2, v2); PG8_STAGE(PG8_SA(0, 0), a2, v2);
;             PG8_WAIT_V(8); PG8_WAIT_L(0); PG8_BAR; PG8_MMA(1, 0, At, B0); PG8_MMA(1, 1, At, B1); PG8_BAR; PG8_SCHED;
.LBB0_427:
	ds_read_b128 v[148:151], v145
	ds_read_b128 v[152:155], v145 offset:1024
	ds_read_b128 v[156:159], v145 offset:2048
	ds_read_b128 v[160:163], v145 offset:3072
	ds_read_b128 v[164:167], v146
	ds_read_b128 v[168:171], v146 offset:1024
	ds_read_b128 v[172:175], v146 offset:2048
	ds_read_b128 v[176:179], v146 offset:3072
	s_add_i32 m0, s23, 0xc000
	ds_read_b128 v[180:183], v147
	ds_read_b128 v[184:187], v147 offset:1024
	ds_read_b128 v[188:191], v147 offset:2048
	ds_read_b128 v[192:195], v147 offset:3072
	ds_read_b128 v[196:199], v147 offset:4096
	ds_read_b128 v[200:203], v147 offset:5120
	ds_read_b128 v[204:207], v147 offset:6144
	ds_read_b128 v[208:211], v147 offset:7168
	global_load_lds_dwordx4 v134, s[36:37]
	s_add_i32 m0, s23, 0xe000
	s_nop 0
	global_load_lds_dwordx4 v136, s[36:37]
	s_waitcnt vmcnt(8)
	s_waitcnt lgkmcnt(0)
	s_setprio 1
	s_barrier
	v_mfma_f32_16x16x32_bf16 v[126:129], v[148:151], v[180:183], v[126:129]
	v_mfma_f32_16x16x32_bf16 v[122:125], v[156:159], v[180:183], v[122:125]
	s_add_u32 s38, s36, 0xfff80080
	s_addc_u32 s39, s37, -1
	v_mfma_f32_16x16x32_bf16 v[118:121], v[148:151], v[188:191], v[118:121]
	v_mfma_f32_16x16x32_bf16 v[114:117], v[156:159], v[188:191], v[114:117]
	s_cmp_eq_u32 s61, 28
	s_cselect_b32 s41, s5, s39
	v_mfma_f32_16x16x32_bf16 v[102:105], v[148:151], v[196:199], v[102:105]
	v_mfma_f32_16x16x32_bf16 v[98:101], v[156:159], v[196:199], v[98:101]
	s_cselect_b32 s40, s4, s38
	s_cselect_b32 s39, s35, s27
	v_mfma_f32_16x16x32_bf16 v[86:89], v[148:151], v[204:207], v[86:89]
	v_mfma_f32_16x16x32_bf16 v[82:85], v[156:159], v[204:207], v[82:85]
	s_cselect_b32 s38, s34, s25
	v_mfma_f32_16x16x32_bf16 v[126:129], v[152:155], v[184:187], v[126:129]
	v_mfma_f32_16x16x32_bf16 v[122:125], v[160:163], v[184:187], v[122:125]
	v_mfma_f32_16x16x32_bf16 v[118:121], v[152:155], v[192:195], v[118:121]
	v_mfma_f32_16x16x32_bf16 v[114:117], v[160:163], v[192:195], v[114:117]
	v_mfma_f32_16x16x32_bf16 v[102:105], v[152:155], v[200:203], v[102:105]
	v_mfma_f32_16x16x32_bf16 v[98:101], v[160:163], v[200:203], v[98:101]
	v_mfma_f32_16x16x32_bf16 v[86:89], v[152:155], v[208:211], v[86:89]
	v_mfma_f32_16x16x32_bf16 v[82:85], v[160:163], v[208:211], v[82:85]
	s_setprio 0
	s_setprio 1
	v_mfma_f32_16x16x32_bf16 v[110:113], v[164:167], v[180:183], v[110:113]
	v_mfma_f32_16x16x32_bf16 v[106:109], v[172:175], v[180:183], v[106:109]
	v_mfma_f32_16x16x32_bf16 v[94:97], v[164:167], v[188:191], v[94:97]
	v_mfma_f32_16x16x32_bf16 v[90:93], v[172:175], v[188:191], v[90:93]
	v_mfma_f32_16x16x32_bf16 v[78:81], v[164:167], v[196:199], v[78:81]
	v_mfma_f32_16x16x32_bf16 v[74:77], v[172:175], v[196:199], v[74:77]
	v_mfma_f32_16x16x32_bf16 v[70:73], v[164:167], v[204:207], v[70:73]
	v_mfma_f32_16x16x32_bf16 v[66:69], v[172:175], v[204:207], v[66:69]
	v_mfma_f32_16x16x32_bf16 v[110:113], v[168:171], v[184:187], v[110:113]
	v_mfma_f32_16x16x32_bf16 v[106:109], v[176:179], v[184:187], v[106:109]
	v_mfma_f32_16x16x32_bf16 v[94:97], v[168:171], v[192:195], v[94:97]
	v_mfma_f32_16x16x32_bf16 v[90:93], v[176:179], v[192:195], v[90:93]
	v_mfma_f32_16x16x32_bf16 v[78:81], v[168:171], v[200:203], v[78:81]
	v_mfma_f32_16x16x32_bf16 v[74:77], v[176:179], v[200:203], v[74:77]
	v_mfma_f32_16x16x32_bf16 v[70:73], v[168:171], v[208:211], v[70:73]
	v_mfma_f32_16x16x32_bf16 v[66:69], v[176:179], v[208:211], v[66:69]
	s_setprio 0
	s_barrier
	s_add_i32 s62, s55, s47
	v_lshl_add_u64 v[212:213], s[38:39], 0, v[130:131]
	s_mov_b32 m0, s62
	ds_read_b128 v[180:183], v147 offset:16384
	ds_read_b128 v[184:187], v147 offset:17408
	ds_read_b128 v[188:191], v147 offset:18432
	ds_read_b128 v[192:195], v147 offset:19456
	ds_read_b128 v[196:199], v147 offset:20480
	ds_read_b128 v[200:203], v147 offset:21504
	ds_read_b128 v[204:207], v147 offset:22528
	ds_read_b128 v[208:211], v147 offset:23552
	global_load_lds_dwordx4 v[212:213], off
	s_add_i32 m0, s62, 0x2000
	s_add_u32 s62, s38, 0x80000
	v_lshl_add_u64 v[214:215], s[38:39], 0, v[132:133]
	s_addc_u32 s63, s39, 0
	s_add_i32 s64, s56, s47
	global_load_lds_dwordx4 v[214:215], off
	v_lshl_add_u64 v[216:217], s[62:63], 0, v[130:131]
	s_mov_b32 m0, s64
	v_lshl_add_u64 v[218:219], s[40:41], 0, v[132:133]
	global_load_lds_dwordx4 v[216:217], off
	v_lshl_add_u64 v[216:217], s[62:63], 0, v[132:133]
	s_add_i32 m0, s64, 0x2000
	s_nop 0
	global_load_lds_dwordx4 v[216:217], off
	v_lshl_add_u64 v[216:217], s[40:41], 0, v[130:131]
	s_mov_b32 m0, s23
	s_nop 0
	global_load_lds_dwordx4 v[216:217], off
	s_mov_b32 m0, s48
	s_nop 0
	global_load_lds_dwordx4 v[218:219], off
	s_waitcnt vmcnt(8)
	s_waitcnt lgkmcnt(0)
	s_setprio 1
	s_barrier
; #define PG8_STAGE(bufoff, gbase, VO) do { _Pragma("unroll") for (int _i = 0; _i < 2; ++_i) \
;         __builtin_amdgcn_global_load_lds((const unsigned*)((const char*)(gbase) + VO[_i]), (LAS unsigned*)(lds + (bufoff) + ldsw + _i * 8192), 16, 0, 0); } while (0)
; #define PG8_LDA(dst, b, h) do { _Pragma("unroll") for (int m = 0; m < 4; ++m) _Pragma("unroll") for (int k = 0; k < 2; ++k) dst[m][k] = *(const LAS bf16x8*)(lds + PG8_SA(b, h) + aoff + m * 2048 + k * 1024); } while (0)
; #define PG8_LDB(dst, b, h) do { _Pragma("unroll") for (int n = 0; n < 2; ++n) _Pragma("unroll") for (int k = 0; k < 2; ++k) dst[n][k] = *(const LAS bf16x8*)(lds + PG8_SB(b, h) + boff + n * 2048 + k * 1024); } while (0)
; #define PG8_MMA(ai, bj, At, Bt) do { __builtin_amdgcn_s_setprio(1); _Pragma("unroll") for (int m = 0; m < 4; ++m) _Pragma("unroll") for (int n = 0; n < 2; ++n) _Pragma("unroll") for (int k = 0; k < 2; ++k) \
;         acc[ai][bj][m][n] = __builtin_amdgcn_mfma_f32_16x16x32_bf16(Bt[n][k], At[m][k], acc[ai][bj][m][n], 0, 0, 0); __builtin_amdgcn_s_setprio(0); } while (0)
; #define PG8_WAIT_V(n) asm volatile("s_waitcnt vmcnt(" #n ")" ::: "memory")
; #define PG8_WAIT_L(n) asm volatile("s_waitcnt lgkmcnt(" #n ")" ::: "memory")
; #define PG8_BAR __builtin_amdgcn_s_barrier()
; #define PG8_SCHED __builtin_amdgcn_sched_barrier(0)
; template <int NSEG, class Epi, bool ALIGN_EPI = PG8_ALIGN, bool SP2 = PG8_SP2>
; DI void gemm_phase(LAS unsigned char* lds, const Gemm g, const StaticOrder& S, const Epi& E) {
;     ...
;             PG8_WAIT_V(8); PG8_WAIT_L(0); PG8_BAR; PG8_MMA(1, 0, At, B0); PG8_MMA(1, 1, At, B1); PG8_BAR; PG8_SCHED;
;             PG8_LDB(B0, 1, 0); PG8_LDB(B1, 1, 1); PG8_SCHED; PG8_LDA(At, 1, 0); PG8_STAGE(PG8_SA(0, 1), a2 + h2, v2);
;             PG8_WAIT_V(8); PG8_WAIT_L(0); PG8_BAR; PG8_MMA(0, 0, At, B0); PG8_MMA(0, 1, At, B1); PG8_BAR; PG8_SCHED;
	v_mfma_f32_16x16x32_bf16 v[54:57], v[148:151], v[180:183], v[54:57]
	v_mfma_f32_16x16x32_bf16 v[46:49], v[156:159], v[180:183], v[46:49]
	s_add_i32 s62, 0, 0x18000
	s_add_i32 s63, 0, 0x1c000
	v_mfma_f32_16x16x32_bf16 v[38:41], v[148:151], v[188:191], v[38:41]
	v_mfma_f32_16x16x32_bf16 v[34:37], v[156:159], v[188:191], v[34:37]
	s_add_u32 s40, s40, 0x80000
	s_addc_u32 s41, s41, 0
	v_mfma_f32_16x16x32_bf16 v[22:25], v[148:151], v[196:199], v[22:25]
	v_mfma_f32_16x16x32_bf16 v[18:21], v[156:159], v[196:199], v[18:21]
	v_mfma_f32_16x16x32_bf16 v[6:9], v[148:151], v[204:207], v[6:9]
	v_mfma_f32_16x16x32_bf16 v[2:5], v[156:159], v[204:207], v[2:5]
	v_mfma_f32_16x16x32_bf16 v[54:57], v[152:155], v[184:187], v[54:57]
	v_mfma_f32_16x16x32_bf16 v[46:49], v[160:163], v[184:187], v[46:49]
	v_mfma_f32_16x16x32_bf16 v[38:41], v[152:155], v[192:195], v[38:41]
	v_mfma_f32_16x16x32_bf16 v[34:37], v[160:163], v[192:195], v[34:37]
	v_mfma_f32_16x16x32_bf16 v[22:25], v[152:155], v[200:203], v[22:25]
	v_mfma_f32_16x16x32_bf16 v[18:21], v[160:163], v[200:203], v[18:21]
	v_mfma_f32_16x16x32_bf16 v[6:9], v[152:155], v[208:211], v[6:9]
	v_mfma_f32_16x16x32_bf16 v[2:5], v[160:163], v[208:211], v[2:5]
	s_setprio 0
	s_setprio 1
	v_mfma_f32_16x16x32_bf16 v[30:33], v[164:167], v[180:183], v[30:33]
	v_mfma_f32_16x16x32_bf16 v[26:29], v[172:175], v[180:183], v[26:29]
	v_mfma_f32_16x16x32_bf16 v[14:17], v[164:167], v[188:191], v[14:17]
	v_mfma_f32_16x16x32_bf16 v[10:13], v[172:175], v[188:191], v[10:13]
	v_mfma_f32_16x16x32_bf16 v[58:61], v[164:167], v[196:199], v[58:61]
	v_mfma_f32_16x16x32_bf16 v[62:65], v[172:175], v[196:199], v[62:65]
	v_mfma_f32_16x16x32_bf16 v[42:45], v[164:167], v[204:207], v[42:45]
	v_mfma_f32_16x16x32_bf16 v[50:53], v[172:175], v[204:207], v[50:53]
	v_mfma_f32_16x16x32_bf16 v[30:33], v[168:171], v[184:187], v[30:33]
	v_mfma_f32_16x16x32_bf16 v[26:29], v[176:179], v[184:187], v[26:29]
	v_mfma_f32_16x16x32_bf16 v[14:17], v[168:171], v[192:195], v[14:17]
	v_mfma_f32_16x16x32_bf16 v[10:13], v[176:179], v[192:195], v[10:13]
	v_mfma_f32_16x16x32_bf16 v[58:61], v[168:171], v[200:203], v[58:61]
	v_mfma_f32_16x16x32_bf16 v[62:65], v[176:179], v[200:203], v[62:65]
	v_mfma_f32_16x16x32_bf16 v[42:45], v[168:171], v[208:211], v[42:45]
	v_mfma_f32_16x16x32_bf16 v[50:53], v[176:179], v[208:211], v[50:53]
	s_setprio 0
	s_barrier
	v_add_u32_e32 v160, s62, v143
	v_add_u32_e32 v176, s63, v143
	ds_read_b128 v[148:151], v160
	ds_read_b128 v[152:155], v160 offset:1024
	ds_read_b128 v[156:159], v160 offset:2048
	ds_read_b128 v[160:163], v160 offset:3072
	ds_read_b128 v[164:167], v176
	ds_read_b128 v[168:171], v176 offset:1024
	ds_read_b128 v[172:175], v176 offset:2048
	ds_read_b128 v[176:179], v176 offset:3072
	s_mov_b32 m0, s49
	ds_read_b128 v[180:183], v147 offset:32768
	ds_read_b128 v[184:187], v147 offset:33792
	ds_read_b128 v[188:191], v147 offset:34816
	ds_read_b128 v[192:195], v147 offset:35840
	ds_read_b128 v[196:199], v147 offset:36864
	ds_read_b128 v[200:203], v147 offset:37888
	ds_read_b128 v[204:207], v147 offset:38912
	ds_read_b128 v[208:211], v147 offset:39936
	global_load_lds_dwordx4 v130, s[40:41]
	s_mov_b32 m0, s50
	s_nop 0
	global_load_lds_dwordx4 v132, s[40:41]
	s_waitcnt vmcnt(8)
	s_waitcnt lgkmcnt(0)
	s_setprio 1
	s_barrier
	v_mfma_f32_16x16x32_bf16 v[126:129], v[148:151], v[180:183], v[126:129]
	v_mfma_f32_16x16x32_bf16 v[122:125], v[156:159], v[180:183], v[122:125]
	v_mfma_f32_16x16x32_bf16 v[118:121], v[148:151], v[188:191], v[118:121]
	v_mfma_f32_16x16x32_bf16 v[114:117], v[156:159], v[188:191], v[114:117]
	v_mfma_f32_16x16x32_bf16 v[102:105], v[148:151], v[196:199], v[102:105]
	v_mfma_f32_16x16x32_bf16 v[98:101], v[156:159], v[196:199], v[98:101]
	v_mfma_f32_16x16x32_bf16 v[86:89], v[148:151], v[204:207], v[86:89]
	v_mfma_f32_16x16x32_bf16 v[82:85], v[156:159], v[204:207], v[82:85]
	v_mfma_f32_16x16x32_bf16 v[126:129], v[152:155], v[184:187], v[126:129]
	v_mfma_f32_16x16x32_bf16 v[122:125], v[160:163], v[184:187], v[122:125]
	v_mfma_f32_16x16x32_bf16 v[118:121], v[152:155], v[192:195], v[118:121]
	v_mfma_f32_16x16x32_bf16 v[114:117], v[160:163], v[192:195], v[114:117]
	v_mfma_f32_16x16x32_bf16 v[102:105], v[152:155], v[200:203], v[102:105]
	v_mfma_f32_16x16x32_bf16 v[98:101], v[160:163], v[200:203], v[98:101]
	v_mfma_f32_16x16x32_bf16 v[86:89], v[152:155], v[208:211], v[86:89]
	v_mfma_f32_16x16x32_bf16 v[82:85], v[160:163], v[208:211], v[82:85]
	s_setprio 0
	s_setprio 1
	v_mfma_f32_16x16x32_bf16 v[110:113], v[164:167], v[180:183], v[110:113]
	v_mfma_f32_16x16x32_bf16 v[106:109], v[172:175], v[180:183], v[106:109]
	v_mfma_f32_16x16x32_bf16 v[94:97], v[164:167], v[188:191], v[94:97]
	v_mfma_f32_16x16x32_bf16 v[90:93], v[172:175], v[188:191], v[90:93]
	v_mfma_f32_16x16x32_bf16 v[78:81], v[164:167], v[196:199], v[78:81]
	v_mfma_f32_16x16x32_bf16 v[74:77], v[172:175], v[196:199], v[74:77]
	v_mfma_f32_16x16x32_bf16 v[70:73], v[164:167], v[204:207], v[70:73]
	v_mfma_f32_16x16x32_bf16 v[66:69], v[172:175], v[204:207], v[66:69]
	v_mfma_f32_16x16x32_bf16 v[110:113], v[168:171], v[184:187], v[110:113]
	v_mfma_f32_16x16x32_bf16 v[106:109], v[176:179], v[184:187], v[106:109]
	v_mfma_f32_16x16x32_bf16 v[94:97], v[168:171], v[192:195], v[94:97]
	v_mfma_f32_16x16x32_bf16 v[90:93], v[176:179], v[192:195], v[90:93]
	v_mfma_f32_16x16x32_bf16 v[78:81], v[168:171], v[200:203], v[78:81]
	v_mfma_f32_16x16x32_bf16 v[74:77], v[176:179], v[200:203], v[74:77]
	v_mfma_f32_16x16x32_bf16 v[70:73], v[168:171], v[208:211], v[70:73]
	v_mfma_f32_16x16x32_bf16 v[66:69], v[176:179], v[208:211], v[66:69]
	s_setprio 0
	s_barrier
; #define PG8_STAGE(bufoff, gbase, VO) do { _Pragma("unroll") for (int _i = 0; _i < 2; ++_i) \
;         __builtin_amdgcn_global_load_lds((const unsigned*)((const char*)(gbase) + VO[_i]), (LAS unsigned*)(lds + (bufoff) + ldsw + _i * 8192), 16, 0, 0); } while (0)
; #define PG8_LDA(dst, b, h) do { _Pragma("unroll") for (int m = 0; m < 4; ++m) _Pragma("unroll") for (int k = 0; k < 2; ++k) dst[m][k] = *(const LAS bf16x8*)(lds + PG8_SA(b, h) + aoff + m * 2048 + k * 1024); } while (0)
; #define PG8_MMA(ai, bj, At, Bt) do { __builtin_amdgcn_s_setprio(1); _Pragma("unroll") for (int m = 0; m < 4; ++m) _Pragma("unroll") for (int n = 0; n < 2; ++n) _Pragma("unroll") for (int k = 0; k < 2; ++k) \
;         acc[ai][bj][m][n] = __builtin_amdgcn_mfma_f32_16x16x32_bf16(Bt[n][k], At[m][k], acc[ai][bj][m][n], 0, 0, 0); __builtin_amdgcn_s_setprio(0); } while (0)
; #define PG8_WAIT_V(n) asm volatile("s_waitcnt vmcnt(" #n ")" ::: "memory")
; #define PG8_WAIT_L(n) asm volatile("s_waitcnt lgkmcnt(" #n ")" ::: "memory")
; #define PG8_BAR __builtin_amdgcn_s_barrier()
; #define PG8_SCHED __builtin_amdgcn_sched_barrier(0)
; template <int NSEG, class Epi, bool ALIGN_EPI = PG8_ALIGN, bool SP2 = PG8_SP2>
; DI void gemm_phase(LAS unsigned char* lds, const Gemm g, const StaticOrder& S, const Epi& E) {
;     ...
;             PG8_LDA(At, 1, 1); PG8_STAGE(PG8_SB(1, 0), b3, v2); PG8_STAGE(PG8_SB(1, 1), b3 + h2, v2); PG8_STAGE(PG8_SA(1, 0), a3, v2);
;             PG8_WAIT_V(8); PG8_WAIT_L(0); PG8_BAR; PG8_MMA(1, 0, At, B0); PG8_MMA(1, 1, At, B1); PG8_BAR; PG8_SCHED;
;     ...
;         if constexpr (ALIGN_EPI) { if (wr == 0) PG8_BAR; }
	s_add_i32 s40, s62, s47
	v_lshl_add_u64 v[212:213], v[212:213], 0, s[12:13]
	s_mov_b32 m0, s40
	ds_read_b128 v[180:183], v147 offset:49152
	ds_read_b128 v[184:187], v147 offset:50176
	ds_read_b128 v[188:191], v147 offset:51200
	ds_read_b128 v[192:195], v147 offset:52224
	ds_read_b128 v[196:199], v147 offset:53248
	ds_read_b128 v[200:203], v147 offset:54272
	ds_read_b128 v[204:207], v147 offset:55296
	ds_read_b128 v[208:211], v147 offset:56320
	global_load_lds_dwordx4 v[212:213], off
	s_add_i32 m0, s40, 0x2000
	s_add_u32 s38, s38, 0x80080
	v_lshl_add_u64 v[212:213], v[214:215], 0, s[12:13]
	s_addc_u32 s39, s39, 0
	s_add_i32 s40, s63, s47
	global_load_lds_dwordx4 v[212:213], off
	v_lshl_add_u64 v[212:213], s[38:39], 0, v[130:131]
	s_mov_b32 m0, s40
	s_nop 0
	global_load_lds_dwordx4 v[212:213], off
	v_lshl_add_u64 v[212:213], s[38:39], 0, v[132:133]
	s_add_i32 m0, s40, 0x2000
	s_nop 0
	global_load_lds_dwordx4 v[212:213], off
	v_lshl_add_u64 v[212:213], v[216:217], 0, s[12:13]
	s_mov_b32 m0, s53
	s_nop 0
	global_load_lds_dwordx4 v[212:213], off
	v_lshl_add_u64 v[212:213], v[218:219], 0, s[12:13]
	s_mov_b32 m0, s54
	s_nop 0
	global_load_lds_dwordx4 v[212:213], off
	s_waitcnt vmcnt(8)
	s_waitcnt lgkmcnt(0)
	s_setprio 1
	s_barrier
	v_mfma_f32_16x16x32_bf16 v[54:57], v[148:151], v[180:183], v[54:57]
	v_mfma_f32_16x16x32_bf16 v[46:49], v[156:159], v[180:183], v[46:49]
	v_mfma_f32_16x16x32_bf16 v[38:41], v[148:151], v[188:191], v[38:41]
	v_mfma_f32_16x16x32_bf16 v[34:37], v[156:159], v[188:191], v[34:37]
	v_mfma_f32_16x16x32_bf16 v[22:25], v[148:151], v[196:199], v[22:25]
	v_mfma_f32_16x16x32_bf16 v[18:21], v[156:159], v[196:199], v[18:21]
	v_mfma_f32_16x16x32_bf16 v[6:9], v[148:151], v[204:207], v[6:9]
	v_mfma_f32_16x16x32_bf16 v[2:5], v[156:159], v[204:207], v[2:5]
	v_mfma_f32_16x16x32_bf16 v[54:57], v[152:155], v[184:187], v[54:57]
	v_mfma_f32_16x16x32_bf16 v[46:49], v[160:163], v[184:187], v[46:49]
	v_mfma_f32_16x16x32_bf16 v[38:41], v[152:155], v[192:195], v[38:41]
	v_mfma_f32_16x16x32_bf16 v[34:37], v[160:163], v[192:195], v[34:37]
	v_mfma_f32_16x16x32_bf16 v[22:25], v[152:155], v[200:203], v[22:25]
	v_mfma_f32_16x16x32_bf16 v[18:21], v[160:163], v[200:203], v[18:21]
	v_mfma_f32_16x16x32_bf16 v[6:9], v[152:155], v[208:211], v[6:9]
	v_mfma_f32_16x16x32_bf16 v[2:5], v[160:163], v[208:211], v[2:5]
	s_setprio 0
	s_setprio 1
	v_mfma_f32_16x16x32_bf16 v[30:33], v[164:167], v[180:183], v[30:33]
	v_mfma_f32_16x16x32_bf16 v[26:29], v[172:175], v[180:183], v[26:29]
	v_mfma_f32_16x16x32_bf16 v[14:17], v[164:167], v[188:191], v[14:17]
	v_mfma_f32_16x16x32_bf16 v[10:13], v[172:175], v[188:191], v[10:13]
	v_mfma_f32_16x16x32_bf16 v[58:61], v[164:167], v[196:199], v[58:61]
	v_mfma_f32_16x16x32_bf16 v[62:65], v[172:175], v[196:199], v[62:65]
	v_mfma_f32_16x16x32_bf16 v[42:45], v[164:167], v[204:207], v[42:45]
	v_mfma_f32_16x16x32_bf16 v[50:53], v[172:175], v[204:207], v[50:53]
	v_mfma_f32_16x16x32_bf16 v[30:33], v[168:171], v[184:187], v[30:33]
	v_mfma_f32_16x16x32_bf16 v[26:29], v[176:179], v[184:187], v[26:29]
	v_mfma_f32_16x16x32_bf16 v[14:17], v[168:171], v[192:195], v[14:17]
	v_mfma_f32_16x16x32_bf16 v[10:13], v[176:179], v[192:195], v[10:13]
	v_mfma_f32_16x16x32_bf16 v[58:61], v[168:171], v[200:203], v[58:61]
	v_mfma_f32_16x16x32_bf16 v[62:65], v[176:179], v[200:203], v[62:65]
	v_mfma_f32_16x16x32_bf16 v[42:45], v[168:171], v[208:211], v[42:45]
	v_mfma_f32_16x16x32_bf16 v[50:53], v[176:179], v[208:211], v[50:53]
	s_setprio 0
	s_barrier
	s_add_i32 s61, s61, 2
	s_add_u32 s36, s36, 0x100
	s_addc_u32 s37, s37, 0
	s_add_u32 s25, s25, 0x100
	s_addc_u32 s27, s27, 0
	s_cmp_gt_u32 s61, 29
	s_cbranch_scc0 .LBB0_427
	s_and_b64 vcc, exec, s[14:15]
	s_cbranch_vccz .LBB0_430
	s_barrier

; #define PG8_STAGE(bufoff, gbase, VO) do { _Pragma("unroll") for (int _i = 0; _i < 2; ++_i) \
;         __builtin_amdgcn_global_load_lds((const unsigned*)((const char*)(gbase) + VO[_i]), (LAS unsigned*)(lds + (bufoff) + ldsw + _i * 8192), 16, 0, 0); } while (0)
; #define PG8_LDA(dst, b, h) do { _Pragma("unroll") for (int m = 0; m < 4; ++m) _Pragma("unroll") for (int k = 0; k < 2; ++k) dst[m][k] = *(const LAS bf16x8*)(lds + PG8_SA(b, h) + aoff + m * 2048 + k * 1024); } while (0)
; #define PG8_LDB(dst, b, h) do { _Pragma("unroll") for (int n = 0; n < 2; ++n) _Pragma("unroll") for (int k = 0; k < 2; ++k) dst[n][k] = *(const LAS bf16x8*)(lds + PG8_SB(b, h) + boff + n * 2048 + k * 1024); } while (0)
; #define PG8_MMA(ai, bj, At, Bt) do { __builtin_amdgcn_s_setprio(1); _Pragma("unroll") for (int m = 0; m < 4; ++m) _Pragma("unroll") for (int n = 0; n < 2; ++n) _Pragma("unroll") for (int k = 0; k < 2; ++k) \
;         acc[ai][bj][m][n] = __builtin_amdgcn_mfma_f32_16x16x32_bf16(Bt[n][k], At[m][k], acc[ai][bj][m][n], 0, 0, 0); __builtin_amdgcn_s_setprio(0); } while (0)
; #define PG8_WAIT_V(n) asm volatile("s_waitcnt vmcnt(" #n ")" ::: "memory")
; #define PG8_BAR __builtin_amdgcn_s_barrier()
; template <int NSEG, class Epi, bool ALIGN_EPI = PG8_ALIGN, bool SP2 = PG8_SP2>
; DI void gemm_phase(LAS unsigned char* lds, const Gemm g, const StaticOrder& S, const Epi& E) {
;     ...
;             const char* a1 = cA + (size_t)(t + 1) * kstep;
;             const char* a2 = last ? nA : cA + (size_t)(t + 2) * kstep; const char* b2 = last ? nB : cB + (size_t)(t + 2) * kstep;
;             const char* a3 = a2 + kstep; const char* b3 = b2 + kstep;
;             unsigned v2[2]; v2[0] = (NSEG > 1 && last) ? voffN[0] : voffC[0]; v2[1] = (NSEG > 1 && last) ? voffN[1] : voffC[1];
;             const size_t h2 = (NSEG > 1 && last) ? hstepN : hstepC;
;             if constexpr (SP2) {
;             PG8_LDB(B0, 0, 0); PG8_LDB(B1, 0, 1); PG8_SCHED; PG8_LDA(At, 0, 0); PG8_STAGE(PG8_SA(1, 1), a1 + hstepC, voffC);
;             PG8_WAIT_V(8); PG8_WAIT_L(0); PG8_BAR; PG8_MMA(0, 0, At, B0); PG8_MMA(0, 1, At, B1); PG8_BAR; PG8_SCHED;
;             PG8_LDA(At, 0, 1); PG8_STAGE(PG8_SB(0, 0), b2, v2); PG8_STAGE(PG8_SB(0, 1), b2 + h2, v2); PG8_STAGE(PG8_SA(0, 0), a2, v2);
;             PG8_WAIT_V(8); PG8_WAIT_L(0); PG8_BAR; PG8_MMA(1, 0, At, B0); PG8_MMA(1, 1, At, B1); PG8_BAR; PG8_SCHED;
.LBB0_501:
	ds_read_b128 v[148:151], v145
	ds_read_b128 v[152:155], v145 offset:1024
	ds_read_b128 v[156:159], v145 offset:2048
	ds_read_b128 v[160:163], v145 offset:3072
	ds_read_b128 v[164:167], v146
	ds_read_b128 v[168:171], v146 offset:1024
	ds_read_b128 v[172:175], v146 offset:2048
	ds_read_b128 v[176:179], v146 offset:3072
	s_add_i32 m0, s15, 0xc000
	ds_read_b128 v[180:183], v147
	ds_read_b128 v[184:187], v147 offset:1024
	ds_read_b128 v[188:191], v147 offset:2048
	ds_read_b128 v[192:195], v147 offset:3072
	ds_read_b128 v[196:199], v147 offset:4096
	ds_read_b128 v[200:203], v147 offset:5120
	ds_read_b128 v[204:207], v147 offset:6144
	ds_read_b128 v[208:211], v147 offset:7168
	global_load_lds_dwordx4 v134, s[22:23]
	s_add_i32 m0, s15, 0xe000
	s_nop 0
	global_load_lds_dwordx4 v136, s[22:23]
	s_waitcnt vmcnt(8)
	s_waitcnt lgkmcnt(0)
	s_setprio 1
	s_barrier
	v_mfma_f32_16x16x32_bf16 v[126:129], v[148:151], v[180:183], v[126:129]
	v_mfma_f32_16x16x32_bf16 v[122:125], v[156:159], v[180:183], v[122:125]
	s_add_u32 s24, s22, 0xfff80080
	s_addc_u32 s25, s23, -1
	v_mfma_f32_16x16x32_bf16 v[118:121], v[148:151], v[188:191], v[118:121]
	v_mfma_f32_16x16x32_bf16 v[114:117], v[156:159], v[188:191], v[114:117]
	s_cmp_eq_u32 s52, 28
	s_cselect_b32 s27, s5, s25
	v_mfma_f32_16x16x32_bf16 v[102:105], v[148:151], v[196:199], v[102:105]
	v_mfma_f32_16x16x32_bf16 v[98:101], v[156:159], v[196:199], v[98:101]
	s_cselect_b32 s26, s4, s24
	s_cselect_b32 s25, s21, s19
	v_mfma_f32_16x16x32_bf16 v[86:89], v[148:151], v[204:207], v[86:89]
	v_mfma_f32_16x16x32_bf16 v[82:85], v[156:159], v[204:207], v[82:85]
	s_cselect_b32 s24, s20, s17
	v_mfma_f32_16x16x32_bf16 v[126:129], v[152:155], v[184:187], v[126:129]
	v_mfma_f32_16x16x32_bf16 v[122:125], v[160:163], v[184:187], v[122:125]
	v_mfma_f32_16x16x32_bf16 v[118:121], v[152:155], v[192:195], v[118:121]
	v_mfma_f32_16x16x32_bf16 v[114:117], v[160:163], v[192:195], v[114:117]
	v_mfma_f32_16x16x32_bf16 v[102:105], v[152:155], v[200:203], v[102:105]
	v_mfma_f32_16x16x32_bf16 v[98:101], v[160:163], v[200:203], v[98:101]
	v_mfma_f32_16x16x32_bf16 v[86:89], v[152:155], v[208:211], v[86:89]
	v_mfma_f32_16x16x32_bf16 v[82:85], v[160:163], v[208:211], v[82:85]
	s_setprio 0
	s_setprio 1
	v_mfma_f32_16x16x32_bf16 v[110:113], v[164:167], v[180:183], v[110:113]
	v_mfma_f32_16x16x32_bf16 v[106:109], v[172:175], v[180:183], v[106:109]
	v_mfma_f32_16x16x32_bf16 v[94:97], v[164:167], v[188:191], v[94:97]
	v_mfma_f32_16x16x32_bf16 v[90:93], v[172:175], v[188:191], v[90:93]
	v_mfma_f32_16x16x32_bf16 v[78:81], v[164:167], v[196:199], v[78:81]
	v_mfma_f32_16x16x32_bf16 v[74:77], v[172:175], v[196:199], v[74:77]
	v_mfma_f32_16x16x32_bf16 v[70:73], v[164:167], v[204:207], v[70:73]
	v_mfma_f32_16x16x32_bf16 v[58:61], v[172:175], v[204:207], v[58:61]
	v_mfma_f32_16x16x32_bf16 v[110:113], v[168:171], v[184:187], v[110:113]
	v_mfma_f32_16x16x32_bf16 v[106:109], v[176:179], v[184:187], v[106:109]
	v_mfma_f32_16x16x32_bf16 v[94:97], v[168:171], v[192:195], v[94:97]
	v_mfma_f32_16x16x32_bf16 v[90:93], v[176:179], v[192:195], v[90:93]
	v_mfma_f32_16x16x32_bf16 v[78:81], v[168:171], v[200:203], v[78:81]
	v_mfma_f32_16x16x32_bf16 v[74:77], v[176:179], v[200:203], v[74:77]
	v_mfma_f32_16x16x32_bf16 v[70:73], v[168:171], v[208:211], v[70:73]
	v_mfma_f32_16x16x32_bf16 v[58:61], v[176:179], v[208:211], v[58:61]
	s_setprio 0
	s_barrier
	s_add_i32 s53, s48, s38
	v_lshl_add_u64 v[212:213], s[24:25], 0, v[130:131]
	s_mov_b32 m0, s53
	ds_read_b128 v[180:183], v147 offset:16384
	ds_read_b128 v[184:187], v147 offset:17408
	ds_read_b128 v[188:191], v147 offset:18432
	ds_read_b128 v[192:195], v147 offset:19456
	ds_read_b128 v[196:199], v147 offset:20480
	ds_read_b128 v[200:203], v147 offset:21504
	ds_read_b128 v[204:207], v147 offset:22528
	ds_read_b128 v[208:211], v147 offset:23552
	global_load_lds_dwordx4 v[212:213], off
	s_add_i32 m0, s53, 0x2000
	s_add_u32 s54, s24, 0x80000
	v_lshl_add_u64 v[214:215], s[24:25], 0, v[132:133]
	s_addc_u32 s55, s25, 0
	s_add_i32 s53, s49, s38
	global_load_lds_dwordx4 v[214:215], off
	v_lshl_add_u64 v[216:217], s[54:55], 0, v[130:131]
	s_mov_b32 m0, s53
	v_lshl_add_u64 v[218:219], s[26:27], 0, v[132:133]
	global_load_lds_dwordx4 v[216:217], off
	v_lshl_add_u64 v[216:217], s[54:55], 0, v[132:133]
	s_add_i32 m0, s53, 0x2000
	s_nop 0
	global_load_lds_dwordx4 v[216:217], off
	v_lshl_add_u64 v[216:217], s[26:27], 0, v[130:131]
	s_mov_b32 m0, s15
	s_nop 0
	global_load_lds_dwordx4 v[216:217], off
	s_mov_b32 m0, s41
	s_nop 0
	global_load_lds_dwordx4 v[218:219], off
	s_waitcnt vmcnt(8)
	s_waitcnt lgkmcnt(0)
	s_setprio 1
	s_barrier
; #define PG8_STAGE(bufoff, gbase, VO) do { _Pragma("unroll") for (int _i = 0; _i < 2; ++_i) \
;         __builtin_amdgcn_global_load_lds((const unsigned*)((const char*)(gbase) + VO[_i]), (LAS unsigned*)(lds + (bufoff) + ldsw + _i * 8192), 16, 0, 0); } while (0)
; #define PG8_LDA(dst, b, h) do { _Pragma("unroll") for (int m = 0; m < 4; ++m) _Pragma("unroll") for (int k = 0; k < 2; ++k) dst[m][k] = *(const LAS bf16x8*)(lds + PG8_SA(b, h) + aoff + m * 2048 + k * 1024); } while (0)
; #define PG8_LDB(dst, b, h) do { _Pragma("unroll") for (int n = 0; n < 2; ++n) _Pragma("unroll") for (int k = 0; k < 2; ++k) dst[n][k] = *(const LAS bf16x8*)(lds + PG8_SB(b, h) + boff + n * 2048 + k * 1024); } while (0)
; #define PG8_MMA(ai, bj, At, Bt) do { __builtin_amdgcn_s_setprio(1); _Pragma("unroll") for (int m = 0; m < 4; ++m) _Pragma("unroll") for (int n = 0; n < 2; ++n) _Pragma("unroll") for (int k = 0; k < 2; ++k) \
;         acc[ai][bj][m][n] = __builtin_amdgcn_mfma_f32_16x16x32_bf16(Bt[n][k], At[m][k], acc[ai][bj][m][n], 0, 0, 0); __builtin_amdgcn_s_setprio(0); } while (0)
; #define PG8_WAIT_V(n) asm volatile("s_waitcnt vmcnt(" #n ")" ::: "memory")
; #define PG8_WAIT_L(n) asm volatile("s_waitcnt lgkmcnt(" #n ")" ::: "memory")
; #define PG8_BAR __builtin_amdgcn_s_barrier()
; #define PG8_SCHED __builtin_amdgcn_sched_barrier(0)
; template <int NSEG, class Epi, bool ALIGN_EPI = PG8_ALIGN, bool SP2 = PG8_SP2>
; DI void gemm_phase(LAS unsigned char* lds, const Gemm g, const StaticOrder& S, const Epi& E) {
;     ...
;             PG8_WAIT_V(8); PG8_WAIT_L(0); PG8_BAR; PG8_MMA(1, 0, At, B0); PG8_MMA(1, 1, At, B1); PG8_BAR; PG8_SCHED;
;             PG8_LDB(B0, 1, 0); PG8_LDB(B1, 1, 1); PG8_SCHED; PG8_LDA(At, 1, 0); PG8_STAGE(PG8_SA(0, 1), a2 + h2, v2);
;             PG8_WAIT_V(8); PG8_WAIT_L(0); PG8_BAR; PG8_MMA(0, 0, At, B0); PG8_MMA(0, 1, At, B1); PG8_BAR; PG8_SCHED;
	v_mfma_f32_16x16x32_bf16 v[46:49], v[148:151], v[180:183], v[46:49]
	v_mfma_f32_16x16x32_bf16 v[42:45], v[156:159], v[180:183], v[42:45]
	s_add_i32 s53, 0, 0x18000
	s_add_i32 s54, 0, 0x1c000
	v_mfma_f32_16x16x32_bf16 v[38:41], v[148:151], v[188:191], v[38:41]
	v_mfma_f32_16x16x32_bf16 v[34:37], v[156:159], v[188:191], v[34:37]
	s_add_u32 s26, s26, 0x80000
	s_addc_u32 s27, s27, 0
	v_mfma_f32_16x16x32_bf16 v[22:25], v[148:151], v[196:199], v[22:25]
	v_mfma_f32_16x16x32_bf16 v[18:21], v[156:159], v[196:199], v[18:21]
	v_mfma_f32_16x16x32_bf16 v[6:9], v[148:151], v[204:207], v[6:9]
	v_mfma_f32_16x16x32_bf16 v[2:5], v[156:159], v[204:207], v[2:5]
	v_mfma_f32_16x16x32_bf16 v[46:49], v[152:155], v[184:187], v[46:49]
	v_mfma_f32_16x16x32_bf16 v[42:45], v[160:163], v[184:187], v[42:45]
	v_mfma_f32_16x16x32_bf16 v[38:41], v[152:155], v[192:195], v[38:41]
	v_mfma_f32_16x16x32_bf16 v[34:37], v[160:163], v[192:195], v[34:37]
	v_mfma_f32_16x16x32_bf16 v[22:25], v[152:155], v[200:203], v[22:25]
	v_mfma_f32_16x16x32_bf16 v[18:21], v[160:163], v[200:203], v[18:21]
	v_mfma_f32_16x16x32_bf16 v[6:9], v[152:155], v[208:211], v[6:9]
	v_mfma_f32_16x16x32_bf16 v[2:5], v[160:163], v[208:211], v[2:5]
	s_setprio 0
	s_setprio 1
	v_mfma_f32_16x16x32_bf16 v[30:33], v[164:167], v[180:183], v[30:33]
	v_mfma_f32_16x16x32_bf16 v[26:29], v[172:175], v[180:183], v[26:29]
	v_mfma_f32_16x16x32_bf16 v[14:17], v[164:167], v[188:191], v[14:17]
	v_mfma_f32_16x16x32_bf16 v[10:13], v[172:175], v[188:191], v[10:13]
	v_mfma_f32_16x16x32_bf16 v[62:65], v[164:167], v[196:199], v[62:65]
	v_mfma_f32_16x16x32_bf16 v[66:69], v[172:175], v[196:199], v[66:69]
	v_mfma_f32_16x16x32_bf16 v[50:53], v[164:167], v[204:207], v[50:53]
	v_mfma_f32_16x16x32_bf16 v[54:57], v[172:175], v[204:207], v[54:57]
	v_mfma_f32_16x16x32_bf16 v[30:33], v[168:171], v[184:187], v[30:33]
	v_mfma_f32_16x16x32_bf16 v[26:29], v[176:179], v[184:187], v[26:29]
	v_mfma_f32_16x16x32_bf16 v[14:17], v[168:171], v[192:195], v[14:17]
	v_mfma_f32_16x16x32_bf16 v[10:13], v[176:179], v[192:195], v[10:13]
	v_mfma_f32_16x16x32_bf16 v[62:65], v[168:171], v[200:203], v[62:65]
	v_mfma_f32_16x16x32_bf16 v[66:69], v[176:179], v[200:203], v[66:69]
	v_mfma_f32_16x16x32_bf16 v[50:53], v[168:171], v[208:211], v[50:53]
	v_mfma_f32_16x16x32_bf16 v[54:57], v[176:179], v[208:211], v[54:57]
	s_setprio 0
	s_barrier
	v_add_u32_e32 v160, s53, v143
	v_add_u32_e32 v176, s54, v143
	ds_read_b128 v[148:151], v160
	ds_read_b128 v[152:155], v160 offset:1024
	ds_read_b128 v[156:159], v160 offset:2048
	ds_read_b128 v[160:163], v160 offset:3072
	ds_read_b128 v[164:167], v176
	ds_read_b128 v[168:171], v176 offset:1024
	ds_read_b128 v[172:175], v176 offset:2048
	ds_read_b128 v[176:179], v176 offset:3072
	s_mov_b32 m0, s42
	ds_read_b128 v[180:183], v147 offset:32768
	ds_read_b128 v[184:187], v147 offset:33792
	ds_read_b128 v[188:191], v147 offset:34816
	ds_read_b128 v[192:195], v147 offset:35840
	ds_read_b128 v[196:199], v147 offset:36864
	ds_read_b128 v[200:203], v147 offset:37888
	ds_read_b128 v[204:207], v147 offset:38912
	ds_read_b128 v[208:211], v147 offset:39936
	global_load_lds_dwordx4 v130, s[26:27]
	s_mov_b32 m0, s43
	s_nop 0
	global_load_lds_dwordx4 v132, s[26:27]
	s_waitcnt vmcnt(8)
	s_waitcnt lgkmcnt(0)
	s_setprio 1
	s_barrier
	v_mfma_f32_16x16x32_bf16 v[126:129], v[148:151], v[180:183], v[126:129]
	v_mfma_f32_16x16x32_bf16 v[122:125], v[156:159], v[180:183], v[122:125]
	v_mfma_f32_16x16x32_bf16 v[118:121], v[148:151], v[188:191], v[118:121]
	v_mfma_f32_16x16x32_bf16 v[114:117], v[156:159], v[188:191], v[114:117]
	v_mfma_f32_16x16x32_bf16 v[102:105], v[148:151], v[196:199], v[102:105]
	v_mfma_f32_16x16x32_bf16 v[98:101], v[156:159], v[196:199], v[98:101]
	v_mfma_f32_16x16x32_bf16 v[86:89], v[148:151], v[204:207], v[86:89]
	v_mfma_f32_16x16x32_bf16 v[82:85], v[156:159], v[204:207], v[82:85]
	v_mfma_f32_16x16x32_bf16 v[126:129], v[152:155], v[184:187], v[126:129]
	v_mfma_f32_16x16x32_bf16 v[122:125], v[160:163], v[184:187], v[122:125]
	v_mfma_f32_16x16x32_bf16 v[118:121], v[152:155], v[192:195], v[118:121]
	v_mfma_f32_16x16x32_bf16 v[114:117], v[160:163], v[192:195], v[114:117]
	v_mfma_f32_16x16x32_bf16 v[102:105], v[152:155], v[200:203], v[102:105]
	v_mfma_f32_16x16x32_bf16 v[98:101], v[160:163], v[200:203], v[98:101]
	v_mfma_f32_16x16x32_bf16 v[86:89], v[152:155], v[208:211], v[86:89]
	v_mfma_f32_16x16x32_bf16 v[82:85], v[160:163], v[208:211], v[82:85]
	s_setprio 0
	s_setprio 1
	v_mfma_f32_16x16x32_bf16 v[110:113], v[164:167], v[180:183], v[110:113]
	v_mfma_f32_16x16x32_bf16 v[106:109], v[172:175], v[180:183], v[106:109]
	v_mfma_f32_16x16x32_bf16 v[94:97], v[164:167], v[188:191], v[94:97]
	v_mfma_f32_16x16x32_bf16 v[90:93], v[172:175], v[188:191], v[90:93]
	v_mfma_f32_16x16x32_bf16 v[78:81], v[164:167], v[196:199], v[78:81]
	v_mfma_f32_16x16x32_bf16 v[74:77], v[172:175], v[196:199], v[74:77]
	v_mfma_f32_16x16x32_bf16 v[70:73], v[164:167], v[204:207], v[70:73]
	v_mfma_f32_16x16x32_bf16 v[58:61], v[172:175], v[204:207], v[58:61]
	v_mfma_f32_16x16x32_bf16 v[110:113], v[168:171], v[184:187], v[110:113]
	v_mfma_f32_16x16x32_bf16 v[106:109], v[176:179], v[184:187], v[106:109]
	v_mfma_f32_16x16x32_bf16 v[94:97], v[168:171], v[192:195], v[94:97]
	v_mfma_f32_16x16x32_bf16 v[90:93], v[176:179], v[192:195], v[90:93]
	v_mfma_f32_16x16x32_bf16 v[78:81], v[168:171], v[200:203], v[78:81]
	v_mfma_f32_16x16x32_bf16 v[74:77], v[176:179], v[200:203], v[74:77]
	v_mfma_f32_16x16x32_bf16 v[70:73], v[168:171], v[208:211], v[70:73]
	v_mfma_f32_16x16x32_bf16 v[58:61], v[176:179], v[208:211], v[58:61]
	s_setprio 0
	s_barrier
; #define PG8_STAGE(bufoff, gbase, VO) do { _Pragma("unroll") for (int _i = 0; _i < 2; ++_i) \
;         __builtin_amdgcn_global_load_lds((const unsigned*)((const char*)(gbase) + VO[_i]), (LAS unsigned*)(lds + (bufoff) + ldsw + _i * 8192), 16, 0, 0); } while (0)
; #define PG8_LDA(dst, b, h) do { _Pragma("unroll") for (int m = 0; m < 4; ++m) _Pragma("unroll") for (int k = 0; k < 2; ++k) dst[m][k] = *(const LAS bf16x8*)(lds + PG8_SA(b, h) + aoff + m * 2048 + k * 1024); } while (0)
; #define PG8_MMA(ai, bj, At, Bt) do { __builtin_amdgcn_s_setprio(1); _Pragma("unroll") for (int m = 0; m < 4; ++m) _Pragma("unroll") for (int n = 0; n < 2; ++n) _Pragma("unroll") for (int k = 0; k < 2; ++k) \
;         acc[ai][bj][m][n] = __builtin_amdgcn_mfma_f32_16x16x32_bf16(Bt[n][k], At[m][k], acc[ai][bj][m][n], 0, 0, 0); __builtin_amdgcn_s_setprio(0); } while (0)
; #define PG8_WAIT_V(n) asm volatile("s_waitcnt vmcnt(" #n ")" ::: "memory")
; #define PG8_WAIT_L(n) asm volatile("s_waitcnt lgkmcnt(" #n ")" ::: "memory")
; #define PG8_BAR __builtin_amdgcn_s_barrier()
; #define PG8_SCHED __builtin_amdgcn_sched_barrier(0)
; template <int NSEG, class Epi, bool ALIGN_EPI = PG8_ALIGN, bool SP2 = PG8_SP2>
; DI void gemm_phase(LAS unsigned char* lds, const Gemm g, const StaticOrder& S, const Epi& E) {
;     ...
;             PG8_LDA(At, 1, 1); PG8_STAGE(PG8_SB(1, 0), b3, v2); PG8_STAGE(PG8_SB(1, 1), b3 + h2, v2); PG8_STAGE(PG8_SA(1, 0), a3, v2);
;             PG8_WAIT_V(8); PG8_WAIT_L(0); PG8_BAR; PG8_MMA(1, 0, At, B0); PG8_MMA(1, 1, At, B1); PG8_BAR; PG8_SCHED;
;     ...
;         if constexpr (ALIGN_EPI) { if (wr == 0) PG8_BAR; }
	s_add_i32 s26, s53, s38
	v_lshl_add_u64 v[212:213], v[212:213], 0, s[10:11]
	s_mov_b32 m0, s26
	ds_read_b128 v[180:183], v147 offset:49152
	ds_read_b128 v[184:187], v147 offset:50176
	ds_read_b128 v[188:191], v147 offset:51200
	ds_read_b128 v[192:195], v147 offset:52224
	ds_read_b128 v[196:199], v147 offset:53248
	ds_read_b128 v[200:203], v147 offset:54272
	ds_read_b128 v[204:207], v147 offset:55296
	ds_read_b128 v[208:211], v147 offset:56320
	global_load_lds_dwordx4 v[212:213], off
	s_add_i32 m0, s26, 0x2000
	s_add_u32 s24, s24, 0x80080
	v_lshl_add_u64 v[212:213], v[214:215], 0, s[10:11]
	s_addc_u32 s25, s25, 0
	s_add_i32 s26, s54, s38
	global_load_lds_dwordx4 v[212:213], off
	v_lshl_add_u64 v[212:213], s[24:25], 0, v[130:131]
	s_mov_b32 m0, s26
	s_nop 0
	global_load_lds_dwordx4 v[212:213], off
	v_lshl_add_u64 v[212:213], s[24:25], 0, v[132:133]
	s_add_i32 m0, s26, 0x2000
	s_nop 0
	global_load_lds_dwordx4 v[212:213], off
	v_lshl_add_u64 v[212:213], v[216:217], 0, s[10:11]
	s_mov_b32 m0, s46
	s_nop 0
	global_load_lds_dwordx4 v[212:213], off
	v_lshl_add_u64 v[212:213], v[218:219], 0, s[10:11]
	s_mov_b32 m0, s47
	s_nop 0
	global_load_lds_dwordx4 v[212:213], off
	s_waitcnt vmcnt(8)
	s_waitcnt lgkmcnt(0)
	s_setprio 1
	s_barrier
	v_mfma_f32_16x16x32_bf16 v[46:49], v[148:151], v[180:183], v[46:49]
	v_mfma_f32_16x16x32_bf16 v[42:45], v[156:159], v[180:183], v[42:45]
	v_mfma_f32_16x16x32_bf16 v[38:41], v[148:151], v[188:191], v[38:41]
	v_mfma_f32_16x16x32_bf16 v[34:37], v[156:159], v[188:191], v[34:37]
	v_mfma_f32_16x16x32_bf16 v[22:25], v[148:151], v[196:199], v[22:25]
	v_mfma_f32_16x16x32_bf16 v[18:21], v[156:159], v[196:199], v[18:21]
	v_mfma_f32_16x16x32_bf16 v[6:9], v[148:151], v[204:207], v[6:9]
	v_mfma_f32_16x16x32_bf16 v[2:5], v[156:159], v[204:207], v[2:5]
	v_mfma_f32_16x16x32_bf16 v[46:49], v[152:155], v[184:187], v[46:49]
	v_mfma_f32_16x16x32_bf16 v[42:45], v[160:163], v[184:187], v[42:45]
	v_mfma_f32_16x16x32_bf16 v[38:41], v[152:155], v[192:195], v[38:41]
	v_mfma_f32_16x16x32_bf16 v[34:37], v[160:163], v[192:195], v[34:37]
	v_mfma_f32_16x16x32_bf16 v[22:25], v[152:155], v[200:203], v[22:25]
	v_mfma_f32_16x16x32_bf16 v[18:21], v[160:163], v[200:203], v[18:21]
	v_mfma_f32_16x16x32_bf16 v[6:9], v[152:155], v[208:211], v[6:9]
	v_mfma_f32_16x16x32_bf16 v[2:5], v[160:163], v[208:211], v[2:5]
	s_setprio 0
	s_setprio 1
	v_mfma_f32_16x16x32_bf16 v[30:33], v[164:167], v[180:183], v[30:33]
	v_mfma_f32_16x16x32_bf16 v[26:29], v[172:175], v[180:183], v[26:29]
	v_mfma_f32_16x16x32_bf16 v[14:17], v[164:167], v[188:191], v[14:17]
	v_mfma_f32_16x16x32_bf16 v[10:13], v[172:175], v[188:191], v[10:13]
	v_mfma_f32_16x16x32_bf16 v[62:65], v[164:167], v[196:199], v[62:65]
	v_mfma_f32_16x16x32_bf16 v[66:69], v[172:175], v[196:199], v[66:69]
	v_mfma_f32_16x16x32_bf16 v[50:53], v[164:167], v[204:207], v[50:53]
	v_mfma_f32_16x16x32_bf16 v[54:57], v[172:175], v[204:207], v[54:57]
	v_mfma_f32_16x16x32_bf16 v[30:33], v[168:171], v[184:187], v[30:33]
	v_mfma_f32_16x16x32_bf16 v[26:29], v[176:179], v[184:187], v[26:29]
	v_mfma_f32_16x16x32_bf16 v[14:17], v[168:171], v[192:195], v[14:17]
	v_mfma_f32_16x16x32_bf16 v[10:13], v[176:179], v[192:195], v[10:13]
	v_mfma_f32_16x16x32_bf16 v[62:65], v[168:171], v[200:203], v[62:65]
	v_mfma_f32_16x16x32_bf16 v[66:69], v[176:179], v[200:203], v[66:69]
	v_mfma_f32_16x16x32_bf16 v[50:53], v[168:171], v[208:211], v[50:53]
	v_mfma_f32_16x16x32_bf16 v[54:57], v[176:179], v[208:211], v[54:57]
	s_setprio 0
	s_barrier
	s_add_i32 s52, s52, 2
	s_add_u32 s22, s22, 0x100
	s_addc_u32 s23, s23, 0
	s_add_u32 s17, s17, 0x100
	s_addc_u32 s19, s19, 0
	s_cmp_gt_u32 s52, 29
	s_cbranch_scc0 .LBB0_501
	s_and_b64 vcc, exec, s[12:13]
	s_cbranch_vccz .LBB0_504
	s_barrier

; #define PG8_STAGE(bufoff, gbase, VO) do { _Pragma("unroll") for (int _i = 0; _i < 2; ++_i) \
;         __builtin_amdgcn_global_load_lds((const unsigned*)((const char*)(gbase) + VO[_i]), (LAS unsigned*)(lds + (bufoff) + ldsw + _i * 8192), 16, 0, 0); } while (0)
; #define PG8_LDA(dst, b, h) do { _Pragma("unroll") for (int m = 0; m < 4; ++m) _Pragma("unroll") for (int k = 0; k < 2; ++k) dst[m][k] = *(const LAS bf16x8*)(lds + PG8_SA(b, h) + aoff + m * 2048 + k * 1024); } while (0)
; #define PG8_LDB(dst, b, h) do { _Pragma("unroll") for (int n = 0; n < 2; ++n) _Pragma("unroll") for (int k = 0; k < 2; ++k) dst[n][k] = *(const LAS bf16x8*)(lds + PG8_SB(b, h) + boff + n * 2048 + k * 1024); } while (0)
; #define PG8_MMA(ai, bj, At, Bt) do { __builtin_amdgcn_s_setprio(1); _Pragma("unroll") for (int m = 0; m < 4; ++m) _Pragma("unroll") for (int n = 0; n < 2; ++n) _Pragma("unroll") for (int k = 0; k < 2; ++k) \
;         acc[ai][bj][m][n] = __builtin_amdgcn_mfma_f32_16x16x32_bf16(Bt[n][k], At[m][k], acc[ai][bj][m][n], 0, 0, 0); __builtin_amdgcn_s_setprio(0); } while (0)
; #define PG8_WAIT_V(n) asm volatile("s_waitcnt vmcnt(" #n ")" ::: "memory")
; #define PG8_BAR __builtin_amdgcn_s_barrier()
; template <int NSEG, class Epi, bool ALIGN_EPI = PG8_ALIGN, bool SP2 = PG8_SP2>
; DI void gemm_phase(LAS unsigned char* lds, const Gemm g, const StaticOrder& S, const Epi& E) {
;     ...
;             const char* a1 = cA + (size_t)(t + 1) * kstep;
;             const char* a2 = last ? nA : cA + (size_t)(t + 2) * kstep; const char* b2 = last ? nB : cB + (size_t)(t + 2) * kstep;
;             const char* a3 = a2 + kstep; const char* b3 = b2 + kstep;
;             unsigned v2[2]; v2[0] = (NSEG > 1 && last) ? voffN[0] : voffC[0]; v2[1] = (NSEG > 1 && last) ? voffN[1] : voffC[1];
;             const size_t h2 = (NSEG > 1 && last) ? hstepN : hstepC;
;             if constexpr (SP2) {
;             PG8_LDB(B0, 0, 0); PG8_LDB(B1, 0, 1); PG8_SCHED; PG8_LDA(At, 0, 0); PG8_STAGE(PG8_SA(1, 1), a1 + hstepC, voffC);
;             PG8_WAIT_V(8); PG8_WAIT_L(0); PG8_BAR; PG8_MMA(0, 0, At, B0); PG8_MMA(0, 1, At, B1); PG8_BAR; PG8_SCHED;
;             PG8_LDA(At, 0, 1); PG8_STAGE(PG8_SB(0, 0), b2, v2); PG8_STAGE(PG8_SB(0, 1), b2 + h2, v2); PG8_STAGE(PG8_SA(0, 0), a2, v2);
;             PG8_WAIT_V(8); PG8_WAIT_L(0); PG8_BAR; PG8_MMA(1, 0, At, B0); PG8_MMA(1, 1, At, B1); PG8_BAR; PG8_SCHED;
.LBB0_545:
	ds_read_b128 v[102:105], v207
	ds_read_b128 v[106:109], v207 offset:1024
	ds_read_b128 v[110:113], v207 offset:2048
	ds_read_b128 v[114:117], v207 offset:3072
	ds_read_b128 v[118:121], v208
	ds_read_b128 v[122:125], v208 offset:1024
	ds_read_b128 v[126:129], v208 offset:2048
	ds_read_b128 v[130:133], v208 offset:3072
	s_add_i32 m0, s3, 0xc000
	ds_read_b128 v[162:165], v209
	ds_read_b128 v[166:169], v209 offset:1024
	ds_read_b128 v[170:173], v209 offset:2048
	ds_read_b128 v[188:191], v209 offset:3072
	ds_read_b128 v[192:195], v209 offset:4096
	ds_read_b128 v[196:199], v209 offset:5120
	ds_read_b128 v[200:203], v209 offset:6144
	ds_read_b128 v[212:215], v209 offset:7168
	global_load_lds_dwordx4 v178, s[4:5]
	s_add_i32 m0, s3, 0xe000
	s_nop 0
	global_load_lds_dwordx4 v180, s[4:5]
	s_waitcnt vmcnt(8)
	s_waitcnt lgkmcnt(0)
	s_setprio 1
	s_barrier
	v_mfma_f32_16x16x32_bf16 v[158:161], v[102:105], v[162:165], v[158:161]
	v_mfma_f32_16x16x32_bf16 v[154:157], v[110:113], v[162:165], v[154:157]
	s_add_u32 s34, s4, 0xfff80080
	s_addc_u32 s35, s5, -1
	v_mfma_f32_16x16x32_bf16 v[150:153], v[102:105], v[170:173], v[150:153]
	v_mfma_f32_16x16x32_bf16 v[146:149], v[110:113], v[170:173], v[146:149]
	s_cmp_eq_u32 s67, 28
	s_cselect_b32 s39, s1, s35
	v_mfma_f32_16x16x32_bf16 v[142:145], v[102:105], v[192:195], v[142:145]
	v_mfma_f32_16x16x32_bf16 v[138:141], v[110:113], v[192:195], v[138:141]
	s_cselect_b32 s38, s25, s34
	s_cselect_b32 s35, s27, s66
	v_mfma_f32_16x16x32_bf16 v[134:137], v[102:105], v[200:203], v[134:137]
	v_mfma_f32_16x16x32_bf16 v[98:101], v[110:113], v[200:203], v[98:101]
	s_cselect_b32 s34, s64, s65
	v_mfma_f32_16x16x32_bf16 v[158:161], v[106:109], v[166:169], v[158:161]
	v_mfma_f32_16x16x32_bf16 v[154:157], v[114:117], v[166:169], v[154:157]
	v_mfma_f32_16x16x32_bf16 v[150:153], v[106:109], v[188:191], v[150:153]
	v_mfma_f32_16x16x32_bf16 v[146:149], v[114:117], v[188:191], v[146:149]
	v_mfma_f32_16x16x32_bf16 v[142:145], v[106:109], v[196:199], v[142:145]
	v_mfma_f32_16x16x32_bf16 v[138:141], v[114:117], v[196:199], v[138:141]
	v_mfma_f32_16x16x32_bf16 v[134:137], v[106:109], v[212:215], v[134:137]
	v_mfma_f32_16x16x32_bf16 v[98:101], v[114:117], v[212:215], v[98:101]
	s_setprio 0
	s_setprio 1
	v_mfma_f32_16x16x32_bf16 v[62:65], v[118:121], v[162:165], v[62:65]
	v_mfma_f32_16x16x32_bf16 v[58:61], v[126:129], v[162:165], v[58:61]
	v_mfma_f32_16x16x32_bf16 v[54:57], v[118:121], v[170:173], v[54:57]
	v_mfma_f32_16x16x32_bf16 v[50:53], v[126:129], v[170:173], v[50:53]
	v_mfma_f32_16x16x32_bf16 v[46:49], v[118:121], v[192:195], v[46:49]
	v_mfma_f32_16x16x32_bf16 v[42:45], v[126:129], v[192:195], v[42:45]
	v_mfma_f32_16x16x32_bf16 v[38:41], v[118:121], v[200:203], v[38:41]
	v_mfma_f32_16x16x32_bf16 v[34:37], v[126:129], v[200:203], v[34:37]
	v_mfma_f32_16x16x32_bf16 v[62:65], v[122:125], v[166:169], v[62:65]
	v_mfma_f32_16x16x32_bf16 v[58:61], v[130:133], v[166:169], v[58:61]
	v_mfma_f32_16x16x32_bf16 v[54:57], v[122:125], v[188:191], v[54:57]
	v_mfma_f32_16x16x32_bf16 v[50:53], v[130:133], v[188:191], v[50:53]
	v_mfma_f32_16x16x32_bf16 v[46:49], v[122:125], v[196:199], v[46:49]
	v_mfma_f32_16x16x32_bf16 v[42:45], v[130:133], v[196:199], v[42:45]
	v_mfma_f32_16x16x32_bf16 v[38:41], v[122:125], v[212:215], v[38:41]
	v_mfma_f32_16x16x32_bf16 v[34:37], v[130:133], v[212:215], v[34:37]
	s_setprio 0
	s_barrier
	s_add_i32 s68, s58, s50
	v_lshl_add_u64 v[204:205], s[34:35], 0, v[174:175]
	s_mov_b32 m0, s68
	ds_read_b128 v[162:165], v209 offset:16384
	ds_read_b128 v[166:169], v209 offset:17408
	ds_read_b128 v[170:173], v209 offset:18432
	ds_read_b128 v[188:191], v209 offset:19456
	ds_read_b128 v[192:195], v209 offset:20480
	ds_read_b128 v[196:199], v209 offset:21504
	ds_read_b128 v[200:203], v209 offset:22528
	ds_read_b128 v[212:215], v209 offset:23552
	global_load_lds_dwordx4 v[204:205], off
	s_add_i32 m0, s68, 0x2000
	s_add_u32 s68, s34, 0x80000
	v_lshl_add_u64 v[216:217], s[34:35], 0, v[176:177]
	s_addc_u32 s69, s35, 0
	s_add_i32 s70, s59, s50
	global_load_lds_dwordx4 v[216:217], off
	v_lshl_add_u64 v[218:219], s[68:69], 0, v[174:175]
	s_mov_b32 m0, s70
	v_lshl_add_u64 v[220:221], s[38:39], 0, v[176:177]
	global_load_lds_dwordx4 v[218:219], off
	v_lshl_add_u64 v[218:219], s[68:69], 0, v[176:177]
	s_add_i32 m0, s70, 0x2000
	s_nop 0
	global_load_lds_dwordx4 v[218:219], off
	v_lshl_add_u64 v[218:219], s[38:39], 0, v[174:175]
	s_mov_b32 m0, s3
	s_nop 0
	global_load_lds_dwordx4 v[218:219], off
	s_mov_b32 m0, s52
	s_nop 0
	global_load_lds_dwordx4 v[220:221], off
	s_waitcnt vmcnt(8)
	s_waitcnt lgkmcnt(0)
	s_setprio 1
	s_barrier
; #define PG8_STAGE(bufoff, gbase, VO) do { _Pragma("unroll") for (int _i = 0; _i < 2; ++_i) \
;         __builtin_amdgcn_global_load_lds((const unsigned*)((const char*)(gbase) + VO[_i]), (LAS unsigned*)(lds + (bufoff) + ldsw + _i * 8192), 16, 0, 0); } while (0)
; #define PG8_LDA(dst, b, h) do { _Pragma("unroll") for (int m = 0; m < 4; ++m) _Pragma("unroll") for (int k = 0; k < 2; ++k) dst[m][k] = *(const LAS bf16x8*)(lds + PG8_SA(b, h) + aoff + m * 2048 + k * 1024); } while (0)
; #define PG8_LDB(dst, b, h) do { _Pragma("unroll") for (int n = 0; n < 2; ++n) _Pragma("unroll") for (int k = 0; k < 2; ++k) dst[n][k] = *(const LAS bf16x8*)(lds + PG8_SB(b, h) + boff + n * 2048 + k * 1024); } while (0)
; #define PG8_MMA(ai, bj, At, Bt) do { __builtin_amdgcn_s_setprio(1); _Pragma("unroll") for (int m = 0; m < 4; ++m) _Pragma("unroll") for (int n = 0; n < 2; ++n) _Pragma("unroll") for (int k = 0; k < 2; ++k) \
;         acc[ai][bj][m][n] = __builtin_amdgcn_mfma_f32_16x16x32_bf16(Bt[n][k], At[m][k], acc[ai][bj][m][n], 0, 0, 0); __builtin_amdgcn_s_setprio(0); } while (0)
; #define PG8_WAIT_V(n) asm volatile("s_waitcnt vmcnt(" #n ")" ::: "memory")
; #define PG8_WAIT_L(n) asm volatile("s_waitcnt lgkmcnt(" #n ")" ::: "memory")
; #define PG8_BAR __builtin_amdgcn_s_barrier()
; #define PG8_SCHED __builtin_amdgcn_sched_barrier(0)
; template <int NSEG, class Epi, bool ALIGN_EPI = PG8_ALIGN, bool SP2 = PG8_SP2>
; DI void gemm_phase(LAS unsigned char* lds, const Gemm g, const StaticOrder& S, const Epi& E) {
;     ...
;             PG8_WAIT_V(8); PG8_WAIT_L(0); PG8_BAR; PG8_MMA(1, 0, At, B0); PG8_MMA(1, 1, At, B1); PG8_BAR; PG8_SCHED;
;             PG8_LDB(B0, 1, 0); PG8_LDB(B1, 1, 1); PG8_SCHED; PG8_LDA(At, 1, 0); PG8_STAGE(PG8_SA(0, 1), a2 + h2, v2);
;             PG8_WAIT_V(8); PG8_WAIT_L(0); PG8_BAR; PG8_MMA(0, 0, At, B0); PG8_MMA(0, 1, At, B1); PG8_BAR; PG8_SCHED;
	v_mfma_f32_16x16x32_bf16 v[94:97], v[102:105], v[162:165], v[94:97]
	v_mfma_f32_16x16x32_bf16 v[90:93], v[110:113], v[162:165], v[90:93]
	s_add_i32 s68, 0, 0x18000
	s_add_i32 s69, 0, 0x1c000
	v_mfma_f32_16x16x32_bf16 v[86:89], v[102:105], v[170:173], v[86:89]
	v_mfma_f32_16x16x32_bf16 v[82:85], v[110:113], v[170:173], v[82:85]
	s_add_u32 s38, s38, 0x80000
	s_addc_u32 s39, s39, 0
	v_mfma_f32_16x16x32_bf16 v[78:81], v[102:105], v[192:195], v[78:81]
	v_mfma_f32_16x16x32_bf16 v[74:77], v[110:113], v[192:195], v[74:77]
	v_mfma_f32_16x16x32_bf16 v[70:73], v[102:105], v[200:203], v[70:73]
	v_mfma_f32_16x16x32_bf16 v[66:69], v[110:113], v[200:203], v[66:69]
	v_mfma_f32_16x16x32_bf16 v[94:97], v[106:109], v[166:169], v[94:97]
	v_mfma_f32_16x16x32_bf16 v[90:93], v[114:117], v[166:169], v[90:93]
	v_mfma_f32_16x16x32_bf16 v[86:89], v[106:109], v[188:191], v[86:89]
	v_mfma_f32_16x16x32_bf16 v[82:85], v[114:117], v[188:191], v[82:85]
	v_mfma_f32_16x16x32_bf16 v[78:81], v[106:109], v[196:199], v[78:81]
	v_mfma_f32_16x16x32_bf16 v[74:77], v[114:117], v[196:199], v[74:77]
	v_mfma_f32_16x16x32_bf16 v[70:73], v[106:109], v[212:215], v[70:73]
	v_mfma_f32_16x16x32_bf16 v[66:69], v[114:117], v[212:215], v[66:69]
	s_setprio 0
	s_setprio 1
	v_mfma_f32_16x16x32_bf16 v[30:33], v[118:121], v[162:165], v[30:33]
	v_mfma_f32_16x16x32_bf16 v[26:29], v[126:129], v[162:165], v[26:29]
	v_mfma_f32_16x16x32_bf16 v[22:25], v[118:121], v[170:173], v[22:25]
	v_mfma_f32_16x16x32_bf16 v[14:17], v[126:129], v[170:173], v[14:17]
	v_mfma_f32_16x16x32_bf16 v[18:21], v[118:121], v[192:195], v[18:21]
	v_mfma_f32_16x16x32_bf16 v[10:13], v[126:129], v[192:195], v[10:13]
	v_mfma_f32_16x16x32_bf16 v[6:9], v[118:121], v[200:203], v[6:9]
	v_mfma_f32_16x16x32_bf16 v[2:5], v[126:129], v[200:203], v[2:5]
	v_mfma_f32_16x16x32_bf16 v[30:33], v[122:125], v[166:169], v[30:33]
	v_mfma_f32_16x16x32_bf16 v[26:29], v[130:133], v[166:169], v[26:29]
	v_mfma_f32_16x16x32_bf16 v[22:25], v[122:125], v[188:191], v[22:25]
	v_mfma_f32_16x16x32_bf16 v[14:17], v[130:133], v[188:191], v[14:17]
	v_mfma_f32_16x16x32_bf16 v[18:21], v[122:125], v[196:199], v[18:21]
	v_mfma_f32_16x16x32_bf16 v[10:13], v[130:133], v[196:199], v[10:13]
	v_mfma_f32_16x16x32_bf16 v[6:9], v[122:125], v[212:215], v[6:9]
	v_mfma_f32_16x16x32_bf16 v[2:5], v[130:133], v[212:215], v[2:5]
	s_setprio 0
	s_barrier
	v_add_u32_e32 v114, s68, v187
	v_add_u32_e32 v130, s69, v187
	ds_read_b128 v[102:105], v114
	ds_read_b128 v[106:109], v114 offset:1024
	ds_read_b128 v[110:113], v114 offset:2048
	ds_read_b128 v[114:117], v114 offset:3072
	ds_read_b128 v[118:121], v130
	ds_read_b128 v[122:125], v130 offset:1024
	ds_read_b128 v[126:129], v130 offset:2048
	ds_read_b128 v[130:133], v130 offset:3072
	s_mov_b32 m0, s53
	ds_read_b128 v[162:165], v209 offset:32768
	ds_read_b128 v[166:169], v209 offset:33792
	ds_read_b128 v[170:173], v209 offset:34816
	ds_read_b128 v[188:191], v209 offset:35840
	ds_read_b128 v[192:195], v209 offset:36864
	ds_read_b128 v[196:199], v209 offset:37888
	ds_read_b128 v[200:203], v209 offset:38912
	ds_read_b128 v[212:215], v209 offset:39936
	global_load_lds_dwordx4 v174, s[38:39]
	s_mov_b32 m0, s54
	s_nop 0
	global_load_lds_dwordx4 v176, s[38:39]
	s_waitcnt vmcnt(8)
	s_waitcnt lgkmcnt(0)
	s_setprio 1
	s_barrier
	v_mfma_f32_16x16x32_bf16 v[158:161], v[102:105], v[162:165], v[158:161]
	v_mfma_f32_16x16x32_bf16 v[154:157], v[110:113], v[162:165], v[154:157]
	v_mfma_f32_16x16x32_bf16 v[150:153], v[102:105], v[170:173], v[150:153]
	v_mfma_f32_16x16x32_bf16 v[146:149], v[110:113], v[170:173], v[146:149]
	v_mfma_f32_16x16x32_bf16 v[142:145], v[102:105], v[192:195], v[142:145]
	v_mfma_f32_16x16x32_bf16 v[138:141], v[110:113], v[192:195], v[138:141]
	v_mfma_f32_16x16x32_bf16 v[134:137], v[102:105], v[200:203], v[134:137]
	v_mfma_f32_16x16x32_bf16 v[98:101], v[110:113], v[200:203], v[98:101]
	v_mfma_f32_16x16x32_bf16 v[158:161], v[106:109], v[166:169], v[158:161]
	v_mfma_f32_16x16x32_bf16 v[154:157], v[114:117], v[166:169], v[154:157]
	v_mfma_f32_16x16x32_bf16 v[150:153], v[106:109], v[188:191], v[150:153]
	v_mfma_f32_16x16x32_bf16 v[146:149], v[114:117], v[188:191], v[146:149]
	v_mfma_f32_16x16x32_bf16 v[142:145], v[106:109], v[196:199], v[142:145]
	v_mfma_f32_16x16x32_bf16 v[138:141], v[114:117], v[196:199], v[138:141]
	v_mfma_f32_16x16x32_bf16 v[134:137], v[106:109], v[212:215], v[134:137]
	v_mfma_f32_16x16x32_bf16 v[98:101], v[114:117], v[212:215], v[98:101]
	s_setprio 0
	s_setprio 1
	v_mfma_f32_16x16x32_bf16 v[62:65], v[118:121], v[162:165], v[62:65]
	v_mfma_f32_16x16x32_bf16 v[58:61], v[126:129], v[162:165], v[58:61]
	v_mfma_f32_16x16x32_bf16 v[54:57], v[118:121], v[170:173], v[54:57]
	v_mfma_f32_16x16x32_bf16 v[50:53], v[126:129], v[170:173], v[50:53]
	v_mfma_f32_16x16x32_bf16 v[46:49], v[118:121], v[192:195], v[46:49]
	v_mfma_f32_16x16x32_bf16 v[42:45], v[126:129], v[192:195], v[42:45]
	v_mfma_f32_16x16x32_bf16 v[38:41], v[118:121], v[200:203], v[38:41]
	v_mfma_f32_16x16x32_bf16 v[34:37], v[126:129], v[200:203], v[34:37]
	v_mfma_f32_16x16x32_bf16 v[62:65], v[122:125], v[166:169], v[62:65]
	v_mfma_f32_16x16x32_bf16 v[58:61], v[130:133], v[166:169], v[58:61]
	v_mfma_f32_16x16x32_bf16 v[54:57], v[122:125], v[188:191], v[54:57]
	v_mfma_f32_16x16x32_bf16 v[50:53], v[130:133], v[188:191], v[50:53]
	v_mfma_f32_16x16x32_bf16 v[46:49], v[122:125], v[196:199], v[46:49]
	v_mfma_f32_16x16x32_bf16 v[42:45], v[130:133], v[196:199], v[42:45]
	v_mfma_f32_16x16x32_bf16 v[38:41], v[122:125], v[212:215], v[38:41]
	v_mfma_f32_16x16x32_bf16 v[34:37], v[130:133], v[212:215], v[34:37]
	s_setprio 0
	s_barrier
; #define PG8_STAGE(bufoff, gbase, VO) do { _Pragma("unroll") for (int _i = 0; _i < 2; ++_i) \
;         __builtin_amdgcn_global_load_lds((const unsigned*)((const char*)(gbase) + VO[_i]), (LAS unsigned*)(lds + (bufoff) + ldsw + _i * 8192), 16, 0, 0); } while (0)
; #define PG8_LDA(dst, b, h) do { _Pragma("unroll") for (int m = 0; m < 4; ++m) _Pragma("unroll") for (int k = 0; k < 2; ++k) dst[m][k] = *(const LAS bf16x8*)(lds + PG8_SA(b, h) + aoff + m * 2048 + k * 1024); } while (0)
; #define PG8_MMA(ai, bj, At, Bt) do { __builtin_amdgcn_s_setprio(1); _Pragma("unroll") for (int m = 0; m < 4; ++m) _Pragma("unroll") for (int n = 0; n < 2; ++n) _Pragma("unroll") for (int k = 0; k < 2; ++k) \
;         acc[ai][bj][m][n] = __builtin_amdgcn_mfma_f32_16x16x32_bf16(Bt[n][k], At[m][k], acc[ai][bj][m][n], 0, 0, 0); __builtin_amdgcn_s_setprio(0); } while (0)
; #define PG8_WAIT_V(n) asm volatile("s_waitcnt vmcnt(" #n ")" ::: "memory")
; #define PG8_WAIT_L(n) asm volatile("s_waitcnt lgkmcnt(" #n ")" ::: "memory")
; #define PG8_BAR __builtin_amdgcn_s_barrier()
; #define PG8_SCHED __builtin_amdgcn_sched_barrier(0)
; template <int NSEG, class Epi, bool ALIGN_EPI = PG8_ALIGN, bool SP2 = PG8_SP2>
; DI void gemm_phase(LAS unsigned char* lds, const Gemm g, const StaticOrder& S, const Epi& E) {
;     ...
;             PG8_LDA(At, 1, 1); PG8_STAGE(PG8_SB(1, 0), b3, v2); PG8_STAGE(PG8_SB(1, 1), b3 + h2, v2); PG8_STAGE(PG8_SA(1, 0), a3, v2);
;             PG8_WAIT_V(8); PG8_WAIT_L(0); PG8_BAR; PG8_MMA(1, 0, At, B0); PG8_MMA(1, 1, At, B1); PG8_BAR; PG8_SCHED;
;     ...
;         if constexpr (ALIGN_EPI) { if (wr == 0) PG8_BAR; }
	s_add_i32 s38, s68, s50
	v_lshl_add_u64 v[204:205], v[204:205], 0, s[16:17]
	s_mov_b32 m0, s38
	ds_read_b128 v[162:165], v209 offset:49152
	ds_read_b128 v[166:169], v209 offset:50176
	ds_read_b128 v[170:173], v209 offset:51200
	ds_read_b128 v[188:191], v209 offset:52224
	ds_read_b128 v[192:195], v209 offset:53248
	ds_read_b128 v[196:199], v209 offset:54272
	ds_read_b128 v[200:203], v209 offset:55296
	ds_read_b128 v[212:215], v209 offset:56320
	global_load_lds_dwordx4 v[204:205], off
	s_add_i32 m0, s38, 0x2000
	s_add_u32 s34, s34, 0x80080
	v_lshl_add_u64 v[204:205], v[216:217], 0, s[16:17]
	s_addc_u32 s35, s35, 0
	s_add_i32 s38, s69, s50
	global_load_lds_dwordx4 v[204:205], off
	v_lshl_add_u64 v[204:205], s[34:35], 0, v[174:175]
	s_mov_b32 m0, s38
	s_nop 0
	global_load_lds_dwordx4 v[204:205], off
	v_lshl_add_u64 v[204:205], s[34:35], 0, v[176:177]
	s_add_i32 m0, s38, 0x2000
	s_nop 0
	global_load_lds_dwordx4 v[204:205], off
	v_lshl_add_u64 v[204:205], v[218:219], 0, s[16:17]
	s_mov_b32 m0, s55
	s_nop 0
	global_load_lds_dwordx4 v[204:205], off
	v_lshl_add_u64 v[204:205], v[220:221], 0, s[16:17]
	s_mov_b32 m0, s56
	s_nop 0
	global_load_lds_dwordx4 v[204:205], off
	s_waitcnt vmcnt(8)
	s_waitcnt lgkmcnt(0)
	s_setprio 1
	s_barrier
	v_mfma_f32_16x16x32_bf16 v[94:97], v[102:105], v[162:165], v[94:97]
	v_mfma_f32_16x16x32_bf16 v[90:93], v[110:113], v[162:165], v[90:93]
	v_mfma_f32_16x16x32_bf16 v[86:89], v[102:105], v[170:173], v[86:89]
	v_mfma_f32_16x16x32_bf16 v[82:85], v[110:113], v[170:173], v[82:85]
	v_mfma_f32_16x16x32_bf16 v[78:81], v[102:105], v[192:195], v[78:81]
	v_mfma_f32_16x16x32_bf16 v[74:77], v[110:113], v[192:195], v[74:77]
	v_mfma_f32_16x16x32_bf16 v[70:73], v[102:105], v[200:203], v[70:73]
	v_mfma_f32_16x16x32_bf16 v[66:69], v[110:113], v[200:203], v[66:69]
	v_mfma_f32_16x16x32_bf16 v[94:97], v[106:109], v[166:169], v[94:97]
	v_mfma_f32_16x16x32_bf16 v[90:93], v[114:117], v[166:169], v[90:93]
	v_mfma_f32_16x16x32_bf16 v[86:89], v[106:109], v[188:191], v[86:89]
	v_mfma_f32_16x16x32_bf16 v[82:85], v[114:117], v[188:191], v[82:85]
	v_mfma_f32_16x16x32_bf16 v[78:81], v[106:109], v[196:199], v[78:81]
	v_mfma_f32_16x16x32_bf16 v[74:77], v[114:117], v[196:199], v[74:77]
	v_mfma_f32_16x16x32_bf16 v[70:73], v[106:109], v[212:215], v[70:73]
	v_mfma_f32_16x16x32_bf16 v[66:69], v[114:117], v[212:215], v[66:69]
	s_setprio 0
	s_setprio 1
	v_mfma_f32_16x16x32_bf16 v[30:33], v[118:121], v[162:165], v[30:33]
	v_mfma_f32_16x16x32_bf16 v[26:29], v[126:129], v[162:165], v[26:29]
	v_mfma_f32_16x16x32_bf16 v[22:25], v[118:121], v[170:173], v[22:25]
	v_mfma_f32_16x16x32_bf16 v[14:17], v[126:129], v[170:173], v[14:17]
	v_mfma_f32_16x16x32_bf16 v[18:21], v[118:121], v[192:195], v[18:21]
	v_mfma_f32_16x16x32_bf16 v[10:13], v[126:129], v[192:195], v[10:13]
	v_mfma_f32_16x16x32_bf16 v[6:9], v[118:121], v[200:203], v[6:9]
	v_mfma_f32_16x16x32_bf16 v[2:5], v[126:129], v[200:203], v[2:5]
	v_mfma_f32_16x16x32_bf16 v[30:33], v[122:125], v[166:169], v[30:33]
	v_mfma_f32_16x16x32_bf16 v[26:29], v[130:133], v[166:169], v[26:29]
	v_mfma_f32_16x16x32_bf16 v[22:25], v[122:125], v[188:191], v[22:25]
	v_mfma_f32_16x16x32_bf16 v[14:17], v[130:133], v[188:191], v[14:17]
	v_mfma_f32_16x16x32_bf16 v[18:21], v[122:125], v[196:199], v[18:21]
	v_mfma_f32_16x16x32_bf16 v[10:13], v[130:133], v[196:199], v[10:13]
	v_mfma_f32_16x16x32_bf16 v[6:9], v[122:125], v[212:215], v[6:9]
	v_mfma_f32_16x16x32_bf16 v[2:5], v[130:133], v[212:215], v[2:5]
	s_setprio 0
	s_barrier
	s_add_i32 s67, s67, 2
	s_add_u32 s4, s4, 0x100
	s_addc_u32 s5, s5, 0
	s_add_u32 s65, s65, 0x100
	s_addc_u32 s66, s66, 0
	s_cmp_gt_u32 s67, 29
	s_cbranch_scc0 .LBB0_545
	s_and_b64 vcc, exec, s[18:19]
	s_cbranch_vccz .LBB0_548
	s_barrier

; #define PG8_STAGE(bufoff, gbase, VO) do { _Pragma("unroll") for (int _i = 0; _i < 2; ++_i) \
;         __builtin_amdgcn_global_load_lds((const unsigned*)((const char*)(gbase) + VO[_i]), (LAS unsigned*)(lds + (bufoff) + ldsw + _i * 8192), 16, 0, 0); } while (0)
; #define PG8_LDA(dst, b, h) do { _Pragma("unroll") for (int m = 0; m < 4; ++m) _Pragma("unroll") for (int k = 0; k < 2; ++k) dst[m][k] = *(const LAS bf16x8*)(lds + PG8_SA(b, h) + aoff + m * 2048 + k * 1024); } while (0)
; #define PG8_LDB(dst, b, h) do { _Pragma("unroll") for (int n = 0; n < 2; ++n) _Pragma("unroll") for (int k = 0; k < 2; ++k) dst[n][k] = *(const LAS bf16x8*)(lds + PG8_SB(b, h) + boff + n * 2048 + k * 1024); } while (0)
; #define PG8_MMA(ai, bj, At, Bt) do { __builtin_amdgcn_s_setprio(1); _Pragma("unroll") for (int m = 0; m < 4; ++m) _Pragma("unroll") for (int n = 0; n < 2; ++n) _Pragma("unroll") for (int k = 0; k < 2; ++k) \
;         acc[ai][bj][m][n] = __builtin_amdgcn_mfma_f32_16x16x32_bf16(Bt[n][k], At[m][k], acc[ai][bj][m][n], 0, 0, 0); __builtin_amdgcn_s_setprio(0); } while (0)
; #define PG8_WAIT_V(n) asm volatile("s_waitcnt vmcnt(" #n ")" ::: "memory")
; #define PG8_BAR __builtin_amdgcn_s_barrier()
; template <int NSEG, class Epi, bool ALIGN_EPI = PG8_ALIGN, bool SP2 = PG8_SP2>
; DI void gemm_phase(LAS unsigned char* lds, const Gemm g, const StaticOrder& S, const Epi& E) {
;     ...
;             const char* a1 = cA + (size_t)(t + 1) * kstep;
;             const char* a2 = last ? nA : cA + (size_t)(t + 2) * kstep; const char* b2 = last ? nB : cB + (size_t)(t + 2) * kstep;
;             const char* a3 = a2 + kstep; const char* b3 = b2 + kstep;
;             unsigned v2[2]; v2[0] = (NSEG > 1 && last) ? voffN[0] : voffC[0]; v2[1] = (NSEG > 1 && last) ? voffN[1] : voffC[1];
;             const size_t h2 = (NSEG > 1 && last) ? hstepN : hstepC;
;             if constexpr (SP2) {
;             PG8_LDB(B0, 0, 0); PG8_LDB(B1, 0, 1); PG8_SCHED; PG8_LDA(At, 0, 0); PG8_STAGE(PG8_SA(1, 1), a1 + hstepC, voffC);
;             PG8_WAIT_V(8); PG8_WAIT_L(0); PG8_BAR; PG8_MMA(0, 0, At, B0); PG8_MMA(0, 1, At, B1); PG8_BAR; PG8_SCHED;
;             PG8_LDA(At, 0, 1); PG8_STAGE(PG8_SB(0, 0), b2, v2); PG8_STAGE(PG8_SB(0, 1), b2 + h2, v2); PG8_STAGE(PG8_SA(0, 0), a2, v2);
;             PG8_WAIT_V(8); PG8_WAIT_L(0); PG8_BAR; PG8_MMA(1, 0, At, B0); PG8_MMA(1, 1, At, B1); PG8_BAR; PG8_SCHED;
.LBB0_599:
	ds_read_b128 v[146:149], v143
	ds_read_b128 v[150:153], v143 offset:1024
	ds_read_b128 v[154:157], v143 offset:2048
	ds_read_b128 v[158:161], v143 offset:3072
	ds_read_b128 v[162:165], v144
	ds_read_b128 v[166:169], v144 offset:1024
	ds_read_b128 v[170:173], v144 offset:2048
	ds_read_b128 v[174:177], v144 offset:3072
	s_add_i32 m0, s45, 0xc000
	ds_read_b128 v[178:181], v145
	ds_read_b128 v[182:185], v145 offset:1024
	ds_read_b128 v[186:189], v145 offset:2048
	ds_read_b128 v[190:193], v145 offset:3072
	ds_read_b128 v[194:197], v145 offset:4096
	ds_read_b128 v[198:201], v145 offset:5120
	ds_read_b128 v[202:205], v145 offset:6144
	ds_read_b128 v[206:209], v145 offset:7168
	global_load_lds_dwordx4 v134, s[26:27]
	s_add_i32 m0, s45, 0xe000
	s_nop 0
	global_load_lds_dwordx4 v136, s[26:27]
	s_waitcnt vmcnt(8)
	s_waitcnt lgkmcnt(0)
	s_setprio 1
	s_barrier
	v_mfma_f32_16x16x32_bf16 v[126:129], v[146:149], v[178:181], v[126:129]
	v_mfma_f32_16x16x32_bf16 v[122:125], v[154:157], v[178:181], v[122:125]
	s_add_u32 s34, s26, 0xffea0080
	s_addc_u32 s35, s27, -1
	v_mfma_f32_16x16x32_bf16 v[118:121], v[146:149], v[186:189], v[118:121]
	v_mfma_f32_16x16x32_bf16 v[114:117], v[154:157], v[186:189], v[114:117]
	s_cmpk_eq_i32 s64, 0x54
	s_cselect_b32 s37, s23, s35
	v_mfma_f32_16x16x32_bf16 v[102:105], v[146:149], v[194:197], v[102:105]
	v_mfma_f32_16x16x32_bf16 v[98:101], v[154:157], v[194:197], v[98:101]
	s_cselect_b32 s36, s22, s34
	s_cselect_b32 s35, s25, s63
	v_mfma_f32_16x16x32_bf16 v[86:89], v[146:149], v[202:205], v[86:89]
	v_mfma_f32_16x16x32_bf16 v[82:85], v[154:157], v[202:205], v[82:85]
	s_cselect_b32 s34, s24, s62
	v_mfma_f32_16x16x32_bf16 v[126:129], v[150:153], v[182:185], v[126:129]
	v_mfma_f32_16x16x32_bf16 v[122:125], v[158:161], v[182:185], v[122:125]
	v_mfma_f32_16x16x32_bf16 v[118:121], v[150:153], v[190:193], v[118:121]
	v_mfma_f32_16x16x32_bf16 v[114:117], v[158:161], v[190:193], v[114:117]
	v_mfma_f32_16x16x32_bf16 v[102:105], v[150:153], v[198:201], v[102:105]
	v_mfma_f32_16x16x32_bf16 v[98:101], v[158:161], v[198:201], v[98:101]
	v_mfma_f32_16x16x32_bf16 v[86:89], v[150:153], v[206:209], v[86:89]
	v_mfma_f32_16x16x32_bf16 v[82:85], v[158:161], v[206:209], v[82:85]
	s_setprio 0
	s_setprio 1
	v_mfma_f32_16x16x32_bf16 v[110:113], v[162:165], v[178:181], v[110:113]
	v_mfma_f32_16x16x32_bf16 v[106:109], v[170:173], v[178:181], v[106:109]
	v_mfma_f32_16x16x32_bf16 v[94:97], v[162:165], v[186:189], v[94:97]
	v_mfma_f32_16x16x32_bf16 v[90:93], v[170:173], v[186:189], v[90:93]
	v_mfma_f32_16x16x32_bf16 v[78:81], v[162:165], v[194:197], v[78:81]
	v_mfma_f32_16x16x32_bf16 v[74:77], v[170:173], v[194:197], v[74:77]
	v_mfma_f32_16x16x32_bf16 v[70:73], v[162:165], v[202:205], v[70:73]
	v_mfma_f32_16x16x32_bf16 v[66:69], v[170:173], v[202:205], v[66:69]
	v_mfma_f32_16x16x32_bf16 v[110:113], v[166:169], v[182:185], v[110:113]
	v_mfma_f32_16x16x32_bf16 v[106:109], v[174:177], v[182:185], v[106:109]
	v_mfma_f32_16x16x32_bf16 v[94:97], v[166:169], v[190:193], v[94:97]
	v_mfma_f32_16x16x32_bf16 v[90:93], v[174:177], v[190:193], v[90:93]
	v_mfma_f32_16x16x32_bf16 v[78:81], v[166:169], v[198:201], v[78:81]
	v_mfma_f32_16x16x32_bf16 v[74:77], v[174:177], v[198:201], v[74:77]
	v_mfma_f32_16x16x32_bf16 v[70:73], v[166:169], v[206:209], v[70:73]
	v_mfma_f32_16x16x32_bf16 v[66:69], v[174:177], v[206:209], v[66:69]
	s_setprio 0
	s_barrier
	s_add_i32 s65, s52, s44
	v_lshl_add_u64 v[210:211], s[34:35], 0, v[130:131]
	s_mov_b32 m0, s65
	ds_read_b128 v[178:181], v145 offset:16384
	ds_read_b128 v[182:185], v145 offset:17408
	ds_read_b128 v[186:189], v145 offset:18432
	ds_read_b128 v[190:193], v145 offset:19456
	ds_read_b128 v[194:197], v145 offset:20480
	ds_read_b128 v[198:201], v145 offset:21504
	ds_read_b128 v[202:205], v145 offset:22528
	ds_read_b128 v[206:209], v145 offset:23552
	global_load_lds_dwordx4 v[210:211], off
	s_add_i32 m0, s65, 0x2000
	s_add_u32 s66, s34, 0x160000
	v_lshl_add_u64 v[212:213], s[34:35], 0, v[132:133]
	s_addc_u32 s67, s35, 0
	s_add_i32 s65, s53, s44
	global_load_lds_dwordx4 v[212:213], off
	v_lshl_add_u64 v[214:215], s[66:67], 0, v[130:131]
	s_mov_b32 m0, s65
	v_lshl_add_u64 v[216:217], s[36:37], 0, v[132:133]
	global_load_lds_dwordx4 v[214:215], off
	v_lshl_add_u64 v[214:215], s[66:67], 0, v[132:133]
	s_add_i32 m0, s65, 0x2000
	s_nop 0
	global_load_lds_dwordx4 v[214:215], off
	v_lshl_add_u64 v[214:215], s[36:37], 0, v[130:131]
	s_mov_b32 m0, s45
	s_nop 0
	global_load_lds_dwordx4 v[214:215], off
	s_mov_b32 m0, s46
	s_nop 0
	global_load_lds_dwordx4 v[216:217], off
	s_waitcnt vmcnt(8)
	s_waitcnt lgkmcnt(0)
	s_setprio 1
	s_barrier
; #define PG8_STAGE(bufoff, gbase, VO) do { _Pragma("unroll") for (int _i = 0; _i < 2; ++_i) \
;         __builtin_amdgcn_global_load_lds((const unsigned*)((const char*)(gbase) + VO[_i]), (LAS unsigned*)(lds + (bufoff) + ldsw + _i * 8192), 16, 0, 0); } while (0)
; #define PG8_LDA(dst, b, h) do { _Pragma("unroll") for (int m = 0; m < 4; ++m) _Pragma("unroll") for (int k = 0; k < 2; ++k) dst[m][k] = *(const LAS bf16x8*)(lds + PG8_SA(b, h) + aoff + m * 2048 + k * 1024); } while (0)
; #define PG8_LDB(dst, b, h) do { _Pragma("unroll") for (int n = 0; n < 2; ++n) _Pragma("unroll") for (int k = 0; k < 2; ++k) dst[n][k] = *(const LAS bf16x8*)(lds + PG8_SB(b, h) + boff + n * 2048 + k * 1024); } while (0)
; #define PG8_MMA(ai, bj, At, Bt) do { __builtin_amdgcn_s_setprio(1); _Pragma("unroll") for (int m = 0; m < 4; ++m) _Pragma("unroll") for (int n = 0; n < 2; ++n) _Pragma("unroll") for (int k = 0; k < 2; ++k) \
;         acc[ai][bj][m][n] = __builtin_amdgcn_mfma_f32_16x16x32_bf16(Bt[n][k], At[m][k], acc[ai][bj][m][n], 0, 0, 0); __builtin_amdgcn_s_setprio(0); } while (0)
; #define PG8_WAIT_V(n) asm volatile("s_waitcnt vmcnt(" #n ")" ::: "memory")
; #define PG8_WAIT_L(n) asm volatile("s_waitcnt lgkmcnt(" #n ")" ::: "memory")
; #define PG8_BAR __builtin_amdgcn_s_barrier()
; #define PG8_SCHED __builtin_amdgcn_sched_barrier(0)
; template <int NSEG, class Epi, bool ALIGN_EPI = PG8_ALIGN, bool SP2 = PG8_SP2>
; DI void gemm_phase(LAS unsigned char* lds, const Gemm g, const StaticOrder& S, const Epi& E) {
;     ...
;             PG8_WAIT_V(8); PG8_WAIT_L(0); PG8_BAR; PG8_MMA(1, 0, At, B0); PG8_MMA(1, 1, At, B1); PG8_BAR; PG8_SCHED;
;             PG8_LDB(B0, 1, 0); PG8_LDB(B1, 1, 1); PG8_SCHED; PG8_LDA(At, 1, 0); PG8_STAGE(PG8_SA(0, 1), a2 + h2, v2);
;             PG8_WAIT_V(8); PG8_WAIT_L(0); PG8_BAR; PG8_MMA(0, 0, At, B0); PG8_MMA(0, 1, At, B1); PG8_BAR; PG8_SCHED;
	v_mfma_f32_16x16x32_bf16 v[54:57], v[146:149], v[178:181], v[54:57]
	v_mfma_f32_16x16x32_bf16 v[46:49], v[154:157], v[178:181], v[46:49]
	s_add_i32 s65, 0, 0x18000
	s_add_i32 s66, 0, 0x1c000
	v_mfma_f32_16x16x32_bf16 v[38:41], v[146:149], v[186:189], v[38:41]
	v_mfma_f32_16x16x32_bf16 v[34:37], v[154:157], v[186:189], v[34:37]
	s_add_u32 s36, s36, 0x160000
	s_addc_u32 s37, s37, 0
	v_mfma_f32_16x16x32_bf16 v[22:25], v[146:149], v[194:197], v[22:25]
	v_mfma_f32_16x16x32_bf16 v[18:21], v[154:157], v[194:197], v[18:21]
	v_mfma_f32_16x16x32_bf16 v[6:9], v[146:149], v[202:205], v[6:9]
	v_mfma_f32_16x16x32_bf16 v[2:5], v[154:157], v[202:205], v[2:5]
	v_mfma_f32_16x16x32_bf16 v[54:57], v[150:153], v[182:185], v[54:57]
	v_mfma_f32_16x16x32_bf16 v[46:49], v[158:161], v[182:185], v[46:49]
	v_mfma_f32_16x16x32_bf16 v[38:41], v[150:153], v[190:193], v[38:41]
	v_mfma_f32_16x16x32_bf16 v[34:37], v[158:161], v[190:193], v[34:37]
	v_mfma_f32_16x16x32_bf16 v[22:25], v[150:153], v[198:201], v[22:25]
	v_mfma_f32_16x16x32_bf16 v[18:21], v[158:161], v[198:201], v[18:21]
	v_mfma_f32_16x16x32_bf16 v[6:9], v[150:153], v[206:209], v[6:9]
	v_mfma_f32_16x16x32_bf16 v[2:5], v[158:161], v[206:209], v[2:5]
	s_setprio 0
	s_setprio 1
	v_mfma_f32_16x16x32_bf16 v[30:33], v[162:165], v[178:181], v[30:33]
	v_mfma_f32_16x16x32_bf16 v[26:29], v[170:173], v[178:181], v[26:29]
	v_mfma_f32_16x16x32_bf16 v[14:17], v[162:165], v[186:189], v[14:17]
	v_mfma_f32_16x16x32_bf16 v[10:13], v[170:173], v[186:189], v[10:13]
	v_mfma_f32_16x16x32_bf16 v[58:61], v[162:165], v[194:197], v[58:61]
	v_mfma_f32_16x16x32_bf16 v[62:65], v[170:173], v[194:197], v[62:65]
	v_mfma_f32_16x16x32_bf16 v[42:45], v[162:165], v[202:205], v[42:45]
	v_mfma_f32_16x16x32_bf16 v[50:53], v[170:173], v[202:205], v[50:53]
	v_mfma_f32_16x16x32_bf16 v[30:33], v[166:169], v[182:185], v[30:33]
	v_mfma_f32_16x16x32_bf16 v[26:29], v[174:177], v[182:185], v[26:29]
	v_mfma_f32_16x16x32_bf16 v[14:17], v[166:169], v[190:193], v[14:17]
	v_mfma_f32_16x16x32_bf16 v[10:13], v[174:177], v[190:193], v[10:13]
	v_mfma_f32_16x16x32_bf16 v[58:61], v[166:169], v[198:201], v[58:61]
	v_mfma_f32_16x16x32_bf16 v[62:65], v[174:177], v[198:201], v[62:65]
	v_mfma_f32_16x16x32_bf16 v[42:45], v[166:169], v[206:209], v[42:45]
	v_mfma_f32_16x16x32_bf16 v[50:53], v[174:177], v[206:209], v[50:53]
	s_setprio 0
	s_barrier
	v_add_u32_e32 v158, s65, v141
	v_add_u32_e32 v174, s66, v141
	ds_read_b128 v[146:149], v158
	ds_read_b128 v[150:153], v158 offset:1024
	ds_read_b128 v[154:157], v158 offset:2048
	ds_read_b128 v[158:161], v158 offset:3072
	ds_read_b128 v[162:165], v174
	ds_read_b128 v[166:169], v174 offset:1024
	ds_read_b128 v[170:173], v174 offset:2048
	ds_read_b128 v[174:177], v174 offset:3072
	s_mov_b32 m0, s47
	ds_read_b128 v[178:181], v145 offset:32768
	ds_read_b128 v[182:185], v145 offset:33792
	ds_read_b128 v[186:189], v145 offset:34816
	ds_read_b128 v[190:193], v145 offset:35840
	ds_read_b128 v[194:197], v145 offset:36864
	ds_read_b128 v[198:201], v145 offset:37888
	ds_read_b128 v[202:205], v145 offset:38912
	ds_read_b128 v[206:209], v145 offset:39936
	global_load_lds_dwordx4 v130, s[36:37]
	s_mov_b32 m0, s48
	s_nop 0
	global_load_lds_dwordx4 v132, s[36:37]
	s_waitcnt vmcnt(8)
	s_waitcnt lgkmcnt(0)
	s_setprio 1
	s_barrier
	v_mfma_f32_16x16x32_bf16 v[126:129], v[146:149], v[178:181], v[126:129]
	v_mfma_f32_16x16x32_bf16 v[122:125], v[154:157], v[178:181], v[122:125]
	v_mfma_f32_16x16x32_bf16 v[118:121], v[146:149], v[186:189], v[118:121]
	v_mfma_f32_16x16x32_bf16 v[114:117], v[154:157], v[186:189], v[114:117]
	v_mfma_f32_16x16x32_bf16 v[102:105], v[146:149], v[194:197], v[102:105]
	v_mfma_f32_16x16x32_bf16 v[98:101], v[154:157], v[194:197], v[98:101]
	v_mfma_f32_16x16x32_bf16 v[86:89], v[146:149], v[202:205], v[86:89]
	v_mfma_f32_16x16x32_bf16 v[82:85], v[154:157], v[202:205], v[82:85]
	v_mfma_f32_16x16x32_bf16 v[126:129], v[150:153], v[182:185], v[126:129]
	v_mfma_f32_16x16x32_bf16 v[122:125], v[158:161], v[182:185], v[122:125]
	v_mfma_f32_16x16x32_bf16 v[118:121], v[150:153], v[190:193], v[118:121]
	v_mfma_f32_16x16x32_bf16 v[114:117], v[158:161], v[190:193], v[114:117]
	v_mfma_f32_16x16x32_bf16 v[102:105], v[150:153], v[198:201], v[102:105]
	v_mfma_f32_16x16x32_bf16 v[98:101], v[158:161], v[198:201], v[98:101]
	v_mfma_f32_16x16x32_bf16 v[86:89], v[150:153], v[206:209], v[86:89]
	v_mfma_f32_16x16x32_bf16 v[82:85], v[158:161], v[206:209], v[82:85]
	s_setprio 0
	s_setprio 1
	v_mfma_f32_16x16x32_bf16 v[110:113], v[162:165], v[178:181], v[110:113]
	v_mfma_f32_16x16x32_bf16 v[106:109], v[170:173], v[178:181], v[106:109]
	v_mfma_f32_16x16x32_bf16 v[94:97], v[162:165], v[186:189], v[94:97]
	v_mfma_f32_16x16x32_bf16 v[90:93], v[170:173], v[186:189], v[90:93]
	v_mfma_f32_16x16x32_bf16 v[78:81], v[162:165], v[194:197], v[78:81]
	v_mfma_f32_16x16x32_bf16 v[74:77], v[170:173], v[194:197], v[74:77]
	v_mfma_f32_16x16x32_bf16 v[70:73], v[162:165], v[202:205], v[70:73]
	v_mfma_f32_16x16x32_bf16 v[66:69], v[170:173], v[202:205], v[66:69]
	v_mfma_f32_16x16x32_bf16 v[110:113], v[166:169], v[182:185], v[110:113]
	v_mfma_f32_16x16x32_bf16 v[106:109], v[174:177], v[182:185], v[106:109]
	v_mfma_f32_16x16x32_bf16 v[94:97], v[166:169], v[190:193], v[94:97]
	v_mfma_f32_16x16x32_bf16 v[90:93], v[174:177], v[190:193], v[90:93]
	v_mfma_f32_16x16x32_bf16 v[78:81], v[166:169], v[198:201], v[78:81]
	v_mfma_f32_16x16x32_bf16 v[74:77], v[174:177], v[198:201], v[74:77]
	v_mfma_f32_16x16x32_bf16 v[70:73], v[166:169], v[206:209], v[70:73]
	v_mfma_f32_16x16x32_bf16 v[66:69], v[174:177], v[206:209], v[66:69]
	s_setprio 0
	s_barrier
; #define PG8_STAGE(bufoff, gbase, VO) do { _Pragma("unroll") for (int _i = 0; _i < 2; ++_i) \
;         __builtin_amdgcn_global_load_lds((const unsigned*)((const char*)(gbase) + VO[_i]), (LAS unsigned*)(lds + (bufoff) + ldsw + _i * 8192), 16, 0, 0); } while (0)
; #define PG8_LDA(dst, b, h) do { _Pragma("unroll") for (int m = 0; m < 4; ++m) _Pragma("unroll") for (int k = 0; k < 2; ++k) dst[m][k] = *(const LAS bf16x8*)(lds + PG8_SA(b, h) + aoff + m * 2048 + k * 1024); } while (0)
; #define PG8_MMA(ai, bj, At, Bt) do { __builtin_amdgcn_s_setprio(1); _Pragma("unroll") for (int m = 0; m < 4; ++m) _Pragma("unroll") for (int n = 0; n < 2; ++n) _Pragma("unroll") for (int k = 0; k < 2; ++k) \
;         acc[ai][bj][m][n] = __builtin_amdgcn_mfma_f32_16x16x32_bf16(Bt[n][k], At[m][k], acc[ai][bj][m][n], 0, 0, 0); __builtin_amdgcn_s_setprio(0); } while (0)
; #define PG8_WAIT_V(n) asm volatile("s_waitcnt vmcnt(" #n ")" ::: "memory")
; #define PG8_WAIT_L(n) asm volatile("s_waitcnt lgkmcnt(" #n ")" ::: "memory")
; #define PG8_BAR __builtin_amdgcn_s_barrier()
; #define PG8_SCHED __builtin_amdgcn_sched_barrier(0)
; template <int NSEG, class Epi, bool ALIGN_EPI = PG8_ALIGN, bool SP2 = PG8_SP2>
; DI void gemm_phase(LAS unsigned char* lds, const Gemm g, const StaticOrder& S, const Epi& E) {
;     ...
;             PG8_LDA(At, 1, 1); PG8_STAGE(PG8_SB(1, 0), b3, v2); PG8_STAGE(PG8_SB(1, 1), b3 + h2, v2); PG8_STAGE(PG8_SA(1, 0), a3, v2);
;             PG8_WAIT_V(8); PG8_WAIT_L(0); PG8_BAR; PG8_MMA(1, 0, At, B0); PG8_MMA(1, 1, At, B1); PG8_BAR; PG8_SCHED;
;     ...
;         if constexpr (ALIGN_EPI) { if (wr == 0) PG8_BAR; }
	s_add_i32 s36, s65, s44
	v_lshl_add_u64 v[210:211], v[210:211], 0, s[10:11]
	s_mov_b32 m0, s36
	ds_read_b128 v[178:181], v145 offset:49152
	ds_read_b128 v[182:185], v145 offset:50176
	ds_read_b128 v[186:189], v145 offset:51200
	ds_read_b128 v[190:193], v145 offset:52224
	ds_read_b128 v[194:197], v145 offset:53248
	ds_read_b128 v[198:201], v145 offset:54272
	ds_read_b128 v[202:205], v145 offset:55296
	ds_read_b128 v[206:209], v145 offset:56320
	global_load_lds_dwordx4 v[210:211], off
	s_add_i32 m0, s36, 0x2000
	s_add_u32 s34, s34, 0x160080
	v_lshl_add_u64 v[210:211], v[212:213], 0, s[10:11]
	s_addc_u32 s35, s35, 0
	s_add_i32 s36, s66, s44
	global_load_lds_dwordx4 v[210:211], off
	v_lshl_add_u64 v[210:211], s[34:35], 0, v[130:131]
	s_mov_b32 m0, s36
	s_nop 0
	global_load_lds_dwordx4 v[210:211], off
	v_lshl_add_u64 v[210:211], s[34:35], 0, v[132:133]
	s_add_i32 m0, s36, 0x2000
	s_nop 0
	global_load_lds_dwordx4 v[210:211], off
	v_lshl_add_u64 v[210:211], v[214:215], 0, s[10:11]
	s_mov_b32 m0, s49
	s_nop 0
	global_load_lds_dwordx4 v[210:211], off
	v_lshl_add_u64 v[210:211], v[216:217], 0, s[10:11]
	s_mov_b32 m0, s50
	s_nop 0
	global_load_lds_dwordx4 v[210:211], off
	s_waitcnt vmcnt(8)
	s_waitcnt lgkmcnt(0)
	s_setprio 1
	s_barrier
	v_mfma_f32_16x16x32_bf16 v[54:57], v[146:149], v[178:181], v[54:57]
	v_mfma_f32_16x16x32_bf16 v[46:49], v[154:157], v[178:181], v[46:49]
	v_mfma_f32_16x16x32_bf16 v[38:41], v[146:149], v[186:189], v[38:41]
	v_mfma_f32_16x16x32_bf16 v[34:37], v[154:157], v[186:189], v[34:37]
	v_mfma_f32_16x16x32_bf16 v[22:25], v[146:149], v[194:197], v[22:25]
	v_mfma_f32_16x16x32_bf16 v[18:21], v[154:157], v[194:197], v[18:21]
	v_mfma_f32_16x16x32_bf16 v[6:9], v[146:149], v[202:205], v[6:9]
	v_mfma_f32_16x16x32_bf16 v[2:5], v[154:157], v[202:205], v[2:5]
	v_mfma_f32_16x16x32_bf16 v[54:57], v[150:153], v[182:185], v[54:57]
	v_mfma_f32_16x16x32_bf16 v[46:49], v[158:161], v[182:185], v[46:49]
	v_mfma_f32_16x16x32_bf16 v[38:41], v[150:153], v[190:193], v[38:41]
	v_mfma_f32_16x16x32_bf16 v[34:37], v[158:161], v[190:193], v[34:37]
	v_mfma_f32_16x16x32_bf16 v[22:25], v[150:153], v[198:201], v[22:25]
	v_mfma_f32_16x16x32_bf16 v[18:21], v[158:161], v[198:201], v[18:21]
	v_mfma_f32_16x16x32_bf16 v[6:9], v[150:153], v[206:209], v[6:9]
	v_mfma_f32_16x16x32_bf16 v[2:5], v[158:161], v[206:209], v[2:5]
	s_setprio 0
	s_setprio 1
	v_mfma_f32_16x16x32_bf16 v[30:33], v[162:165], v[178:181], v[30:33]
	v_mfma_f32_16x16x32_bf16 v[26:29], v[170:173], v[178:181], v[26:29]
	v_mfma_f32_16x16x32_bf16 v[14:17], v[162:165], v[186:189], v[14:17]
	v_mfma_f32_16x16x32_bf16 v[10:13], v[170:173], v[186:189], v[10:13]
	v_mfma_f32_16x16x32_bf16 v[58:61], v[162:165], v[194:197], v[58:61]
	v_mfma_f32_16x16x32_bf16 v[62:65], v[170:173], v[194:197], v[62:65]
	v_mfma_f32_16x16x32_bf16 v[42:45], v[162:165], v[202:205], v[42:45]
	v_mfma_f32_16x16x32_bf16 v[50:53], v[170:173], v[202:205], v[50:53]
	v_mfma_f32_16x16x32_bf16 v[30:33], v[166:169], v[182:185], v[30:33]
	v_mfma_f32_16x16x32_bf16 v[26:29], v[174:177], v[182:185], v[26:29]
	v_mfma_f32_16x16x32_bf16 v[14:17], v[166:169], v[190:193], v[14:17]
	v_mfma_f32_16x16x32_bf16 v[10:13], v[174:177], v[190:193], v[10:13]
	v_mfma_f32_16x16x32_bf16 v[58:61], v[166:169], v[198:201], v[58:61]
	v_mfma_f32_16x16x32_bf16 v[62:65], v[174:177], v[198:201], v[62:65]
	v_mfma_f32_16x16x32_bf16 v[42:45], v[166:169], v[206:209], v[42:45]
	v_mfma_f32_16x16x32_bf16 v[50:53], v[174:177], v[206:209], v[50:53]
	s_setprio 0
	s_barrier
	s_add_i32 s64, s64, 2
	s_add_u32 s26, s26, 0x100
	s_addc_u32 s27, s27, 0
	s_add_u32 s62, s62, 0x100
	s_addc_u32 s63, s63, 0
	s_cmpk_gt_u32 s64, 0x55
	s_cbranch_scc0 .LBB0_599
	s_and_b64 vcc, exec, s[12:13]
	s_cbranch_vccz .LBB0_602
	s_barrier
